# v16: v12 + sample-attention softmax max/sum all-reduce via DPP and permlane swaps instead of ds_bpermute chains
# speedup vs baseline: 1.0087x; 1.0045x over previous
; DI void attn_sample_item(const Params& p, int item, ldsp lds, int tid_) {
;     ...
;   for (int t = 0; t < 4; ++t) { f32x4 a = {0.f, 0.f, 0.f, 0.f}; const float* pp = (const float*)(p.ws + B_PART) + (size_t)(b * 4 + t) * 1024 + h * 256 + lane * 4;
; #pragma unroll
;     for (int kp = 0; kp < 4; ++kp) a += *(const f32x4*)(pp + (size_t)kp * 512 * 1024);
;     q[t][0] = a[0] * 0.0625f; q[t][1] = a[1] * 0.0625f; q[t][2] = a[2] * 0.0625f; q[t][3] = a[3] * 0.0625f; }
;   const bool b0 = lane & 1, b1 = lane & 2;
;   f32x4 kvA[16], kvB[16];
; #pragma unroll
;   for (int j = 0; j < 16; ++j) kvA[j] = __builtin_nontemporal_load((const f32x4*)(ck + (size_t)(wid * 32 + j) * 1024 + lane * 4));
; #pragma unroll
;   for (int j = 0; j < 16; ++j) kvB[j] = __builtin_nontemporal_load((const f32x4*)(ck + (size_t)(wid * 32 + 16 + j) * 1024 + lane * 4));
.LBB0_1604:
	s_ashr_i32 s4, s40, 2
	s_ashr_i32 s5, s4, 31
	s_lshl_b64 s[4:5], s[4:5], 18
	s_and_b32 s26, s0, 0x300
	v_mov_b32_e32 v222, v212
	s_or_b32 s4, s4, s26
	s_and_b32 s28, s40, -4
	s_lshl_b32 s6, s26, 2
	s_add_u32 s6, s36, s6
	v_and_b32_e32 v223, 63, v222
	s_addc_u32 s7, s37, 0
	v_lshlrev_b32_e32 v144, 4, v223
	s_ashr_i32 s29, s28, 31
	v_lshl_add_u64 v[48:49], s[6:7], 0, v[144:145]
	s_lshl_b64 s[6:7], s[28:29], 12
	v_lshl_add_u64 v[8:9], v[48:49], 0, s[6:7]
	v_add_co_u32_e32 v4, vcc, s3, v8
	s_or_b32 s6, s28, 1
	s_nop 0
	v_addc_co_u32_e32 v5, vcc, 0, v9, vcc
	v_add_co_u32_e32 v10, vcc, s33, v8
	s_ashr_i32 s7, s6, 31
	s_nop 0
	v_addc_co_u32_e32 v11, vcc, 0, v9, vcc
	v_add_co_u32_e32 v12, vcc, s38, v8
	s_lshl_b64 s[6:7], s[6:7], 12
	s_nop 0
	v_addc_co_u32_e32 v13, vcc, 0, v9, vcc
	v_lshl_add_u64 v[24:25], v[48:49], 0, s[6:7]
	v_add_co_u32_e32 v20, vcc, s3, v24
	s_or_b32 s6, s28, 2
	s_nop 0
	v_addc_co_u32_e32 v21, vcc, 0, v25, vcc
	v_add_co_u32_e32 v26, vcc, s33, v24
	s_ashr_i32 s7, s6, 31
	s_nop 0
	v_addc_co_u32_e32 v27, vcc, 0, v25, vcc
	v_add_co_u32_e32 v28, vcc, s38, v24
	s_lshl_b64 s[6:7], s[6:7], 12
	global_load_dwordx4 v[0:3], v[8:9], off
	s_nop 0
	global_load_dwordx4 v[4:7], v[4:5], off
	v_addc_co_u32_e32 v29, vcc, 0, v25, vcc
	v_lshl_add_u64 v[44:45], v[48:49], 0, s[6:7]
	global_load_dwordx4 v[8:11], v[10:11], off
	s_nop 0
	global_load_dwordx4 v[12:15], v[12:13], off
	s_nop 0
	global_load_dwordx4 v[16:19], v[24:25], off
	s_nop 0
	global_load_dwordx4 v[20:23], v[20:21], off
	v_add_co_u32_e32 v36, vcc, s3, v44
	global_load_dwordx4 v[24:27], v[26:27], off
	s_nop 0
	global_load_dwordx4 v[28:31], v[28:29], off
	v_addc_co_u32_e32 v37, vcc, 0, v45, vcc
	v_add_co_u32_e32 v40, vcc, s33, v44
	global_load_dwordx4 v[32:35], v[44:45], off
	s_nop 0
	global_load_dwordx4 v[36:39], v[36:37], off
	v_addc_co_u32_e32 v41, vcc, 0, v45, vcc
	v_add_co_u32_e32 v44, vcc, s38, v44
	global_load_dwordx4 v[40:43], v[40:41], off
	s_nop 0
	v_addc_co_u32_e32 v45, vcc, 0, v45, vcc
	global_load_dwordx4 v[44:47], v[44:45], off
	s_or_b32 s6, s40, 3
	s_ashr_i32 s7, s6, 31
	s_lshl_b64 s[6:7], s[6:7], 12
	s_lshl_b64 s[30:31], s[4:5], 2
	s_add_u32 s4, s12, s30
	s_addc_u32 s5, s13, s31
	s_waitcnt vmcnt(11)
	v_pk_add_f32 v[2:3], v[2:3], 0 op_sel_hi:[1,0]
	v_pk_add_f32 v[0:1], v[0:1], 0 op_sel_hi:[1,0]
	s_waitcnt vmcnt(10)
	v_pk_add_f32 v[2:3], v[2:3], v[6:7]
	v_pk_add_f32 v[0:1], v[0:1], v[4:5]
	s_waitcnt vmcnt(9)
	v_pk_add_f32 v[2:3], v[2:3], v[10:11]
	s_waitcnt vmcnt(7)
	v_pk_add_f32 v[4:5], v[18:19], 0 op_sel_hi:[1,0]
	v_pk_add_f32 v[6:7], v[16:17], 0 op_sel_hi:[1,0]
	v_pk_add_f32 v[0:1], v[0:1], v[8:9]
	s_waitcnt vmcnt(6)
	v_pk_add_f32 v[4:5], v[4:5], v[22:23]
	v_pk_add_f32 v[6:7], v[6:7], v[20:21]
	v_pk_add_f32 v[2:3], v[2:3], v[14:15]
	v_pk_add_f32 v[0:1], v[0:1], v[12:13]
	s_waitcnt vmcnt(5)
	v_pk_add_f32 v[4:5], v[4:5], v[26:27]
	v_pk_add_f32 v[6:7], v[6:7], v[24:25]
	v_mul_f32_e32 v228, 0x3d800000, v0
	v_mul_f32_e32 v231, 0x3d800000, v1
	v_mul_f32_e32 v229, 0x3d800000, v2
	v_mul_f32_e32 v225, 0x3d800000, v3
	s_waitcnt vmcnt(4)
	v_pk_add_f32 v[0:1], v[4:5], v[30:31]
	v_pk_add_f32 v[2:3], v[6:7], v[28:29]
	v_mul_f32_e32 v227, 0x3d800000, v0
	v_mul_f32_e32 v226, 0x3d800000, v2
	v_mul_f32_e32 v230, 0x3d800000, v3
	v_mul_f32_e32 v224, 0x3d800000, v1
	s_waitcnt vmcnt(3)
	v_pk_add_f32 v[0:1], v[34:35], 0 op_sel_hi:[1,0]
	v_pk_add_f32 v[2:3], v[32:33], 0 op_sel_hi:[1,0]
	s_waitcnt vmcnt(2)
	v_pk_add_f32 v[0:1], v[0:1], v[38:39]
	v_pk_add_f32 v[2:3], v[2:3], v[36:37]
	s_waitcnt vmcnt(1)
	v_pk_add_f32 v[0:1], v[0:1], v[42:43]
	v_pk_add_f32 v[2:3], v[2:3], v[40:41]
	s_waitcnt vmcnt(0)
	v_pk_add_f32 v[210:211], v[0:1], v[46:47]
	v_pk_add_f32 v[0:1], v[2:3], v[44:45]
	v_mul_f32_e32 v233, 0x3d800000, v210
	v_mul_f32_e32 v232, 0x3d800000, v0
	v_mul_f32_e32 v234, 0x3d800000, v1
	v_lshl_add_u64 v[0:1], v[48:49], 0, s[6:7]
	v_add_co_u32_e32 v2, vcc, s3, v0
	v_ashrrev_i32_e32 v210, 6, v222
	s_nop 0
	v_addc_co_u32_e32 v3, vcc, 0, v1, vcc
	global_load_dwordx4 v[128:131], v[0:1], off
	global_load_dwordx4 v[132:135], v[2:3], off
	v_add_co_u32_e32 v2, vcc, s33, v0
	v_mul_f32_e32 v211, 0x3d800000, v211
	s_nop 0
	v_addc_co_u32_e32 v3, vcc, 0, v1, vcc
	v_add_co_u32_e32 v0, vcc, s38, v0
	v_cmp_lt_i32_e64 s[6:7], v218, v216
	s_nop 0
	v_addc_co_u32_e32 v1, vcc, 0, v1, vcc
	global_load_dwordx4 v[136:139], v[2:3], off
	global_load_dwordx4 v[140:143], v[0:1], off
	v_lshlrev_b32_e32 v0, 5, v210
	v_ashrrev_i32_e32 v1, 31, v0
	v_or_b32_e32 v6, 1, v0
	v_lshl_add_u64 v[2:3], s[4:5], 0, v[144:145]
	v_lshlrev_b64 v[162:163], 12, v[0:1]
	v_ashrrev_i32_e32 v7, 31, v6
	v_lshl_add_u64 v[4:5], v[2:3], 0, v[162:163]
	v_lshlrev_b64 v[166:167], 12, v[6:7]
	v_lshl_add_u64 v[6:7], v[2:3], 0, v[166:167]
	global_load_dwordx4 v[124:127], v[4:5], off nt
	global_load_dwordx4 v[120:123], v[6:7], off nt
	v_or_b32_e32 v4, 2, v0
	v_ashrrev_i32_e32 v5, 31, v4
	v_or_b32_e32 v6, 3, v0
	v_lshlrev_b64 v[168:169], 12, v[4:5]
	v_ashrrev_i32_e32 v7, 31, v6
	v_lshl_add_u64 v[4:5], v[2:3], 0, v[168:169]
	v_lshlrev_b64 v[172:173], 12, v[6:7]
	v_lshl_add_u64 v[6:7], v[2:3], 0, v[172:173]
	global_load_dwordx4 v[116:119], v[4:5], off nt
	global_load_dwordx4 v[112:115], v[6:7], off nt
	v_or_b32_e32 v4, 4, v0
	v_ashrrev_i32_e32 v5, 31, v4
	v_or_b32_e32 v6, 5, v0
	v_lshlrev_b64 v[176:177], 12, v[4:5]
	v_ashrrev_i32_e32 v7, 31, v6
	v_lshl_add_u64 v[4:5], v[2:3], 0, v[176:177]
	v_lshlrev_b64 v[180:181], 12, v[6:7]
	v_lshl_add_u64 v[6:7], v[2:3], 0, v[180:181]
	global_load_dwordx4 v[108:111], v[4:5], off nt
	global_load_dwordx4 v[104:107], v[6:7], off nt
	v_or_b32_e32 v4, 6, v0
	v_ashrrev_i32_e32 v5, 31, v4
	v_or_b32_e32 v6, 7, v0
; DI void attn_sample_item(const Params& p, int item, ldsp lds, int tid_) {
;     ...
;   for (int t = 0; t < 4; ++t) { f32x4 a = {0.f, 0.f, 0.f, 0.f}; const float* pp = (const float*)(p.ws + B_PART) + (size_t)(b * 4 + t) * 1024 + h * 256 + lane * 4;
; #pragma unroll
;     for (int kp = 0; kp < 4; ++kp) a += *(const f32x4*)(pp + (size_t)kp * 512 * 1024);
;     q[t][0] = a[0] * 0.0625f; q[t][1] = a[1] * 0.0625f; q[t][2] = a[2] * 0.0625f; q[t][3] = a[3] * 0.0625f; }
;     ...
;   for (int j = 0; j < 16; ++j) kvA[j] = __builtin_nontemporal_load((const f32x4*)(ck + (size_t)(wid * 32 + j) * 1024 + lane * 4));
; #pragma unroll
;   for (int j = 0; j < 16; ++j) kvB[j] = __builtin_nontemporal_load((const f32x4*)(ck + (size_t)(wid * 32 + 16 + j) * 1024 + lane * 4));
	v_lshlrev_b64 v[182:183], 12, v[4:5]
	v_ashrrev_i32_e32 v7, 31, v6
	v_lshl_add_u64 v[4:5], v[2:3], 0, v[182:183]
	v_lshlrev_b64 v[186:187], 12, v[6:7]
	v_lshl_add_u64 v[6:7], v[2:3], 0, v[186:187]
	global_load_dwordx4 v[100:103], v[4:5], off nt
	global_load_dwordx4 v[96:99], v[6:7], off nt
	v_or_b32_e32 v4, 8, v0
	v_ashrrev_i32_e32 v5, 31, v4
	v_or_b32_e32 v6, 9, v0
	v_lshlrev_b64 v[190:191], 12, v[4:5]
	v_ashrrev_i32_e32 v7, 31, v6
	v_lshl_add_u64 v[4:5], v[2:3], 0, v[190:191]
	v_lshlrev_b64 v[194:195], 12, v[6:7]
	v_lshl_add_u64 v[6:7], v[2:3], 0, v[194:195]
	global_load_dwordx4 v[92:95], v[4:5], off nt
	global_load_dwordx4 v[88:91], v[6:7], off nt
	v_or_b32_e32 v4, 10, v0
	v_ashrrev_i32_e32 v5, 31, v4
	v_or_b32_e32 v6, 11, v0
	v_lshlrev_b64 v[198:199], 12, v[4:5]
	v_ashrrev_i32_e32 v7, 31, v6
	v_lshl_add_u64 v[4:5], v[2:3], 0, v[198:199]
	v_lshlrev_b64 v[200:201], 12, v[6:7]
	v_lshl_add_u64 v[6:7], v[2:3], 0, v[200:201]
	global_load_dwordx4 v[84:87], v[4:5], off nt
	global_load_dwordx4 v[80:83], v[6:7], off nt
	v_or_b32_e32 v4, 12, v0
	v_ashrrev_i32_e32 v5, 31, v4
	v_or_b32_e32 v6, 13, v0
	v_lshlrev_b64 v[202:203], 12, v[4:5]
	v_ashrrev_i32_e32 v7, 31, v6
	v_lshl_add_u64 v[4:5], v[2:3], 0, v[202:203]
	v_lshlrev_b64 v[204:205], 12, v[6:7]
	v_lshl_add_u64 v[6:7], v[2:3], 0, v[204:205]
	global_load_dwordx4 v[76:79], v[4:5], off nt
	global_load_dwordx4 v[72:75], v[6:7], off nt
	v_or_b32_e32 v4, 14, v0
	v_ashrrev_i32_e32 v5, 31, v4
	v_or_b32_e32 v6, 15, v0
	v_lshlrev_b64 v[206:207], 12, v[4:5]
	v_ashrrev_i32_e32 v7, 31, v6
	v_lshl_add_u64 v[4:5], v[2:3], 0, v[206:207]
	v_lshlrev_b64 v[208:209], 12, v[6:7]
	v_lshl_add_u64 v[6:7], v[2:3], 0, v[208:209]
	global_load_dwordx4 v[68:71], v[4:5], off nt
	global_load_dwordx4 v[64:67], v[6:7], off nt
	v_or_b32_e32 v4, 16, v0
	v_ashrrev_i32_e32 v5, 31, v4
	v_or_b32_e32 v6, 17, v0
	v_lshlrev_b64 v[146:147], 12, v[4:5]
	v_ashrrev_i32_e32 v7, 31, v6
	v_lshl_add_u64 v[4:5], v[2:3], 0, v[146:147]
	v_lshlrev_b64 v[148:149], 12, v[6:7]
	v_lshl_add_u64 v[6:7], v[2:3], 0, v[148:149]
	global_load_dwordx4 v[60:63], v[4:5], off nt
	global_load_dwordx4 v[56:59], v[6:7], off nt
	v_or_b32_e32 v4, 18, v0
	v_ashrrev_i32_e32 v5, 31, v4
	v_or_b32_e32 v6, 19, v0
	v_lshlrev_b64 v[150:151], 12, v[4:5]
	v_ashrrev_i32_e32 v7, 31, v6
	v_lshl_add_u64 v[4:5], v[2:3], 0, v[150:151]
	v_lshlrev_b64 v[152:153], 12, v[6:7]
	v_lshl_add_u64 v[6:7], v[2:3], 0, v[152:153]
	global_load_dwordx4 v[52:55], v[4:5], off nt
	global_load_dwordx4 v[48:51], v[6:7], off nt
	v_or_b32_e32 v4, 20, v0
	v_ashrrev_i32_e32 v5, 31, v4
	v_or_b32_e32 v6, 21, v0
	v_lshlrev_b64 v[154:155], 12, v[4:5]
	v_ashrrev_i32_e32 v7, 31, v6
	v_lshl_add_u64 v[4:5], v[2:3], 0, v[154:155]
	v_lshlrev_b64 v[156:157], 12, v[6:7]
	v_lshl_add_u64 v[6:7], v[2:3], 0, v[156:157]
	global_load_dwordx4 v[44:47], v[4:5], off nt
	global_load_dwordx4 v[40:43], v[6:7], off nt
	v_or_b32_e32 v4, 22, v0
	v_ashrrev_i32_e32 v5, 31, v4
	v_or_b32_e32 v6, 23, v0
	v_lshlrev_b64 v[158:159], 12, v[4:5]
	v_ashrrev_i32_e32 v7, 31, v6
	v_lshl_add_u64 v[4:5], v[2:3], 0, v[158:159]
	v_lshlrev_b64 v[160:161], 12, v[6:7]
	v_lshl_add_u64 v[6:7], v[2:3], 0, v[160:161]
	global_load_dwordx4 v[36:39], v[4:5], off nt
	global_load_dwordx4 v[32:35], v[6:7], off nt
	v_or_b32_e32 v4, 24, v0
	v_ashrrev_i32_e32 v5, 31, v4
	v_or_b32_e32 v6, 25, v0
	v_lshlrev_b64 v[164:165], 12, v[4:5]
	v_ashrrev_i32_e32 v7, 31, v6
	v_lshl_add_u64 v[4:5], v[2:3], 0, v[164:165]
	v_lshlrev_b64 v[170:171], 12, v[6:7]
	v_lshl_add_u64 v[6:7], v[2:3], 0, v[170:171]
	global_load_dwordx4 v[28:31], v[4:5], off nt
	global_load_dwordx4 v[24:27], v[6:7], off nt
	v_or_b32_e32 v4, 26, v0
	v_ashrrev_i32_e32 v5, 31, v4
	v_or_b32_e32 v6, 27, v0
	v_lshlrev_b64 v[174:175], 12, v[4:5]
	v_ashrrev_i32_e32 v7, 31, v6
	v_lshl_add_u64 v[4:5], v[2:3], 0, v[174:175]
	v_lshlrev_b64 v[178:179], 12, v[6:7]
	v_lshl_add_u64 v[6:7], v[2:3], 0, v[178:179]
	global_load_dwordx4 v[20:23], v[4:5], off nt
	global_load_dwordx4 v[16:19], v[6:7], off nt
	v_or_b32_e32 v4, 28, v0
	v_ashrrev_i32_e32 v5, 31, v4
	v_or_b32_e32 v6, 29, v0
	v_lshlrev_b64 v[184:185], 12, v[4:5]
	v_ashrrev_i32_e32 v7, 31, v6
	v_lshl_add_u64 v[4:5], v[2:3], 0, v[184:185]
	v_lshlrev_b64 v[188:189], 12, v[6:7]
	v_lshl_add_u64 v[6:7], v[2:3], 0, v[188:189]
	global_load_dwordx4 v[12:15], v[4:5], off nt
	global_load_dwordx4 v[8:11], v[6:7], off nt
	v_or_b32_e32 v4, 30, v0
	v_or_b32_e32 v0, 31, v0
	v_ashrrev_i32_e32 v5, 31, v4
	v_ashrrev_i32_e32 v1, 31, v0
	v_lshlrev_b64 v[192:193], 12, v[4:5]
	v_lshlrev_b64 v[196:197], 12, v[0:1]
	v_lshl_add_u64 v[4:5], v[2:3], 0, v[192:193]
	v_lshl_add_u64 v[0:1], v[2:3], 0, v[196:197]
	global_load_dwordx4 v[4:7], v[4:5], off nt
	s_nop 0
	global_load_dwordx4 v[0:3], v[0:1], off nt
	s_waitcnt vmcnt(35)
	v_pk_add_f32 v[128:129], v[128:129], 0 op_sel_hi:[1,0]
	v_pk_add_f32 v[130:131], v[130:131], 0 op_sel_hi:[1,0]
	s_waitcnt vmcnt(34)
	v_pk_add_f32 v[128:129], v[128:129], v[132:133]
	v_pk_add_f32 v[130:131], v[130:131], v[134:135]
	s_waitcnt vmcnt(33)
	v_pk_add_f32 v[128:129], v[128:129], v[136:137]
	v_pk_add_f32 v[130:131], v[130:131], v[138:139]
	s_waitcnt vmcnt(32)
; DI void attn_sample_item(const Params& p, int item, ldsp lds, int tid_) {
;     ...
;     q[t][0] = a[0] * 0.0625f; q[t][1] = a[1] * 0.0625f; q[t][2] = a[2] * 0.0625f; q[t][3] = a[3] * 0.0625f; }
;     ...
;   SC_SCORE(kvA, 0)
;   SC_SCORE(kvB, 1)
	v_pk_add_f32 v[128:129], v[128:129], v[140:141]
	v_pk_add_f32 v[130:131], v[130:131], v[142:143]
	v_mul_f32_e32 v138, 0x3d800000, v129
	v_mul_f32_e32 v135, 0x3d800000, v128
	v_mul_f32_e32 v134, 0x3d800000, v131
	s_add_u32 s66, s14, s30
	s_addc_u32 s67, s15, s31
	v_mul_f32_e32 v137, 0x3d800000, v130
	v_lshlrev_b32_e32 v128, 2, v215
	v_lshlrev_b32_e32 v129, 2, v217
	v_lshlrev_b32_e32 v130, 2, v218
	v_lshlrev_b32_e32 v131, 2, v219
	v_lshlrev_b32_e32 v132, 2, v220
	v_lshlrev_b32_e32 v133, 2, v221
	v_lshl_add_u32 v136, v210, 7, 16
	v_and_b32_e32 v139, 3, v223
	v_bfrev_b32_e32 v139, v139
	v_lshrrev_b32_e32 v139, 20, v139
	v_and_b32_e32 v235, -4, v223
	v_add3_u32 v235, v136, v139, v235
	v_mov_b32_e32 v236, v228
	v_mov_b32_e32 v237, v226
	v_mov_b32_e32 v238, v231
	v_mov_b32_e32 v239, v230
	v_mov_b32_e32 v240, v229
	v_mov_b32_e32 v241, v227
	v_mov_b32_e32 v242, v225
	v_mov_b32_e32 v243, v224
	v_mov_b32_e32 v244, v232
	v_mov_b32_e32 v245, v135
	v_mov_b32_e32 v246, v234
	v_mov_b32_e32 v247, v138
	v_mov_b32_e32 v248, v233
	v_mov_b32_e32 v249, v137
	v_mov_b32_e32 v250, v211
	v_mov_b32_e32 v251, v134
	s_mov_b32 vcc_lo, 0x55555555
	s_mov_b32 vcc_hi, 0x55555555
	s_mov_b32 s4, 0x33333333
	s_mov_b32 s5, 0x33333333
	s_mov_b32 s6, 0x0f0f0f0f
	s_mov_b32 s7, 0x0f0f0f0f
	s_mov_b32 s64, 0x00ff00ff
	s_mov_b32 s65, 0x00ff00ff
	s_waitcnt vmcnt(31)
	v_pk_mul_f32 v[252:253], v[236:237], v[124:125] op_sel_hi:[1,0]
	v_pk_mul_f32 v[254:255], v[244:245], v[124:125] op_sel_hi:[1,0]
	v_pk_fma_f32 v[252:253], v[238:239], v[124:125], v[252:253] op_sel:[0,1,0]
	v_pk_fma_f32 v[254:255], v[246:247], v[124:125], v[254:255] op_sel:[0,1,0]
	v_pk_fma_f32 v[252:253], v[240:241], v[126:127], v[252:253] op_sel_hi:[1,0,1]
	v_pk_fma_f32 v[254:255], v[248:249], v[126:127], v[254:255] op_sel_hi:[1,0,1]
	v_pk_fma_f32 v[252:253], v[242:243], v[126:127], v[252:253] op_sel:[0,1,0]
	v_pk_fma_f32 v[254:255], v[250:251], v[126:127], v[254:255] op_sel:[0,1,0]
	s_waitcnt vmcnt(30)
	v_pk_mul_f32 v[140:141], v[236:237], v[120:121] op_sel_hi:[1,0]
	v_pk_mul_f32 v[142:143], v[244:245], v[120:121] op_sel_hi:[1,0]
	v_pk_fma_f32 v[140:141], v[238:239], v[120:121], v[140:141] op_sel:[0,1,0]
	v_pk_fma_f32 v[142:143], v[246:247], v[120:121], v[142:143] op_sel:[0,1,0]
	v_pk_fma_f32 v[140:141], v[240:241], v[122:123], v[140:141] op_sel_hi:[1,0,1]
	v_pk_fma_f32 v[142:143], v[248:249], v[122:123], v[142:143] op_sel_hi:[1,0,1]
	v_pk_fma_f32 v[140:141], v[242:243], v[122:123], v[140:141] op_sel:[0,1,0]
	v_pk_fma_f32 v[142:143], v[250:251], v[122:123], v[142:143] op_sel:[0,1,0]
	v_add_f32_dpp v124, v252, v252 quad_perm:[1,0,3,2] row_mask:0xf bank_mask:0xf
	v_add_f32_dpp v125, v253, v253 quad_perm:[1,0,3,2] row_mask:0xf bank_mask:0xf
	v_add_f32_dpp v126, v254, v254 quad_perm:[1,0,3,2] row_mask:0xf bank_mask:0xf
	v_add_f32_dpp v127, v255, v255 quad_perm:[1,0,3,2] row_mask:0xf bank_mask:0xf
	v_cndmask_b32_e32 v124, v126, v124, vcc
	v_cndmask_b32_e32 v125, v127, v125, vcc
	s_waitcnt vmcnt(29)
	v_pk_mul_f32 v[252:253], v[236:237], v[116:117] op_sel_hi:[1,0]
	v_pk_mul_f32 v[254:255], v[244:245], v[116:117] op_sel_hi:[1,0]
	v_pk_fma_f32 v[252:253], v[238:239], v[116:117], v[252:253] op_sel:[0,1,0]
	v_pk_fma_f32 v[254:255], v[246:247], v[116:117], v[254:255] op_sel:[0,1,0]
	v_pk_fma_f32 v[252:253], v[240:241], v[118:119], v[252:253] op_sel_hi:[1,0,1]
	v_pk_fma_f32 v[254:255], v[248:249], v[118:119], v[254:255] op_sel_hi:[1,0,1]
	v_pk_fma_f32 v[252:253], v[242:243], v[118:119], v[252:253] op_sel:[0,1,0]
	v_pk_fma_f32 v[254:255], v[250:251], v[118:119], v[254:255] op_sel:[0,1,0]
	v_add_f32_dpp v120, v140, v140 quad_perm:[1,0,3,2] row_mask:0xf bank_mask:0xf
	v_add_f32_dpp v121, v141, v141 quad_perm:[1,0,3,2] row_mask:0xf bank_mask:0xf
	v_add_f32_dpp v122, v142, v142 quad_perm:[1,0,3,2] row_mask:0xf bank_mask:0xf
	v_add_f32_dpp v123, v143, v143 quad_perm:[1,0,3,2] row_mask:0xf bank_mask:0xf
	v_cndmask_b32_e32 v120, v122, v120, vcc
	v_cndmask_b32_e32 v121, v123, v121, vcc
	v_add_f32_dpp v126, v124, v124 quad_perm:[2,3,0,1] row_mask:0xf bank_mask:0xf
	v_add_f32_dpp v127, v125, v125 quad_perm:[2,3,0,1] row_mask:0xf bank_mask:0xf
	v_cndmask_b32_e64 v124, v127, v126, s[4:5]
	s_waitcnt vmcnt(28)
	v_pk_mul_f32 v[140:141], v[236:237], v[112:113] op_sel_hi:[1,0]
	v_pk_mul_f32 v[142:143], v[244:245], v[112:113] op_sel_hi:[1,0]
	v_pk_fma_f32 v[140:141], v[238:239], v[112:113], v[140:141] op_sel:[0,1,0]
	v_pk_fma_f32 v[142:143], v[246:247], v[112:113], v[142:143] op_sel:[0,1,0]
	v_pk_fma_f32 v[140:141], v[240:241], v[114:115], v[140:141] op_sel_hi:[1,0,1]
	v_pk_fma_f32 v[142:143], v[248:249], v[114:115], v[142:143] op_sel_hi:[1,0,1]
	v_pk_fma_f32 v[140:141], v[242:243], v[114:115], v[140:141] op_sel:[0,1,0]
	v_pk_fma_f32 v[142:143], v[250:251], v[114:115], v[142:143] op_sel:[0,1,0]
	v_add_f32_dpp v116, v252, v252 quad_perm:[1,0,3,2] row_mask:0xf bank_mask:0xf
	v_add_f32_dpp v117, v253, v253 quad_perm:[1,0,3,2] row_mask:0xf bank_mask:0xf
	v_add_f32_dpp v118, v254, v254 quad_perm:[1,0,3,2] row_mask:0xf bank_mask:0xf
	v_add_f32_dpp v119, v255, v255 quad_perm:[1,0,3,2] row_mask:0xf bank_mask:0xf
	v_cndmask_b32_e32 v116, v118, v116, vcc
	v_cndmask_b32_e32 v117, v119, v117, vcc
	v_add_f32_dpp v122, v120, v120 quad_perm:[2,3,0,1] row_mask:0xf bank_mask:0xf
	v_add_f32_dpp v123, v121, v121 quad_perm:[2,3,0,1] row_mask:0xf bank_mask:0xf
	v_cndmask_b32_e64 v120, v123, v122, s[4:5]
	v_cndmask_b32_e64 v125, v120, v124, s[6:7]
	v_cndmask_b32_e64 v126, v124, v120, s[6:7]
	s_waitcnt vmcnt(27)
; DI void attn_sample_item(const Params& p, int item, ldsp lds, int tid_) {
;     ...
;   SC_SCORE(kvA, 0)
;   SC_SCORE(kvB, 1)
	v_pk_mul_f32 v[252:253], v[236:237], v[108:109] op_sel_hi:[1,0]
	v_pk_mul_f32 v[254:255], v[244:245], v[108:109] op_sel_hi:[1,0]
	v_pk_fma_f32 v[252:253], v[238:239], v[108:109], v[252:253] op_sel:[0,1,0]
	v_pk_fma_f32 v[254:255], v[246:247], v[108:109], v[254:255] op_sel:[0,1,0]
	v_pk_fma_f32 v[252:253], v[240:241], v[110:111], v[252:253] op_sel_hi:[1,0,1]
	v_pk_fma_f32 v[254:255], v[248:249], v[110:111], v[254:255] op_sel_hi:[1,0,1]
	v_pk_fma_f32 v[252:253], v[242:243], v[110:111], v[252:253] op_sel:[0,1,0]
	v_pk_fma_f32 v[254:255], v[250:251], v[110:111], v[254:255] op_sel:[0,1,0]
	v_add_f32_dpp v124, v126, v125 row_ror:4 row_mask:0xf bank_mask:0xf
	v_add_f32_dpp v112, v140, v140 quad_perm:[1,0,3,2] row_mask:0xf bank_mask:0xf
	v_add_f32_dpp v113, v141, v141 quad_perm:[1,0,3,2] row_mask:0xf bank_mask:0xf
	v_add_f32_dpp v114, v142, v142 quad_perm:[1,0,3,2] row_mask:0xf bank_mask:0xf
	v_add_f32_dpp v115, v143, v143 quad_perm:[1,0,3,2] row_mask:0xf bank_mask:0xf
	v_cndmask_b32_e32 v112, v114, v112, vcc
	v_cndmask_b32_e32 v113, v115, v113, vcc
	v_add_f32_dpp v118, v116, v116 quad_perm:[2,3,0,1] row_mask:0xf bank_mask:0xf
	v_add_f32_dpp v119, v117, v117 quad_perm:[2,3,0,1] row_mask:0xf bank_mask:0xf
	v_cndmask_b32_e64 v116, v119, v118, s[4:5]
	s_waitcnt vmcnt(26)
	v_pk_mul_f32 v[140:141], v[236:237], v[104:105] op_sel_hi:[1,0]
	v_pk_mul_f32 v[142:143], v[244:245], v[104:105] op_sel_hi:[1,0]
	v_pk_fma_f32 v[140:141], v[238:239], v[104:105], v[140:141] op_sel:[0,1,0]
	v_pk_fma_f32 v[142:143], v[246:247], v[104:105], v[142:143] op_sel:[0,1,0]
	v_pk_fma_f32 v[140:141], v[240:241], v[106:107], v[140:141] op_sel_hi:[1,0,1]
	v_pk_fma_f32 v[142:143], v[248:249], v[106:107], v[142:143] op_sel_hi:[1,0,1]
	v_pk_fma_f32 v[140:141], v[242:243], v[106:107], v[140:141] op_sel:[0,1,0]
	v_pk_fma_f32 v[142:143], v[250:251], v[106:107], v[142:143] op_sel:[0,1,0]
	v_add_f32_dpp v108, v252, v252 quad_perm:[1,0,3,2] row_mask:0xf bank_mask:0xf
	v_add_f32_dpp v109, v253, v253 quad_perm:[1,0,3,2] row_mask:0xf bank_mask:0xf
	v_add_f32_dpp v110, v254, v254 quad_perm:[1,0,3,2] row_mask:0xf bank_mask:0xf
	v_add_f32_dpp v111, v255, v255 quad_perm:[1,0,3,2] row_mask:0xf bank_mask:0xf
	v_cndmask_b32_e32 v108, v110, v108, vcc
	v_cndmask_b32_e32 v109, v111, v109, vcc
	v_add_f32_dpp v114, v112, v112 quad_perm:[2,3,0,1] row_mask:0xf bank_mask:0xf
	v_add_f32_dpp v115, v113, v113 quad_perm:[2,3,0,1] row_mask:0xf bank_mask:0xf
	v_cndmask_b32_e64 v112, v115, v114, s[4:5]
	v_cndmask_b32_e64 v117, v112, v116, s[6:7]
	v_cndmask_b32_e64 v118, v116, v112, s[6:7]
	s_waitcnt vmcnt(25)
	v_pk_mul_f32 v[252:253], v[236:237], v[100:101] op_sel_hi:[1,0]
	v_pk_mul_f32 v[254:255], v[244:245], v[100:101] op_sel_hi:[1,0]
	v_pk_fma_f32 v[252:253], v[238:239], v[100:101], v[252:253] op_sel:[0,1,0]
	v_pk_fma_f32 v[254:255], v[246:247], v[100:101], v[254:255] op_sel:[0,1,0]
	v_pk_fma_f32 v[252:253], v[240:241], v[102:103], v[252:253] op_sel_hi:[1,0,1]
	v_pk_fma_f32 v[254:255], v[248:249], v[102:103], v[254:255] op_sel_hi:[1,0,1]
	v_pk_fma_f32 v[252:253], v[242:243], v[102:103], v[252:253] op_sel:[0,1,0]
	v_pk_fma_f32 v[254:255], v[250:251], v[102:103], v[254:255] op_sel:[0,1,0]
	v_add_f32_dpp v116, v118, v117 row_ror:4 row_mask:0xf bank_mask:0xf
	v_cndmask_b32_e64 v125, v116, v124, s[64:65]
	v_cndmask_b32_e64 v126, v124, v116, s[64:65]
	v_add_f32_dpp v104, v140, v140 quad_perm:[1,0,3,2] row_mask:0xf bank_mask:0xf
	v_add_f32_dpp v105, v141, v141 quad_perm:[1,0,3,2] row_mask:0xf bank_mask:0xf
	v_add_f32_dpp v106, v142, v142 quad_perm:[1,0,3,2] row_mask:0xf bank_mask:0xf
	v_add_f32_dpp v107, v143, v143 quad_perm:[1,0,3,2] row_mask:0xf bank_mask:0xf
	v_cndmask_b32_e32 v104, v106, v104, vcc
	v_cndmask_b32_e32 v105, v107, v105, vcc
	v_add_f32_dpp v110, v108, v108 quad_perm:[2,3,0,1] row_mask:0xf bank_mask:0xf
	v_add_f32_dpp v111, v109, v109 quad_perm:[2,3,0,1] row_mask:0xf bank_mask:0xf
	v_cndmask_b32_e64 v108, v111, v110, s[4:5]
	s_waitcnt vmcnt(24)
	v_pk_mul_f32 v[140:141], v[236:237], v[96:97] op_sel_hi:[1,0]
	v_pk_mul_f32 v[142:143], v[244:245], v[96:97] op_sel_hi:[1,0]
	v_pk_fma_f32 v[140:141], v[238:239], v[96:97], v[140:141] op_sel:[0,1,0]
	v_pk_fma_f32 v[142:143], v[246:247], v[96:97], v[142:143] op_sel:[0,1,0]
	v_pk_fma_f32 v[140:141], v[240:241], v[98:99], v[140:141] op_sel_hi:[1,0,1]
	v_pk_fma_f32 v[142:143], v[248:249], v[98:99], v[142:143] op_sel_hi:[1,0,1]
	v_pk_fma_f32 v[140:141], v[242:243], v[98:99], v[140:141] op_sel:[0,1,0]
	v_pk_fma_f32 v[142:143], v[250:251], v[98:99], v[142:143] op_sel:[0,1,0]
	v_add_f32_dpp v124, v126, v125 row_ror:8 row_mask:0xf bank_mask:0xf
	v_add_f32_dpp v100, v252, v252 quad_perm:[1,0,3,2] row_mask:0xf bank_mask:0xf
	v_add_f32_dpp v101, v253, v253 quad_perm:[1,0,3,2] row_mask:0xf bank_mask:0xf
	v_add_f32_dpp v102, v254, v254 quad_perm:[1,0,3,2] row_mask:0xf bank_mask:0xf
	v_add_f32_dpp v103, v255, v255 quad_perm:[1,0,3,2] row_mask:0xf bank_mask:0xf
	v_cndmask_b32_e32 v100, v102, v100, vcc
	v_cndmask_b32_e32 v101, v103, v101, vcc
	v_add_f32_dpp v106, v104, v104 quad_perm:[2,3,0,1] row_mask:0xf bank_mask:0xf
	v_add_f32_dpp v107, v105, v105 quad_perm:[2,3,0,1] row_mask:0xf bank_mask:0xf
	v_cndmask_b32_e64 v104, v107, v106, s[4:5]
	v_cndmask_b32_e64 v109, v104, v108, s[6:7]
	v_cndmask_b32_e64 v110, v108, v104, s[6:7]
	s_waitcnt vmcnt(23)
; DI void attn_sample_item(const Params& p, int item, ldsp lds, int tid_) {
;     ...
;   SC_SCORE(kvA, 0)
;   SC_SCORE(kvB, 1)
	v_pk_mul_f32 v[252:253], v[236:237], v[92:93] op_sel_hi:[1,0]
	v_pk_mul_f32 v[254:255], v[244:245], v[92:93] op_sel_hi:[1,0]
	v_pk_fma_f32 v[252:253], v[238:239], v[92:93], v[252:253] op_sel:[0,1,0]
	v_pk_fma_f32 v[254:255], v[246:247], v[92:93], v[254:255] op_sel:[0,1,0]
	v_pk_fma_f32 v[252:253], v[240:241], v[94:95], v[252:253] op_sel_hi:[1,0,1]
	v_pk_fma_f32 v[254:255], v[248:249], v[94:95], v[254:255] op_sel_hi:[1,0,1]
	v_pk_fma_f32 v[252:253], v[242:243], v[94:95], v[252:253] op_sel:[0,1,0]
	v_pk_fma_f32 v[254:255], v[250:251], v[94:95], v[254:255] op_sel:[0,1,0]
	v_add_f32_dpp v108, v110, v109 row_ror:4 row_mask:0xf bank_mask:0xf
	v_add_f32_dpp v96, v140, v140 quad_perm:[1,0,3,2] row_mask:0xf bank_mask:0xf
	v_add_f32_dpp v97, v141, v141 quad_perm:[1,0,3,2] row_mask:0xf bank_mask:0xf
	v_add_f32_dpp v98, v142, v142 quad_perm:[1,0,3,2] row_mask:0xf bank_mask:0xf
	v_add_f32_dpp v99, v143, v143 quad_perm:[1,0,3,2] row_mask:0xf bank_mask:0xf
	v_cndmask_b32_e32 v96, v98, v96, vcc
	v_cndmask_b32_e32 v97, v99, v97, vcc
	v_add_f32_dpp v102, v100, v100 quad_perm:[2,3,0,1] row_mask:0xf bank_mask:0xf
	v_add_f32_dpp v103, v101, v101 quad_perm:[2,3,0,1] row_mask:0xf bank_mask:0xf
	v_cndmask_b32_e64 v100, v103, v102, s[4:5]
	s_waitcnt vmcnt(22)
	v_pk_mul_f32 v[140:141], v[236:237], v[88:89] op_sel_hi:[1,0]
	v_pk_mul_f32 v[142:143], v[244:245], v[88:89] op_sel_hi:[1,0]
	v_pk_fma_f32 v[140:141], v[238:239], v[88:89], v[140:141] op_sel:[0,1,0]
	v_pk_fma_f32 v[142:143], v[246:247], v[88:89], v[142:143] op_sel:[0,1,0]
	v_pk_fma_f32 v[140:141], v[240:241], v[90:91], v[140:141] op_sel_hi:[1,0,1]
	v_pk_fma_f32 v[142:143], v[248:249], v[90:91], v[142:143] op_sel_hi:[1,0,1]
	v_pk_fma_f32 v[140:141], v[242:243], v[90:91], v[140:141] op_sel:[0,1,0]
	v_pk_fma_f32 v[142:143], v[250:251], v[90:91], v[142:143] op_sel:[0,1,0]
	v_add_f32_dpp v92, v252, v252 quad_perm:[1,0,3,2] row_mask:0xf bank_mask:0xf
	v_add_f32_dpp v93, v253, v253 quad_perm:[1,0,3,2] row_mask:0xf bank_mask:0xf
	v_add_f32_dpp v94, v254, v254 quad_perm:[1,0,3,2] row_mask:0xf bank_mask:0xf
	v_add_f32_dpp v95, v255, v255 quad_perm:[1,0,3,2] row_mask:0xf bank_mask:0xf
	v_cndmask_b32_e32 v92, v94, v92, vcc
	v_cndmask_b32_e32 v93, v95, v93, vcc
	v_add_f32_dpp v98, v96, v96 quad_perm:[2,3,0,1] row_mask:0xf bank_mask:0xf
	v_add_f32_dpp v99, v97, v97 quad_perm:[2,3,0,1] row_mask:0xf bank_mask:0xf
	v_cndmask_b32_e64 v96, v99, v98, s[4:5]
	v_cndmask_b32_e64 v101, v96, v100, s[6:7]
	v_cndmask_b32_e64 v102, v100, v96, s[6:7]
	s_waitcnt vmcnt(21)
	v_pk_mul_f32 v[252:253], v[236:237], v[84:85] op_sel_hi:[1,0]
	v_pk_mul_f32 v[254:255], v[244:245], v[84:85] op_sel_hi:[1,0]
	v_pk_fma_f32 v[252:253], v[238:239], v[84:85], v[252:253] op_sel:[0,1,0]
	v_pk_fma_f32 v[254:255], v[246:247], v[84:85], v[254:255] op_sel:[0,1,0]
	v_pk_fma_f32 v[252:253], v[240:241], v[86:87], v[252:253] op_sel_hi:[1,0,1]
	v_pk_fma_f32 v[254:255], v[248:249], v[86:87], v[254:255] op_sel_hi:[1,0,1]
	v_pk_fma_f32 v[252:253], v[242:243], v[86:87], v[252:253] op_sel:[0,1,0]
	v_pk_fma_f32 v[254:255], v[250:251], v[86:87], v[254:255] op_sel:[0,1,0]
	v_add_f32_dpp v100, v102, v101 row_ror:4 row_mask:0xf bank_mask:0xf
	v_cndmask_b32_e64 v109, v100, v108, s[64:65]
	v_cndmask_b32_e64 v110, v108, v100, s[64:65]
	v_add_f32_dpp v88, v140, v140 quad_perm:[1,0,3,2] row_mask:0xf bank_mask:0xf
	v_add_f32_dpp v89, v141, v141 quad_perm:[1,0,3,2] row_mask:0xf bank_mask:0xf
	v_add_f32_dpp v90, v142, v142 quad_perm:[1,0,3,2] row_mask:0xf bank_mask:0xf
	v_add_f32_dpp v91, v143, v143 quad_perm:[1,0,3,2] row_mask:0xf bank_mask:0xf
	v_cndmask_b32_e32 v88, v90, v88, vcc
	v_cndmask_b32_e32 v89, v91, v89, vcc
	v_add_f32_dpp v94, v92, v92 quad_perm:[2,3,0,1] row_mask:0xf bank_mask:0xf
	v_add_f32_dpp v95, v93, v93 quad_perm:[2,3,0,1] row_mask:0xf bank_mask:0xf
	v_cndmask_b32_e64 v92, v95, v94, s[4:5]
	s_waitcnt vmcnt(20)
	v_pk_mul_f32 v[140:141], v[236:237], v[80:81] op_sel_hi:[1,0]
	v_pk_mul_f32 v[142:143], v[244:245], v[80:81] op_sel_hi:[1,0]
	v_pk_fma_f32 v[140:141], v[238:239], v[80:81], v[140:141] op_sel:[0,1,0]
	v_pk_fma_f32 v[142:143], v[246:247], v[80:81], v[142:143] op_sel:[0,1,0]
	v_pk_fma_f32 v[140:141], v[240:241], v[82:83], v[140:141] op_sel_hi:[1,0,1]
	v_pk_fma_f32 v[142:143], v[248:249], v[82:83], v[142:143] op_sel_hi:[1,0,1]
	v_pk_fma_f32 v[140:141], v[242:243], v[82:83], v[140:141] op_sel:[0,1,0]
	v_pk_fma_f32 v[142:143], v[250:251], v[82:83], v[142:143] op_sel:[0,1,0]
	v_add_f32_dpp v108, v110, v109 row_ror:8 row_mask:0xf bank_mask:0xf
	v_add_f32_dpp v84, v252, v252 quad_perm:[1,0,3,2] row_mask:0xf bank_mask:0xf
	v_add_f32_dpp v85, v253, v253 quad_perm:[1,0,3,2] row_mask:0xf bank_mask:0xf
	v_add_f32_dpp v86, v254, v254 quad_perm:[1,0,3,2] row_mask:0xf bank_mask:0xf
	v_add_f32_dpp v87, v255, v255 quad_perm:[1,0,3,2] row_mask:0xf bank_mask:0xf
	v_cndmask_b32_e32 v84, v86, v84, vcc
	v_cndmask_b32_e32 v85, v87, v85, vcc
	v_add_f32_dpp v90, v88, v88 quad_perm:[2,3,0,1] row_mask:0xf bank_mask:0xf
	v_add_f32_dpp v91, v89, v89 quad_perm:[2,3,0,1] row_mask:0xf bank_mask:0xf
	v_cndmask_b32_e64 v88, v91, v90, s[4:5]
	v_cndmask_b32_e64 v93, v88, v92, s[6:7]
	v_cndmask_b32_e64 v94, v92, v88, s[6:7]
	s_waitcnt vmcnt(19)
; DI void attn_sample_item(const Params& p, int item, ldsp lds, int tid_) {
;     ...
;   SC_SCORE(kvA, 0)
;   SC_SCORE(kvB, 1)
	v_pk_mul_f32 v[252:253], v[236:237], v[76:77] op_sel_hi:[1,0]
	v_pk_mul_f32 v[254:255], v[244:245], v[76:77] op_sel_hi:[1,0]
	v_pk_fma_f32 v[252:253], v[238:239], v[76:77], v[252:253] op_sel:[0,1,0]
	v_pk_fma_f32 v[254:255], v[246:247], v[76:77], v[254:255] op_sel:[0,1,0]
	v_pk_fma_f32 v[252:253], v[240:241], v[78:79], v[252:253] op_sel_hi:[1,0,1]
	v_pk_fma_f32 v[254:255], v[248:249], v[78:79], v[254:255] op_sel_hi:[1,0,1]
	v_pk_fma_f32 v[252:253], v[242:243], v[78:79], v[252:253] op_sel:[0,1,0]
	v_pk_fma_f32 v[254:255], v[250:251], v[78:79], v[254:255] op_sel:[0,1,0]
	v_permlane16_swap_b32_e32 v124, v108
	v_add_f32_e32 v124, v124, v108
	v_add_f32_dpp v92, v94, v93 row_ror:4 row_mask:0xf bank_mask:0xf
	v_add_f32_dpp v80, v140, v140 quad_perm:[1,0,3,2] row_mask:0xf bank_mask:0xf
	v_add_f32_dpp v81, v141, v141 quad_perm:[1,0,3,2] row_mask:0xf bank_mask:0xf
	v_add_f32_dpp v82, v142, v142 quad_perm:[1,0,3,2] row_mask:0xf bank_mask:0xf
	v_add_f32_dpp v83, v143, v143 quad_perm:[1,0,3,2] row_mask:0xf bank_mask:0xf
	v_cndmask_b32_e32 v80, v82, v80, vcc
	v_cndmask_b32_e32 v81, v83, v81, vcc
	v_add_f32_dpp v86, v84, v84 quad_perm:[2,3,0,1] row_mask:0xf bank_mask:0xf
	v_add_f32_dpp v87, v85, v85 quad_perm:[2,3,0,1] row_mask:0xf bank_mask:0xf
	v_cndmask_b32_e64 v84, v87, v86, s[4:5]
	s_waitcnt vmcnt(18)
	v_pk_mul_f32 v[140:141], v[236:237], v[72:73] op_sel_hi:[1,0]
	v_pk_mul_f32 v[142:143], v[244:245], v[72:73] op_sel_hi:[1,0]
	v_pk_fma_f32 v[140:141], v[238:239], v[72:73], v[140:141] op_sel:[0,1,0]
	v_pk_fma_f32 v[142:143], v[246:247], v[72:73], v[142:143] op_sel:[0,1,0]
	v_pk_fma_f32 v[140:141], v[240:241], v[74:75], v[140:141] op_sel_hi:[1,0,1]
	v_pk_fma_f32 v[142:143], v[248:249], v[74:75], v[142:143] op_sel_hi:[1,0,1]
	v_pk_fma_f32 v[140:141], v[242:243], v[74:75], v[140:141] op_sel:[0,1,0]
	v_pk_fma_f32 v[142:143], v[250:251], v[74:75], v[142:143] op_sel:[0,1,0]
	v_add_f32_dpp v76, v252, v252 quad_perm:[1,0,3,2] row_mask:0xf bank_mask:0xf
	v_add_f32_dpp v77, v253, v253 quad_perm:[1,0,3,2] row_mask:0xf bank_mask:0xf
	v_add_f32_dpp v78, v254, v254 quad_perm:[1,0,3,2] row_mask:0xf bank_mask:0xf
	v_add_f32_dpp v79, v255, v255 quad_perm:[1,0,3,2] row_mask:0xf bank_mask:0xf
	v_cndmask_b32_e32 v76, v78, v76, vcc
	v_cndmask_b32_e32 v77, v79, v77, vcc
	v_add_f32_dpp v82, v80, v80 quad_perm:[2,3,0,1] row_mask:0xf bank_mask:0xf
	v_add_f32_dpp v83, v81, v81 quad_perm:[2,3,0,1] row_mask:0xf bank_mask:0xf
	v_cndmask_b32_e64 v80, v83, v82, s[4:5]
	v_cndmask_b32_e64 v85, v80, v84, s[6:7]
	v_cndmask_b32_e64 v86, v84, v80, s[6:7]
	s_waitcnt vmcnt(17)
	v_pk_mul_f32 v[252:253], v[236:237], v[68:69] op_sel_hi:[1,0]
	v_pk_mul_f32 v[254:255], v[244:245], v[68:69] op_sel_hi:[1,0]
	v_pk_fma_f32 v[252:253], v[238:239], v[68:69], v[252:253] op_sel:[0,1,0]
	v_pk_fma_f32 v[254:255], v[246:247], v[68:69], v[254:255] op_sel:[0,1,0]
	v_pk_fma_f32 v[252:253], v[240:241], v[70:71], v[252:253] op_sel_hi:[1,0,1]
	v_pk_fma_f32 v[254:255], v[248:249], v[70:71], v[254:255] op_sel_hi:[1,0,1]
	v_pk_fma_f32 v[252:253], v[242:243], v[70:71], v[252:253] op_sel:[0,1,0]
	v_pk_fma_f32 v[254:255], v[250:251], v[70:71], v[254:255] op_sel:[0,1,0]
	v_add_f32_dpp v84, v86, v85 row_ror:4 row_mask:0xf bank_mask:0xf
	v_cndmask_b32_e64 v93, v84, v92, s[64:65]
	v_cndmask_b32_e64 v94, v92, v84, s[64:65]
	v_add_f32_dpp v72, v140, v140 quad_perm:[1,0,3,2] row_mask:0xf bank_mask:0xf
	v_add_f32_dpp v73, v141, v141 quad_perm:[1,0,3,2] row_mask:0xf bank_mask:0xf
	v_add_f32_dpp v74, v142, v142 quad_perm:[1,0,3,2] row_mask:0xf bank_mask:0xf
	v_add_f32_dpp v75, v143, v143 quad_perm:[1,0,3,2] row_mask:0xf bank_mask:0xf
	v_cndmask_b32_e32 v72, v74, v72, vcc
	v_cndmask_b32_e32 v73, v75, v73, vcc
	v_add_f32_dpp v78, v76, v76 quad_perm:[2,3,0,1] row_mask:0xf bank_mask:0xf
	v_add_f32_dpp v79, v77, v77 quad_perm:[2,3,0,1] row_mask:0xf bank_mask:0xf
	v_cndmask_b32_e64 v76, v79, v78, s[4:5]
	s_waitcnt vmcnt(16)
	v_pk_mul_f32 v[140:141], v[236:237], v[64:65] op_sel_hi:[1,0]
	v_pk_mul_f32 v[142:143], v[244:245], v[64:65] op_sel_hi:[1,0]
	v_pk_fma_f32 v[140:141], v[238:239], v[64:65], v[140:141] op_sel:[0,1,0]
	v_pk_fma_f32 v[142:143], v[246:247], v[64:65], v[142:143] op_sel:[0,1,0]
	v_pk_fma_f32 v[140:141], v[240:241], v[66:67], v[140:141] op_sel_hi:[1,0,1]
	v_pk_fma_f32 v[142:143], v[248:249], v[66:67], v[142:143] op_sel_hi:[1,0,1]
	v_pk_fma_f32 v[140:141], v[242:243], v[66:67], v[140:141] op_sel:[0,1,0]
	v_pk_fma_f32 v[142:143], v[250:251], v[66:67], v[142:143] op_sel:[0,1,0]
	v_add_f32_dpp v92, v94, v93 row_ror:8 row_mask:0xf bank_mask:0xf
	v_add_f32_dpp v68, v252, v252 quad_perm:[1,0,3,2] row_mask:0xf bank_mask:0xf
	v_add_f32_dpp v69, v253, v253 quad_perm:[1,0,3,2] row_mask:0xf bank_mask:0xf
	v_add_f32_dpp v70, v254, v254 quad_perm:[1,0,3,2] row_mask:0xf bank_mask:0xf
	v_add_f32_dpp v71, v255, v255 quad_perm:[1,0,3,2] row_mask:0xf bank_mask:0xf
	v_cndmask_b32_e32 v68, v70, v68, vcc
	v_cndmask_b32_e32 v69, v71, v69, vcc
	v_add_f32_dpp v74, v72, v72 quad_perm:[2,3,0,1] row_mask:0xf bank_mask:0xf
	v_add_f32_dpp v75, v73, v73 quad_perm:[2,3,0,1] row_mask:0xf bank_mask:0xf
	v_cndmask_b32_e64 v72, v75, v74, s[4:5]
	v_cndmask_b32_e64 v77, v72, v76, s[6:7]
	v_cndmask_b32_e64 v78, v76, v72, s[6:7]
	s_waitcnt vmcnt(15)
; DI void attn_sample_item(const Params& p, int item, ldsp lds, int tid_) {
;     ...
;   SC_SCORE(kvA, 0)
;   SC_SCORE(kvB, 1)
	v_pk_mul_f32 v[252:253], v[236:237], v[60:61] op_sel_hi:[1,0]
	v_pk_mul_f32 v[254:255], v[244:245], v[60:61] op_sel_hi:[1,0]
	v_pk_fma_f32 v[252:253], v[238:239], v[60:61], v[252:253] op_sel:[0,1,0]
	v_pk_fma_f32 v[254:255], v[246:247], v[60:61], v[254:255] op_sel:[0,1,0]
	v_pk_fma_f32 v[252:253], v[240:241], v[62:63], v[252:253] op_sel_hi:[1,0,1]
	v_pk_fma_f32 v[254:255], v[248:249], v[62:63], v[254:255] op_sel_hi:[1,0,1]
	v_pk_fma_f32 v[252:253], v[242:243], v[62:63], v[252:253] op_sel:[0,1,0]
	v_pk_fma_f32 v[254:255], v[250:251], v[62:63], v[254:255] op_sel:[0,1,0]
	v_add_f32_dpp v76, v78, v77 row_ror:4 row_mask:0xf bank_mask:0xf
	v_add_f32_dpp v64, v140, v140 quad_perm:[1,0,3,2] row_mask:0xf bank_mask:0xf
	v_add_f32_dpp v65, v141, v141 quad_perm:[1,0,3,2] row_mask:0xf bank_mask:0xf
	v_add_f32_dpp v66, v142, v142 quad_perm:[1,0,3,2] row_mask:0xf bank_mask:0xf
	v_add_f32_dpp v67, v143, v143 quad_perm:[1,0,3,2] row_mask:0xf bank_mask:0xf
	v_cndmask_b32_e32 v64, v66, v64, vcc
	v_cndmask_b32_e32 v65, v67, v65, vcc
	v_add_f32_dpp v70, v68, v68 quad_perm:[2,3,0,1] row_mask:0xf bank_mask:0xf
	v_add_f32_dpp v71, v69, v69 quad_perm:[2,3,0,1] row_mask:0xf bank_mask:0xf
	v_cndmask_b32_e64 v68, v71, v70, s[4:5]
	s_waitcnt vmcnt(14)
	v_pk_mul_f32 v[140:141], v[236:237], v[56:57] op_sel_hi:[1,0]
	v_pk_mul_f32 v[142:143], v[244:245], v[56:57] op_sel_hi:[1,0]
	v_pk_fma_f32 v[140:141], v[238:239], v[56:57], v[140:141] op_sel:[0,1,0]
	v_pk_fma_f32 v[142:143], v[246:247], v[56:57], v[142:143] op_sel:[0,1,0]
	v_pk_fma_f32 v[140:141], v[240:241], v[58:59], v[140:141] op_sel_hi:[1,0,1]
	v_pk_fma_f32 v[142:143], v[248:249], v[58:59], v[142:143] op_sel_hi:[1,0,1]
	v_pk_fma_f32 v[140:141], v[242:243], v[58:59], v[140:141] op_sel:[0,1,0]
	v_pk_fma_f32 v[142:143], v[250:251], v[58:59], v[142:143] op_sel:[0,1,0]
	v_add_f32_dpp v60, v252, v252 quad_perm:[1,0,3,2] row_mask:0xf bank_mask:0xf
	v_add_f32_dpp v61, v253, v253 quad_perm:[1,0,3,2] row_mask:0xf bank_mask:0xf
	v_add_f32_dpp v62, v254, v254 quad_perm:[1,0,3,2] row_mask:0xf bank_mask:0xf
	v_add_f32_dpp v63, v255, v255 quad_perm:[1,0,3,2] row_mask:0xf bank_mask:0xf
	v_cndmask_b32_e32 v60, v62, v60, vcc
	v_cndmask_b32_e32 v61, v63, v61, vcc
	v_add_f32_dpp v66, v64, v64 quad_perm:[2,3,0,1] row_mask:0xf bank_mask:0xf
	v_add_f32_dpp v67, v65, v65 quad_perm:[2,3,0,1] row_mask:0xf bank_mask:0xf
	v_cndmask_b32_e64 v64, v67, v66, s[4:5]
	v_cndmask_b32_e64 v69, v64, v68, s[6:7]
	v_cndmask_b32_e64 v70, v68, v64, s[6:7]
	s_waitcnt vmcnt(13)
	v_pk_mul_f32 v[252:253], v[236:237], v[52:53] op_sel_hi:[1,0]
	v_pk_mul_f32 v[254:255], v[244:245], v[52:53] op_sel_hi:[1,0]
	v_pk_fma_f32 v[252:253], v[238:239], v[52:53], v[252:253] op_sel:[0,1,0]
	v_pk_fma_f32 v[254:255], v[246:247], v[52:53], v[254:255] op_sel:[0,1,0]
	v_pk_fma_f32 v[252:253], v[240:241], v[54:55], v[252:253] op_sel_hi:[1,0,1]
	v_pk_fma_f32 v[254:255], v[248:249], v[54:55], v[254:255] op_sel_hi:[1,0,1]
	v_pk_fma_f32 v[252:253], v[242:243], v[54:55], v[252:253] op_sel:[0,1,0]
	v_pk_fma_f32 v[254:255], v[250:251], v[54:55], v[254:255] op_sel:[0,1,0]
	v_add_f32_dpp v68, v70, v69 row_ror:4 row_mask:0xf bank_mask:0xf
	v_cndmask_b32_e64 v77, v68, v76, s[64:65]
	v_cndmask_b32_e64 v78, v76, v68, s[64:65]
	v_add_f32_dpp v56, v140, v140 quad_perm:[1,0,3,2] row_mask:0xf bank_mask:0xf
	v_add_f32_dpp v57, v141, v141 quad_perm:[1,0,3,2] row_mask:0xf bank_mask:0xf
	v_add_f32_dpp v58, v142, v142 quad_perm:[1,0,3,2] row_mask:0xf bank_mask:0xf
	v_add_f32_dpp v59, v143, v143 quad_perm:[1,0,3,2] row_mask:0xf bank_mask:0xf
	v_cndmask_b32_e32 v56, v58, v56, vcc
	v_cndmask_b32_e32 v57, v59, v57, vcc
	v_add_f32_dpp v62, v60, v60 quad_perm:[2,3,0,1] row_mask:0xf bank_mask:0xf
	v_add_f32_dpp v63, v61, v61 quad_perm:[2,3,0,1] row_mask:0xf bank_mask:0xf
	v_cndmask_b32_e64 v60, v63, v62, s[4:5]
	s_waitcnt vmcnt(12)
	v_pk_mul_f32 v[140:141], v[236:237], v[48:49] op_sel_hi:[1,0]
	v_pk_mul_f32 v[142:143], v[244:245], v[48:49] op_sel_hi:[1,0]
	v_pk_fma_f32 v[140:141], v[238:239], v[48:49], v[140:141] op_sel:[0,1,0]
	v_pk_fma_f32 v[142:143], v[246:247], v[48:49], v[142:143] op_sel:[0,1,0]
	v_pk_fma_f32 v[140:141], v[240:241], v[50:51], v[140:141] op_sel_hi:[1,0,1]
	v_pk_fma_f32 v[142:143], v[248:249], v[50:51], v[142:143] op_sel_hi:[1,0,1]
	v_pk_fma_f32 v[140:141], v[242:243], v[50:51], v[140:141] op_sel:[0,1,0]
	v_pk_fma_f32 v[142:143], v[250:251], v[50:51], v[142:143] op_sel:[0,1,0]
	v_add_f32_dpp v76, v78, v77 row_ror:8 row_mask:0xf bank_mask:0xf
	v_add_f32_dpp v52, v252, v252 quad_perm:[1,0,3,2] row_mask:0xf bank_mask:0xf
	v_add_f32_dpp v53, v253, v253 quad_perm:[1,0,3,2] row_mask:0xf bank_mask:0xf
	v_add_f32_dpp v54, v254, v254 quad_perm:[1,0,3,2] row_mask:0xf bank_mask:0xf
	v_add_f32_dpp v55, v255, v255 quad_perm:[1,0,3,2] row_mask:0xf bank_mask:0xf
	v_cndmask_b32_e32 v52, v54, v52, vcc
	v_cndmask_b32_e32 v53, v55, v53, vcc
	v_add_f32_dpp v58, v56, v56 quad_perm:[2,3,0,1] row_mask:0xf bank_mask:0xf
	v_add_f32_dpp v59, v57, v57 quad_perm:[2,3,0,1] row_mask:0xf bank_mask:0xf
	v_cndmask_b32_e64 v56, v59, v58, s[4:5]
	v_cndmask_b32_e64 v61, v56, v60, s[6:7]
	v_cndmask_b32_e64 v62, v60, v56, s[6:7]
	s_waitcnt vmcnt(11)
; DI void attn_sample_item(const Params& p, int item, ldsp lds, int tid_) {
;     ...
;   SC_SCORE(kvA, 0)
;   SC_SCORE(kvB, 1)
	v_pk_mul_f32 v[252:253], v[236:237], v[44:45] op_sel_hi:[1,0]
	v_pk_mul_f32 v[254:255], v[244:245], v[44:45] op_sel_hi:[1,0]
	v_pk_fma_f32 v[252:253], v[238:239], v[44:45], v[252:253] op_sel:[0,1,0]
	v_pk_fma_f32 v[254:255], v[246:247], v[44:45], v[254:255] op_sel:[0,1,0]
	v_pk_fma_f32 v[252:253], v[240:241], v[46:47], v[252:253] op_sel_hi:[1,0,1]
	v_pk_fma_f32 v[254:255], v[248:249], v[46:47], v[254:255] op_sel_hi:[1,0,1]
	v_pk_fma_f32 v[252:253], v[242:243], v[46:47], v[252:253] op_sel:[0,1,0]
	v_pk_fma_f32 v[254:255], v[250:251], v[46:47], v[254:255] op_sel:[0,1,0]
	v_permlane16_swap_b32_e32 v92, v76
	v_add_f32_e32 v92, v92, v76
	v_add_f32_dpp v60, v62, v61 row_ror:4 row_mask:0xf bank_mask:0xf
	v_add_f32_dpp v48, v140, v140 quad_perm:[1,0,3,2] row_mask:0xf bank_mask:0xf
	v_add_f32_dpp v49, v141, v141 quad_perm:[1,0,3,2] row_mask:0xf bank_mask:0xf
	v_add_f32_dpp v50, v142, v142 quad_perm:[1,0,3,2] row_mask:0xf bank_mask:0xf
	v_add_f32_dpp v51, v143, v143 quad_perm:[1,0,3,2] row_mask:0xf bank_mask:0xf
	v_cndmask_b32_e32 v48, v50, v48, vcc
	v_cndmask_b32_e32 v49, v51, v49, vcc
	v_add_f32_dpp v54, v52, v52 quad_perm:[2,3,0,1] row_mask:0xf bank_mask:0xf
	v_add_f32_dpp v55, v53, v53 quad_perm:[2,3,0,1] row_mask:0xf bank_mask:0xf
	v_cndmask_b32_e64 v52, v55, v54, s[4:5]
	s_waitcnt vmcnt(10)
	v_pk_mul_f32 v[140:141], v[236:237], v[40:41] op_sel_hi:[1,0]
	v_pk_mul_f32 v[142:143], v[244:245], v[40:41] op_sel_hi:[1,0]
	v_pk_fma_f32 v[140:141], v[238:239], v[40:41], v[140:141] op_sel:[0,1,0]
	v_pk_fma_f32 v[142:143], v[246:247], v[40:41], v[142:143] op_sel:[0,1,0]
	v_pk_fma_f32 v[140:141], v[240:241], v[42:43], v[140:141] op_sel_hi:[1,0,1]
	v_pk_fma_f32 v[142:143], v[248:249], v[42:43], v[142:143] op_sel_hi:[1,0,1]
	v_pk_fma_f32 v[140:141], v[242:243], v[42:43], v[140:141] op_sel:[0,1,0]
	v_pk_fma_f32 v[142:143], v[250:251], v[42:43], v[142:143] op_sel:[0,1,0]
	v_permlane32_swap_b32_e32 v124, v92
	v_add_f32_e32 v124, v124, v92
	ds_write_b32 v235, v124
	v_add_f32_dpp v44, v252, v252 quad_perm:[1,0,3,2] row_mask:0xf bank_mask:0xf
	v_add_f32_dpp v45, v253, v253 quad_perm:[1,0,3,2] row_mask:0xf bank_mask:0xf
	v_add_f32_dpp v46, v254, v254 quad_perm:[1,0,3,2] row_mask:0xf bank_mask:0xf
	v_add_f32_dpp v47, v255, v255 quad_perm:[1,0,3,2] row_mask:0xf bank_mask:0xf
	v_cndmask_b32_e32 v44, v46, v44, vcc
	v_cndmask_b32_e32 v45, v47, v45, vcc
	v_add_f32_dpp v50, v48, v48 quad_perm:[2,3,0,1] row_mask:0xf bank_mask:0xf
	v_add_f32_dpp v51, v49, v49 quad_perm:[2,3,0,1] row_mask:0xf bank_mask:0xf
	v_cndmask_b32_e64 v48, v51, v50, s[4:5]
	v_cndmask_b32_e64 v53, v48, v52, s[6:7]
	v_cndmask_b32_e64 v54, v52, v48, s[6:7]
	s_waitcnt vmcnt(9)
	v_pk_mul_f32 v[252:253], v[236:237], v[36:37] op_sel_hi:[1,0]
	v_pk_mul_f32 v[254:255], v[244:245], v[36:37] op_sel_hi:[1,0]
	v_pk_fma_f32 v[252:253], v[238:239], v[36:37], v[252:253] op_sel:[0,1,0]
	v_pk_fma_f32 v[254:255], v[246:247], v[36:37], v[254:255] op_sel:[0,1,0]
	v_pk_fma_f32 v[252:253], v[240:241], v[38:39], v[252:253] op_sel_hi:[1,0,1]
	v_pk_fma_f32 v[254:255], v[248:249], v[38:39], v[254:255] op_sel_hi:[1,0,1]
	v_pk_fma_f32 v[252:253], v[242:243], v[38:39], v[252:253] op_sel:[0,1,0]
	v_pk_fma_f32 v[254:255], v[250:251], v[38:39], v[254:255] op_sel:[0,1,0]
	v_add_f32_dpp v52, v54, v53 row_ror:4 row_mask:0xf bank_mask:0xf
	v_cndmask_b32_e64 v61, v52, v60, s[64:65]
	v_cndmask_b32_e64 v62, v60, v52, s[64:65]
	v_add_f32_dpp v40, v140, v140 quad_perm:[1,0,3,2] row_mask:0xf bank_mask:0xf
	v_add_f32_dpp v41, v141, v141 quad_perm:[1,0,3,2] row_mask:0xf bank_mask:0xf
	v_add_f32_dpp v42, v142, v142 quad_perm:[1,0,3,2] row_mask:0xf bank_mask:0xf
	v_add_f32_dpp v43, v143, v143 quad_perm:[1,0,3,2] row_mask:0xf bank_mask:0xf
	v_cndmask_b32_e32 v40, v42, v40, vcc
	v_cndmask_b32_e32 v41, v43, v41, vcc
	v_add_f32_dpp v46, v44, v44 quad_perm:[2,3,0,1] row_mask:0xf bank_mask:0xf
	v_add_f32_dpp v47, v45, v45 quad_perm:[2,3,0,1] row_mask:0xf bank_mask:0xf
	v_cndmask_b32_e64 v44, v47, v46, s[4:5]
	s_waitcnt vmcnt(8)
	v_pk_mul_f32 v[140:141], v[236:237], v[32:33] op_sel_hi:[1,0]
	v_pk_mul_f32 v[142:143], v[244:245], v[32:33] op_sel_hi:[1,0]
	v_pk_fma_f32 v[140:141], v[238:239], v[32:33], v[140:141] op_sel:[0,1,0]
	v_pk_fma_f32 v[142:143], v[246:247], v[32:33], v[142:143] op_sel:[0,1,0]
	v_pk_fma_f32 v[140:141], v[240:241], v[34:35], v[140:141] op_sel_hi:[1,0,1]
	v_pk_fma_f32 v[142:143], v[248:249], v[34:35], v[142:143] op_sel_hi:[1,0,1]
	v_pk_fma_f32 v[140:141], v[242:243], v[34:35], v[140:141] op_sel:[0,1,0]
	v_pk_fma_f32 v[142:143], v[250:251], v[34:35], v[142:143] op_sel:[0,1,0]
	v_add_f32_dpp v60, v62, v61 row_ror:8 row_mask:0xf bank_mask:0xf
	v_add_f32_dpp v36, v252, v252 quad_perm:[1,0,3,2] row_mask:0xf bank_mask:0xf
	v_add_f32_dpp v37, v253, v253 quad_perm:[1,0,3,2] row_mask:0xf bank_mask:0xf
	v_add_f32_dpp v38, v254, v254 quad_perm:[1,0,3,2] row_mask:0xf bank_mask:0xf
	v_add_f32_dpp v39, v255, v255 quad_perm:[1,0,3,2] row_mask:0xf bank_mask:0xf
	v_cndmask_b32_e32 v36, v38, v36, vcc
	v_cndmask_b32_e32 v37, v39, v37, vcc
	v_add_f32_dpp v42, v40, v40 quad_perm:[2,3,0,1] row_mask:0xf bank_mask:0xf
	v_add_f32_dpp v43, v41, v41 quad_perm:[2,3,0,1] row_mask:0xf bank_mask:0xf
	v_cndmask_b32_e64 v40, v43, v42, s[4:5]
	v_cndmask_b32_e64 v45, v40, v44, s[6:7]
	v_cndmask_b32_e64 v46, v44, v40, s[6:7]
	s_waitcnt vmcnt(7)
; DI void attn_sample_item(const Params& p, int item, ldsp lds, int tid_) {
;     ...
;   SC_SCORE(kvA, 0)
;   SC_SCORE(kvB, 1)
	v_pk_mul_f32 v[252:253], v[236:237], v[28:29] op_sel_hi:[1,0]
	v_pk_mul_f32 v[254:255], v[244:245], v[28:29] op_sel_hi:[1,0]
	v_pk_fma_f32 v[252:253], v[238:239], v[28:29], v[252:253] op_sel:[0,1,0]
	v_pk_fma_f32 v[254:255], v[246:247], v[28:29], v[254:255] op_sel:[0,1,0]
	v_pk_fma_f32 v[252:253], v[240:241], v[30:31], v[252:253] op_sel_hi:[1,0,1]
	v_pk_fma_f32 v[254:255], v[248:249], v[30:31], v[254:255] op_sel_hi:[1,0,1]
	v_pk_fma_f32 v[252:253], v[242:243], v[30:31], v[252:253] op_sel:[0,1,0]
	v_pk_fma_f32 v[254:255], v[250:251], v[30:31], v[254:255] op_sel:[0,1,0]
	v_add_f32_dpp v44, v46, v45 row_ror:4 row_mask:0xf bank_mask:0xf
	v_add_f32_dpp v32, v140, v140 quad_perm:[1,0,3,2] row_mask:0xf bank_mask:0xf
	v_add_f32_dpp v33, v141, v141 quad_perm:[1,0,3,2] row_mask:0xf bank_mask:0xf
	v_add_f32_dpp v34, v142, v142 quad_perm:[1,0,3,2] row_mask:0xf bank_mask:0xf
	v_add_f32_dpp v35, v143, v143 quad_perm:[1,0,3,2] row_mask:0xf bank_mask:0xf
	v_cndmask_b32_e32 v32, v34, v32, vcc
	v_cndmask_b32_e32 v33, v35, v33, vcc
	v_add_f32_dpp v38, v36, v36 quad_perm:[2,3,0,1] row_mask:0xf bank_mask:0xf
	v_add_f32_dpp v39, v37, v37 quad_perm:[2,3,0,1] row_mask:0xf bank_mask:0xf
	v_cndmask_b32_e64 v36, v39, v38, s[4:5]
	s_waitcnt vmcnt(6)
	v_pk_mul_f32 v[140:141], v[236:237], v[24:25] op_sel_hi:[1,0]
	v_pk_mul_f32 v[142:143], v[244:245], v[24:25] op_sel_hi:[1,0]
	v_pk_fma_f32 v[140:141], v[238:239], v[24:25], v[140:141] op_sel:[0,1,0]
	v_pk_fma_f32 v[142:143], v[246:247], v[24:25], v[142:143] op_sel:[0,1,0]
	v_pk_fma_f32 v[140:141], v[240:241], v[26:27], v[140:141] op_sel_hi:[1,0,1]
	v_pk_fma_f32 v[142:143], v[248:249], v[26:27], v[142:143] op_sel_hi:[1,0,1]
	v_pk_fma_f32 v[140:141], v[242:243], v[26:27], v[140:141] op_sel:[0,1,0]
	v_pk_fma_f32 v[142:143], v[250:251], v[26:27], v[142:143] op_sel:[0,1,0]
	v_add_f32_dpp v28, v252, v252 quad_perm:[1,0,3,2] row_mask:0xf bank_mask:0xf
	v_add_f32_dpp v29, v253, v253 quad_perm:[1,0,3,2] row_mask:0xf bank_mask:0xf
	v_add_f32_dpp v30, v254, v254 quad_perm:[1,0,3,2] row_mask:0xf bank_mask:0xf
	v_add_f32_dpp v31, v255, v255 quad_perm:[1,0,3,2] row_mask:0xf bank_mask:0xf
	v_cndmask_b32_e32 v28, v30, v28, vcc
	v_cndmask_b32_e32 v29, v31, v29, vcc
	v_add_f32_dpp v34, v32, v32 quad_perm:[2,3,0,1] row_mask:0xf bank_mask:0xf
	v_add_f32_dpp v35, v33, v33 quad_perm:[2,3,0,1] row_mask:0xf bank_mask:0xf
	v_cndmask_b32_e64 v32, v35, v34, s[4:5]
	v_cndmask_b32_e64 v37, v32, v36, s[6:7]
	v_cndmask_b32_e64 v38, v36, v32, s[6:7]
	s_waitcnt vmcnt(5)
	v_pk_mul_f32 v[252:253], v[236:237], v[20:21] op_sel_hi:[1,0]
	v_pk_mul_f32 v[254:255], v[244:245], v[20:21] op_sel_hi:[1,0]
	v_pk_fma_f32 v[252:253], v[238:239], v[20:21], v[252:253] op_sel:[0,1,0]
	v_pk_fma_f32 v[254:255], v[246:247], v[20:21], v[254:255] op_sel:[0,1,0]
	v_pk_fma_f32 v[252:253], v[240:241], v[22:23], v[252:253] op_sel_hi:[1,0,1]
	v_pk_fma_f32 v[254:255], v[248:249], v[22:23], v[254:255] op_sel_hi:[1,0,1]
	v_pk_fma_f32 v[252:253], v[242:243], v[22:23], v[252:253] op_sel:[0,1,0]
	v_pk_fma_f32 v[254:255], v[250:251], v[22:23], v[254:255] op_sel:[0,1,0]
	v_add_f32_dpp v36, v38, v37 row_ror:4 row_mask:0xf bank_mask:0xf
	v_cndmask_b32_e64 v45, v36, v44, s[64:65]
	v_cndmask_b32_e64 v46, v44, v36, s[64:65]
	v_add_f32_dpp v24, v140, v140 quad_perm:[1,0,3,2] row_mask:0xf bank_mask:0xf
	v_add_f32_dpp v25, v141, v141 quad_perm:[1,0,3,2] row_mask:0xf bank_mask:0xf
	v_add_f32_dpp v26, v142, v142 quad_perm:[1,0,3,2] row_mask:0xf bank_mask:0xf
	v_add_f32_dpp v27, v143, v143 quad_perm:[1,0,3,2] row_mask:0xf bank_mask:0xf
	v_cndmask_b32_e32 v24, v26, v24, vcc
	v_cndmask_b32_e32 v25, v27, v25, vcc
	v_add_f32_dpp v30, v28, v28 quad_perm:[2,3,0,1] row_mask:0xf bank_mask:0xf
	v_add_f32_dpp v31, v29, v29 quad_perm:[2,3,0,1] row_mask:0xf bank_mask:0xf
	v_cndmask_b32_e64 v28, v31, v30, s[4:5]
	s_waitcnt vmcnt(4)
	v_pk_mul_f32 v[140:141], v[236:237], v[16:17] op_sel_hi:[1,0]
	v_pk_mul_f32 v[142:143], v[244:245], v[16:17] op_sel_hi:[1,0]
	v_pk_fma_f32 v[140:141], v[238:239], v[16:17], v[140:141] op_sel:[0,1,0]
	v_pk_fma_f32 v[142:143], v[246:247], v[16:17], v[142:143] op_sel:[0,1,0]
	v_pk_fma_f32 v[140:141], v[240:241], v[18:19], v[140:141] op_sel_hi:[1,0,1]
	v_pk_fma_f32 v[142:143], v[248:249], v[18:19], v[142:143] op_sel_hi:[1,0,1]
	v_pk_fma_f32 v[140:141], v[242:243], v[18:19], v[140:141] op_sel:[0,1,0]
	v_pk_fma_f32 v[142:143], v[250:251], v[18:19], v[142:143] op_sel:[0,1,0]
	v_add_f32_dpp v44, v46, v45 row_ror:8 row_mask:0xf bank_mask:0xf
	v_add_f32_dpp v20, v252, v252 quad_perm:[1,0,3,2] row_mask:0xf bank_mask:0xf
	v_add_f32_dpp v21, v253, v253 quad_perm:[1,0,3,2] row_mask:0xf bank_mask:0xf
	v_add_f32_dpp v22, v254, v254 quad_perm:[1,0,3,2] row_mask:0xf bank_mask:0xf
	v_add_f32_dpp v23, v255, v255 quad_perm:[1,0,3,2] row_mask:0xf bank_mask:0xf
	v_cndmask_b32_e32 v20, v22, v20, vcc
	v_cndmask_b32_e32 v21, v23, v21, vcc
	v_add_f32_dpp v26, v24, v24 quad_perm:[2,3,0,1] row_mask:0xf bank_mask:0xf
	v_add_f32_dpp v27, v25, v25 quad_perm:[2,3,0,1] row_mask:0xf bank_mask:0xf
	v_cndmask_b32_e64 v24, v27, v26, s[4:5]
	v_cndmask_b32_e64 v29, v24, v28, s[6:7]
	v_cndmask_b32_e64 v30, v28, v24, s[6:7]
	s_waitcnt vmcnt(3)
; DI void attn_sample_item(const Params& p, int item, ldsp lds, int tid_) {
;     ...
;   SC_SCORE(kvA, 0)
;   SC_SCORE(kvB, 1)
	v_pk_mul_f32 v[252:253], v[236:237], v[12:13] op_sel_hi:[1,0]
	v_pk_mul_f32 v[254:255], v[244:245], v[12:13] op_sel_hi:[1,0]
	v_pk_fma_f32 v[252:253], v[238:239], v[12:13], v[252:253] op_sel:[0,1,0]
	v_pk_fma_f32 v[254:255], v[246:247], v[12:13], v[254:255] op_sel:[0,1,0]
	v_pk_fma_f32 v[252:253], v[240:241], v[14:15], v[252:253] op_sel_hi:[1,0,1]
	v_pk_fma_f32 v[254:255], v[248:249], v[14:15], v[254:255] op_sel_hi:[1,0,1]
	v_pk_fma_f32 v[252:253], v[242:243], v[14:15], v[252:253] op_sel:[0,1,0]
	v_pk_fma_f32 v[254:255], v[250:251], v[14:15], v[254:255] op_sel:[0,1,0]
	v_permlane16_swap_b32_e32 v60, v44
	v_add_f32_e32 v60, v60, v44
	v_add_f32_dpp v28, v30, v29 row_ror:4 row_mask:0xf bank_mask:0xf
	v_add_f32_dpp v16, v140, v140 quad_perm:[1,0,3,2] row_mask:0xf bank_mask:0xf
	v_add_f32_dpp v17, v141, v141 quad_perm:[1,0,3,2] row_mask:0xf bank_mask:0xf
	v_add_f32_dpp v18, v142, v142 quad_perm:[1,0,3,2] row_mask:0xf bank_mask:0xf
	v_add_f32_dpp v19, v143, v143 quad_perm:[1,0,3,2] row_mask:0xf bank_mask:0xf
	v_cndmask_b32_e32 v16, v18, v16, vcc
	v_cndmask_b32_e32 v17, v19, v17, vcc
	v_add_f32_dpp v22, v20, v20 quad_perm:[2,3,0,1] row_mask:0xf bank_mask:0xf
	v_add_f32_dpp v23, v21, v21 quad_perm:[2,3,0,1] row_mask:0xf bank_mask:0xf
	v_cndmask_b32_e64 v20, v23, v22, s[4:5]
	s_waitcnt vmcnt(2)
	v_pk_mul_f32 v[140:141], v[236:237], v[8:9] op_sel_hi:[1,0]
	v_pk_mul_f32 v[142:143], v[244:245], v[8:9] op_sel_hi:[1,0]
	v_pk_fma_f32 v[140:141], v[238:239], v[8:9], v[140:141] op_sel:[0,1,0]
	v_pk_fma_f32 v[142:143], v[246:247], v[8:9], v[142:143] op_sel:[0,1,0]
	v_pk_fma_f32 v[140:141], v[240:241], v[10:11], v[140:141] op_sel_hi:[1,0,1]
	v_pk_fma_f32 v[142:143], v[248:249], v[10:11], v[142:143] op_sel_hi:[1,0,1]
	v_pk_fma_f32 v[140:141], v[242:243], v[10:11], v[140:141] op_sel:[0,1,0]
	v_pk_fma_f32 v[142:143], v[250:251], v[10:11], v[142:143] op_sel:[0,1,0]
	v_add_f32_dpp v12, v252, v252 quad_perm:[1,0,3,2] row_mask:0xf bank_mask:0xf
	v_add_f32_dpp v13, v253, v253 quad_perm:[1,0,3,2] row_mask:0xf bank_mask:0xf
	v_add_f32_dpp v14, v254, v254 quad_perm:[1,0,3,2] row_mask:0xf bank_mask:0xf
	v_add_f32_dpp v15, v255, v255 quad_perm:[1,0,3,2] row_mask:0xf bank_mask:0xf
	v_cndmask_b32_e32 v12, v14, v12, vcc
	v_cndmask_b32_e32 v13, v15, v13, vcc
	v_add_f32_dpp v18, v16, v16 quad_perm:[2,3,0,1] row_mask:0xf bank_mask:0xf
	v_add_f32_dpp v19, v17, v17 quad_perm:[2,3,0,1] row_mask:0xf bank_mask:0xf
	v_cndmask_b32_e64 v16, v19, v18, s[4:5]
	v_cndmask_b32_e64 v21, v16, v20, s[6:7]
	v_cndmask_b32_e64 v22, v20, v16, s[6:7]
	s_waitcnt vmcnt(1)
	v_pk_mul_f32 v[252:253], v[236:237], v[4:5] op_sel_hi:[1,0]
	v_pk_mul_f32 v[254:255], v[244:245], v[4:5] op_sel_hi:[1,0]
	v_pk_fma_f32 v[252:253], v[238:239], v[4:5], v[252:253] op_sel:[0,1,0]
	v_pk_fma_f32 v[254:255], v[246:247], v[4:5], v[254:255] op_sel:[0,1,0]
	v_pk_fma_f32 v[252:253], v[240:241], v[6:7], v[252:253] op_sel_hi:[1,0,1]
	v_pk_fma_f32 v[254:255], v[248:249], v[6:7], v[254:255] op_sel_hi:[1,0,1]
	v_pk_fma_f32 v[252:253], v[242:243], v[6:7], v[252:253] op_sel:[0,1,0]
	v_pk_fma_f32 v[254:255], v[250:251], v[6:7], v[254:255] op_sel:[0,1,0]
	v_add_f32_dpp v20, v22, v21 row_ror:4 row_mask:0xf bank_mask:0xf
	v_cndmask_b32_e64 v29, v20, v28, s[64:65]
	v_cndmask_b32_e64 v30, v28, v20, s[64:65]
	v_add_f32_dpp v8, v140, v140 quad_perm:[1,0,3,2] row_mask:0xf bank_mask:0xf
	v_add_f32_dpp v9, v141, v141 quad_perm:[1,0,3,2] row_mask:0xf bank_mask:0xf
	v_add_f32_dpp v10, v142, v142 quad_perm:[1,0,3,2] row_mask:0xf bank_mask:0xf
	v_add_f32_dpp v11, v143, v143 quad_perm:[1,0,3,2] row_mask:0xf bank_mask:0xf
	v_cndmask_b32_e32 v8, v10, v8, vcc
	v_cndmask_b32_e32 v9, v11, v9, vcc
	v_add_f32_dpp v14, v12, v12 quad_perm:[2,3,0,1] row_mask:0xf bank_mask:0xf
	v_add_f32_dpp v15, v13, v13 quad_perm:[2,3,0,1] row_mask:0xf bank_mask:0xf
	v_cndmask_b32_e64 v12, v15, v14, s[4:5]
	s_waitcnt vmcnt(0)
; DI void lbar() { asm volatile("s_waitcnt lgkmcnt(0)" ::: "memory"); __builtin_amdgcn_s_barrier(); asm volatile("" ::: "memory"); }
; DI void attn_sample_item(const Params& p, int item, ldsp lds, int tid_) {
;     ...
;   SC_SCORE(kvA, 0)
;   SC_SCORE(kvB, 1)
;     ...
;   f32x4 vvA[16], vvB[16];
; #pragma unroll
;   for (int j = 0; j < 16; ++j) vvA[j] = __builtin_nontemporal_load((const f32x4*)(cv + (size_t)(wid * 32 + j) * 1024 + lane * 4));
;   lbar();
;   if (wid < 4) {
;     ...
;   for (int j = 0; j < 16; ++j) vvB[j] = __builtin_nontemporal_load((const f32x4*)(cv + (size_t)(wid * 32 + 16 + j) * 1024 + lane * 4));
	v_pk_mul_f32 v[140:141], v[236:237], v[0:1] op_sel_hi:[1,0]
	v_pk_mul_f32 v[142:143], v[244:245], v[0:1] op_sel_hi:[1,0]
	v_pk_fma_f32 v[140:141], v[238:239], v[0:1], v[140:141] op_sel:[0,1,0]
	v_pk_fma_f32 v[142:143], v[246:247], v[0:1], v[142:143] op_sel:[0,1,0]
	v_pk_fma_f32 v[140:141], v[240:241], v[2:3], v[140:141] op_sel_hi:[1,0,1]
	v_pk_fma_f32 v[142:143], v[248:249], v[2:3], v[142:143] op_sel_hi:[1,0,1]
	v_pk_fma_f32 v[140:141], v[242:243], v[2:3], v[140:141] op_sel:[0,1,0]
	v_pk_fma_f32 v[142:143], v[250:251], v[2:3], v[142:143] op_sel:[0,1,0]
	v_add_f32_dpp v28, v30, v29 row_ror:8 row_mask:0xf bank_mask:0xf
	v_add_f32_dpp v4, v252, v252 quad_perm:[1,0,3,2] row_mask:0xf bank_mask:0xf
	v_add_f32_dpp v5, v253, v253 quad_perm:[1,0,3,2] row_mask:0xf bank_mask:0xf
	v_add_f32_dpp v6, v254, v254 quad_perm:[1,0,3,2] row_mask:0xf bank_mask:0xf
	v_add_f32_dpp v7, v255, v255 quad_perm:[1,0,3,2] row_mask:0xf bank_mask:0xf
	v_cndmask_b32_e32 v4, v6, v4, vcc
	v_cndmask_b32_e32 v5, v7, v5, vcc
	v_add_f32_dpp v10, v8, v8 quad_perm:[2,3,0,1] row_mask:0xf bank_mask:0xf
	v_add_f32_dpp v11, v9, v9 quad_perm:[2,3,0,1] row_mask:0xf bank_mask:0xf
	v_cndmask_b32_e64 v8, v11, v10, s[4:5]
	v_cndmask_b32_e64 v13, v8, v12, s[6:7]
	v_cndmask_b32_e64 v14, v12, v8, s[6:7]
	s_nop 1
	v_add_f32_dpp v12, v14, v13 row_ror:4 row_mask:0xf bank_mask:0xf
	v_add_f32_dpp v0, v140, v140 quad_perm:[1,0,3,2] row_mask:0xf bank_mask:0xf
	v_add_f32_dpp v1, v141, v141 quad_perm:[1,0,3,2] row_mask:0xf bank_mask:0xf
	v_add_f32_dpp v2, v142, v142 quad_perm:[1,0,3,2] row_mask:0xf bank_mask:0xf
	v_add_f32_dpp v3, v143, v143 quad_perm:[1,0,3,2] row_mask:0xf bank_mask:0xf
	v_cndmask_b32_e32 v0, v2, v0, vcc
	v_cndmask_b32_e32 v1, v3, v1, vcc
	v_add_f32_dpp v6, v4, v4 quad_perm:[2,3,0,1] row_mask:0xf bank_mask:0xf
	v_add_f32_dpp v7, v5, v5 quad_perm:[2,3,0,1] row_mask:0xf bank_mask:0xf
	v_cndmask_b32_e64 v4, v7, v6, s[4:5]
	v_add_f32_dpp v2, v0, v0 quad_perm:[2,3,0,1] row_mask:0xf bank_mask:0xf
	v_add_f32_dpp v3, v1, v1 quad_perm:[2,3,0,1] row_mask:0xf bank_mask:0xf
	v_cndmask_b32_e64 v0, v3, v2, s[4:5]
	v_cndmask_b32_e64 v5, v0, v4, s[6:7]
	v_cndmask_b32_e64 v6, v4, v0, s[6:7]
	s_nop 1
	v_add_f32_dpp v4, v6, v5 row_ror:4 row_mask:0xf bank_mask:0xf
	v_cndmask_b32_e64 v13, v4, v12, s[64:65]
	v_cndmask_b32_e64 v14, v12, v4, s[64:65]
	s_nop 1
	v_add_f32_dpp v12, v14, v13 row_ror:8 row_mask:0xf bank_mask:0xf
	s_nop 1
	v_permlane16_swap_b32_e32 v28, v12
	v_add_f32_e32 v28, v28, v12
	s_nop 1
	v_permlane32_swap_b32_e32 v60, v28
	v_add_f32_e32 v60, v60, v28
	ds_write_b32 v235, v60 offset:64
	v_add_u32_e32 v100, v162, v144
	global_load_dwordx4 v[100:103], v100, s[66:67] nt
	v_add_u32_e32 v92, v166, v144
	global_load_dwordx4 v[92:95], v92, s[66:67] nt
	v_add_u32_e32 v112, v168, v144
	global_load_dwordx4 v[112:115], v112, s[66:67] nt
	v_add_u32_e32 v108, v172, v144
	global_load_dwordx4 v[108:111], v108, s[66:67] nt
	v_add_u32_e32 v120, v176, v144
	global_load_dwordx4 v[120:123], v120, s[66:67] nt
	v_add_u32_e32 v116, v180, v144
	global_load_dwordx4 v[116:119], v116, s[66:67] nt
	v_add_u32_e32 v124, v182, v144
	global_load_dwordx4 v[124:127], v124, s[66:67] nt
	v_add_u32_e32 v104, v186, v144
	global_load_dwordx4 v[104:107], v104, s[66:67] nt
	v_add_u32_e32 v68, v190, v144
	global_load_dwordx4 v[68:71], v68, s[66:67] nt
	v_add_u32_e32 v64, v194, v144
	global_load_dwordx4 v[64:67], v64, s[66:67] nt
	v_add_u32_e32 v80, v198, v144
	global_load_dwordx4 v[80:83], v80, s[66:67] nt
	v_add_u32_e32 v76, v200, v144
	global_load_dwordx4 v[76:79], v76, s[66:67] nt
	v_add_u32_e32 v88, v202, v144
	global_load_dwordx4 v[88:91], v88, s[66:67] nt
	v_add_u32_e32 v84, v204, v144
	global_load_dwordx4 v[84:87], v84, s[66:67] nt
	v_add_u32_e32 v96, v206, v144
	global_load_dwordx4 v[96:99], v96, s[66:67] nt
	v_add_u32_e32 v72, v208, v144
	global_load_dwordx4 v[72:75], v72, s[66:67] nt
	v_add_u32_e32 v40, v146, v144
	global_load_dwordx4 v[40:43], v40, s[66:67] nt
	v_add_u32_e32 v36, v148, v144
	global_load_dwordx4 v[36:39], v36, s[66:67] nt
	v_add_u32_e32 v48, v150, v144
	global_load_dwordx4 v[48:51], v48, s[66:67] nt
	v_add_u32_e32 v44, v152, v144
	global_load_dwordx4 v[44:47], v44, s[66:67] nt
	v_add_u32_e32 v56, v154, v144
	global_load_dwordx4 v[56:59], v56, s[66:67] nt
	v_add_u32_e32 v52, v156, v144
	global_load_dwordx4 v[52:55], v52, s[66:67] nt
	v_add_u32_e32 v60, v158, v144
	global_load_dwordx4 v[60:63], v60, s[66:67] nt
	v_add_u32_e32 v32, v160, v144
	global_load_dwordx4 v[32:35], v32, s[66:67] nt
	v_add_u32_e32 v12, v164, v144
	global_load_dwordx4 v[12:15], v12, s[66:67] nt
	v_add_u32_e32 v4, v170, v144
	global_load_dwordx4 v[4:7], v4, s[66:67] nt
	v_add_u32_e32 v20, v174, v144
	global_load_dwordx4 v[20:23], v20, s[66:67] nt
	v_add_u32_e32 v8, v178, v144
	global_load_dwordx4 v[8:11], v8, s[66:67] nt
	v_add_u32_e32 v24, v184, v144
	global_load_dwordx4 v[24:27], v24, s[66:67] nt
	v_add_u32_e32 v16, v188, v144
	global_load_dwordx4 v[16:19], v16, s[66:67] nt
	v_add_u32_e32 v28, v192, v144
	global_load_dwordx4 v[28:31], v28, s[66:67] nt
	v_add_u32_e32 v0, v196, v144
	global_load_dwordx4 v[0:3], v0, s[66:67] nt
	v_lshlrev_b32_e32 v240, 2, v223
	s_waitcnt lgkmcnt(0)
	s_barrier
	v_cmp_gt_i32_e32 vcc, 4, v210
	s_and_saveexec_b64 s[4:5], vcc
	s_cbranch_execz .LBB0_1603

; DI float wave_sum(float v) { for (int o = 32; o >= 1; o >>= 1) v += __shfl_xor(v, o); return v; }
; DI void attn_sample_item(const Params& p, int item, ldsp lds, int tid_) {
;     ...
;   if (wid < 4) {
;     float v[4]; float mx = -1e30f;
; #pragma unroll
;     for (int j = 0; j < 4; ++j) { v[j] = SC[wid * 256 + j * 64 + lane]; mx = fmaxf(mx, v[j]); }
;     for (int o = 32; o >= 1; o >>= 1) mx = fmaxf(mx, __shfl_xor(mx, o));
;     float s = 0.f;
; #pragma unroll
;     for (int j = 0; j < 4; ++j) { v[j] = __expf(v[j] - mx); s += v[j]; }
;     s = wave_sum(s); const float inv = 1.f / s;
; #pragma unroll
;     for (int j = 0; j < 4; ++j) SC[wid * 256 + j * 64 + lane] = v[j] * inv;
;   }
	v_lshlrev_b32_e32 v241, 10, v210
	v_add3_u32 v244, 16, v241, v240
	ds_read2st64_b32 v[240:241], v244 offset1:1
	ds_read2st64_b32 v[242:243], v244 offset0:2 offset1:3
	s_waitcnt lgkmcnt(1)
	v_max3_f32 v245, v240, s39, v241
	s_waitcnt lgkmcnt(0)
	v_max3_f32 v245, v245, v242, v243
	s_nop 1
	v_max_f32_dpp v245, v245, v245 quad_perm:[1,0,3,2] row_mask:0xf bank_mask:0xf
	s_nop 1
	v_max_f32_dpp v245, v245, v245 quad_perm:[2,3,0,1] row_mask:0xf bank_mask:0xf
	s_nop 1
	v_max_f32_dpp v245, v245, v245 row_ror:4 row_mask:0xf bank_mask:0xf
	s_nop 1
	v_max_f32_dpp v245, v245, v245 row_ror:8 row_mask:0xf bank_mask:0xf
	v_mov_b32_e32 v246, v245
	s_nop 1
	v_permlane16_swap_b32_e32 v245, v246
	v_max_f32_e32 v245, v245, v246
	v_mov_b32_e32 v246, v245
	s_nop 1
	v_permlane32_swap_b32_e32 v245, v246
	v_max_f32_e32 v245, v245, v246
	v_sub_f32_e32 v240, v240, v245
	v_sub_f32_e32 v241, v241, v245
	v_mul_f32_e32 v240, 0x3fb8aa3b, v240
	v_sub_f32_e32 v242, v242, v245
	v_mul_f32_e32 v241, 0x3fb8aa3b, v241
	v_exp_f32_e32 v240, v240
	v_sub_f32_e32 v243, v243, v245
	v_mul_f32_e32 v242, 0x3fb8aa3b, v242
	v_exp_f32_e32 v241, v241
	v_mul_f32_e32 v243, 0x3fb8aa3b, v243
	v_exp_f32_e32 v242, v242
	v_exp_f32_e32 v243, v243
	v_add_f32_e32 v245, 0, v240
	v_add_f32_e32 v245, v241, v245
	v_add_f32_e32 v245, v242, v245
	v_add_f32_e32 v245, v243, v245
	s_nop 1
	v_add_f32_dpp v245, v245, v245 quad_perm:[1,0,3,2] row_mask:0xf bank_mask:0xf
	s_nop 1
	v_add_f32_dpp v245, v245, v245 quad_perm:[2,3,0,1] row_mask:0xf bank_mask:0xf
	s_nop 1
	v_add_f32_dpp v245, v245, v245 row_ror:4 row_mask:0xf bank_mask:0xf
	s_nop 1
	v_add_f32_dpp v245, v245, v245 row_ror:8 row_mask:0xf bank_mask:0xf
	v_mov_b32_e32 v246, v245
	s_nop 1
	v_permlane16_swap_b32_e32 v245, v246
	v_add_f32_e32 v245, v245, v246
	v_mov_b32_e32 v246, v245
	s_nop 1
	v_permlane32_swap_b32_e32 v245, v246
	v_add_f32_e32 v245, v245, v246
	v_div_scale_f32 v246, s[6:7], v245, v245, 1.0
	v_rcp_f32_e32 v247, v246
	v_div_scale_f32 v248, vcc, 1.0, v245, 1.0
	v_fma_f32 v249, -v246, v247, 1.0
	v_fmac_f32_e32 v247, v249, v247
	v_mul_f32_e32 v249, v248, v247
	v_fma_f32 v250, -v246, v249, v248
	v_fmac_f32_e32 v249, v250, v247
	v_fma_f32 v246, -v246, v249, v248
	v_div_fmas_f32 v246, v246, v247, v249
	v_div_fixup_f32 v245, v246, v245, 1.0
	v_mul_f32_e32 v240, v240, v245
	v_mul_f32_e32 v241, v241, v245
	v_mul_f32_e32 v242, v242, v245
	v_mul_f32_e32 v243, v243, v245
	ds_write2st64_b32 v244, v240, v241 offset1:1
	ds_write2st64_b32 v244, v242, v243 offset0:2 offset1:3
	s_branch .LBB0_1603

; DI void attn_sample_item(const Params& p, int item, ldsp lds, int tid_) {
;     ...
;   for (int t = 0; t < 4; ++t) { f32x4 a = {0.f, 0.f, 0.f, 0.f}; const float* pp = (const float*)(p.ws + B_PART) + (size_t)(b * 4 + t) * 1024 + h * 256 + lane * 4;
; #pragma unroll
;     for (int kp = 0; kp < 4; ++kp) a += *(const f32x4*)(pp + (size_t)kp * 512 * 1024);
;     q[t][0] = a[0] * 0.0625f; q[t][1] = a[1] * 0.0625f; q[t][2] = a[2] * 0.0625f; q[t][3] = a[3] * 0.0625f; }
;   const bool b0 = lane & 1, b1 = lane & 2;
;   f32x4 kvA[16], kvB[16];
; #pragma unroll
;   for (int j = 0; j < 16; ++j) kvA[j] = __builtin_nontemporal_load((const f32x4*)(ck + (size_t)(wid * 32 + j) * 1024 + lane * 4));
; #pragma unroll
;   for (int j = 0; j < 16; ++j) kvB[j] = __builtin_nontemporal_load((const f32x4*)(ck + (size_t)(wid * 32 + 16 + j) * 1024 + lane * 4));
.LBB0_1676:
	s_ashr_i32 s4, s38, 2
	s_ashr_i32 s5, s4, 31
	s_lshl_b64 s[4:5], s[4:5], 18
	s_and_b32 s24, s0, 0x300
	v_mov_b32_e32 v222, v212
	s_or_b32 s4, s4, s24
	s_and_b32 s26, s38, -4
	s_lshl_b32 s6, s24, 2
	s_add_u32 s6, s36, s6
	v_and_b32_e32 v223, 63, v222
	s_addc_u32 s7, s37, 0
	v_lshlrev_b32_e32 v144, 4, v223
	s_ashr_i32 s27, s26, 31
	v_lshl_add_u64 v[48:49], s[6:7], 0, v[144:145]
	s_lshl_b64 s[6:7], s[26:27], 12
	v_lshl_add_u64 v[8:9], v[48:49], 0, s[6:7]
	v_add_co_u32_e32 v10, vcc, s3, v8
	s_or_b32 s6, s26, 1
	s_nop 0
	v_addc_co_u32_e32 v11, vcc, 0, v9, vcc
	global_load_dwordx4 v[0:3], v[8:9], off
	global_load_dwordx4 v[4:7], v[10:11], off
	v_add_co_u32_e32 v10, vcc, s33, v8
	s_ashr_i32 s7, s6, 31
	s_nop 0
	v_addc_co_u32_e32 v11, vcc, 0, v9, vcc
	v_add_co_u32_e32 v12, vcc, s34, v8
	s_lshl_b64 s[6:7], s[6:7], 12
	s_nop 0
	v_addc_co_u32_e32 v13, vcc, 0, v9, vcc
	v_lshl_add_u64 v[24:25], v[48:49], 0, s[6:7]
	v_add_co_u32_e32 v20, vcc, s3, v24
	s_or_b32 s6, s26, 2
	s_nop 0
	v_addc_co_u32_e32 v21, vcc, 0, v25, vcc
	v_add_co_u32_e32 v26, vcc, s33, v24
	s_ashr_i32 s7, s6, 31
	s_nop 0
	v_addc_co_u32_e32 v27, vcc, 0, v25, vcc
	v_add_co_u32_e32 v28, vcc, s34, v24
	s_lshl_b64 s[6:7], s[6:7], 12
	s_nop 0
	v_addc_co_u32_e32 v29, vcc, 0, v25, vcc
	v_lshl_add_u64 v[44:45], v[48:49], 0, s[6:7]
	global_load_dwordx4 v[8:11], v[10:11], off
	s_nop 0
	global_load_dwordx4 v[12:15], v[12:13], off
	s_nop 0
	global_load_dwordx4 v[16:19], v[24:25], off
	s_nop 0
	global_load_dwordx4 v[20:23], v[20:21], off
	v_add_co_u32_e32 v36, vcc, s3, v44
	global_load_dwordx4 v[24:27], v[26:27], off
	s_nop 0
	global_load_dwordx4 v[28:31], v[28:29], off
	v_addc_co_u32_e32 v37, vcc, 0, v45, vcc
	v_add_co_u32_e32 v40, vcc, s33, v44
	global_load_dwordx4 v[32:35], v[44:45], off
	s_nop 0
	global_load_dwordx4 v[36:39], v[36:37], off
	v_addc_co_u32_e32 v41, vcc, 0, v45, vcc
	v_add_co_u32_e32 v44, vcc, s34, v44
	global_load_dwordx4 v[40:43], v[40:41], off
	s_nop 0
	v_addc_co_u32_e32 v45, vcc, 0, v45, vcc
	global_load_dwordx4 v[44:47], v[44:45], off
	s_or_b32 s6, s38, 3
	s_ashr_i32 s7, s6, 31
	s_lshl_b64 s[6:7], s[6:7], 12
	s_lshl_b64 s[28:29], s[4:5], 2
	s_add_u32 s4, s12, s28
	s_addc_u32 s5, s13, s29
	s_waitcnt vmcnt(11)
	v_pk_add_f32 v[2:3], v[2:3], 0 op_sel_hi:[1,0]
	v_pk_add_f32 v[0:1], v[0:1], 0 op_sel_hi:[1,0]
	s_waitcnt vmcnt(10)
	v_pk_add_f32 v[2:3], v[2:3], v[6:7]
	v_pk_add_f32 v[0:1], v[0:1], v[4:5]
	s_waitcnt vmcnt(9)
	v_pk_add_f32 v[2:3], v[2:3], v[10:11]
	s_waitcnt vmcnt(7)
	v_pk_add_f32 v[4:5], v[18:19], 0 op_sel_hi:[1,0]
	v_pk_add_f32 v[6:7], v[16:17], 0 op_sel_hi:[1,0]
	v_pk_add_f32 v[0:1], v[0:1], v[8:9]
	s_waitcnt vmcnt(6)
	v_pk_add_f32 v[4:5], v[4:5], v[22:23]
	v_pk_add_f32 v[6:7], v[6:7], v[20:21]
	v_pk_add_f32 v[2:3], v[2:3], v[14:15]
	v_pk_add_f32 v[0:1], v[0:1], v[12:13]
	s_waitcnt vmcnt(5)
	v_pk_add_f32 v[4:5], v[4:5], v[26:27]
	v_pk_add_f32 v[6:7], v[6:7], v[24:25]
	v_mul_f32_e32 v228, 0x3d800000, v0
	v_mul_f32_e32 v231, 0x3d800000, v1
	v_mul_f32_e32 v229, 0x3d800000, v2
	v_mul_f32_e32 v225, 0x3d800000, v3
	s_waitcnt vmcnt(4)
	v_pk_add_f32 v[0:1], v[4:5], v[30:31]
	v_pk_add_f32 v[2:3], v[6:7], v[28:29]
	v_mul_f32_e32 v227, 0x3d800000, v0
	v_mul_f32_e32 v226, 0x3d800000, v2
	v_mul_f32_e32 v230, 0x3d800000, v3
	v_mul_f32_e32 v224, 0x3d800000, v1
	s_waitcnt vmcnt(3)
	v_pk_add_f32 v[0:1], v[34:35], 0 op_sel_hi:[1,0]
	v_pk_add_f32 v[2:3], v[32:33], 0 op_sel_hi:[1,0]
	s_waitcnt vmcnt(2)
	v_pk_add_f32 v[0:1], v[0:1], v[38:39]
	v_pk_add_f32 v[2:3], v[2:3], v[36:37]
	s_waitcnt vmcnt(1)
	v_pk_add_f32 v[0:1], v[0:1], v[42:43]
	v_pk_add_f32 v[2:3], v[2:3], v[40:41]
	s_waitcnt vmcnt(0)
	v_pk_add_f32 v[210:211], v[0:1], v[46:47]
	v_pk_add_f32 v[0:1], v[2:3], v[44:45]
	v_mul_f32_e32 v233, 0x3d800000, v210
	v_mul_f32_e32 v232, 0x3d800000, v0
	v_mul_f32_e32 v234, 0x3d800000, v1
	v_lshl_add_u64 v[0:1], v[48:49], 0, s[6:7]
	v_add_co_u32_e32 v2, vcc, s3, v0
	v_ashrrev_i32_e32 v210, 6, v222
	s_nop 0
	v_addc_co_u32_e32 v3, vcc, 0, v1, vcc
	global_load_dwordx4 v[128:131], v[0:1], off
	global_load_dwordx4 v[132:135], v[2:3], off
	v_add_co_u32_e32 v2, vcc, s33, v0
	v_mul_f32_e32 v211, 0x3d800000, v211
	s_nop 0
	v_addc_co_u32_e32 v3, vcc, 0, v1, vcc
	v_add_co_u32_e32 v0, vcc, s34, v0
	v_cmp_lt_i32_e64 s[6:7], v218, v216
	s_nop 0
	v_addc_co_u32_e32 v1, vcc, 0, v1, vcc
	global_load_dwordx4 v[136:139], v[2:3], off
	global_load_dwordx4 v[140:143], v[0:1], off
	v_lshlrev_b32_e32 v0, 5, v210
	v_ashrrev_i32_e32 v1, 31, v0
	v_or_b32_e32 v6, 1, v0
	v_lshl_add_u64 v[2:3], s[4:5], 0, v[144:145]
	v_lshlrev_b64 v[158:159], 12, v[0:1]
	v_ashrrev_i32_e32 v7, 31, v6
	v_lshl_add_u64 v[4:5], v[2:3], 0, v[158:159]
	v_lshlrev_b64 v[162:163], 12, v[6:7]
	v_lshl_add_u64 v[6:7], v[2:3], 0, v[162:163]
	global_load_dwordx4 v[124:127], v[4:5], off nt
	global_load_dwordx4 v[120:123], v[6:7], off nt
	v_or_b32_e32 v4, 2, v0
	v_ashrrev_i32_e32 v5, 31, v4
	v_or_b32_e32 v6, 3, v0
	v_lshlrev_b64 v[164:165], 12, v[4:5]
	v_ashrrev_i32_e32 v7, 31, v6
	v_lshl_add_u64 v[4:5], v[2:3], 0, v[164:165]
	v_lshlrev_b64 v[168:169], 12, v[6:7]
	v_lshl_add_u64 v[6:7], v[2:3], 0, v[168:169]
	global_load_dwordx4 v[116:119], v[4:5], off nt
	global_load_dwordx4 v[112:115], v[6:7], off nt
	v_or_b32_e32 v4, 4, v0
	v_ashrrev_i32_e32 v5, 31, v4
	v_or_b32_e32 v6, 5, v0
	v_lshlrev_b64 v[172:173], 12, v[4:5]
	v_ashrrev_i32_e32 v7, 31, v6
	v_lshl_add_u64 v[4:5], v[2:3], 0, v[172:173]
	v_lshlrev_b64 v[176:177], 12, v[6:7]
	v_lshl_add_u64 v[6:7], v[2:3], 0, v[176:177]
	global_load_dwordx4 v[108:111], v[4:5], off nt
	global_load_dwordx4 v[104:107], v[6:7], off nt
	v_or_b32_e32 v4, 6, v0
	v_ashrrev_i32_e32 v5, 31, v4
	v_or_b32_e32 v6, 7, v0
; DI void attn_sample_item(const Params& p, int item, ldsp lds, int tid_) {
;     ...
;   for (int t = 0; t < 4; ++t) { f32x4 a = {0.f, 0.f, 0.f, 0.f}; const float* pp = (const float*)(p.ws + B_PART) + (size_t)(b * 4 + t) * 1024 + h * 256 + lane * 4;
; #pragma unroll
;     for (int kp = 0; kp < 4; ++kp) a += *(const f32x4*)(pp + (size_t)kp * 512 * 1024);
;     q[t][0] = a[0] * 0.0625f; q[t][1] = a[1] * 0.0625f; q[t][2] = a[2] * 0.0625f; q[t][3] = a[3] * 0.0625f; }
;     ...
;   for (int j = 0; j < 16; ++j) kvA[j] = __builtin_nontemporal_load((const f32x4*)(ck + (size_t)(wid * 32 + j) * 1024 + lane * 4));
; #pragma unroll
;   for (int j = 0; j < 16; ++j) kvB[j] = __builtin_nontemporal_load((const f32x4*)(ck + (size_t)(wid * 32 + 16 + j) * 1024 + lane * 4));
	v_lshlrev_b64 v[180:181], 12, v[4:5]
	v_ashrrev_i32_e32 v7, 31, v6
	v_lshl_add_u64 v[4:5], v[2:3], 0, v[180:181]
	v_lshlrev_b64 v[184:185], 12, v[6:7]
	v_lshl_add_u64 v[6:7], v[2:3], 0, v[184:185]
	global_load_dwordx4 v[100:103], v[4:5], off nt
	global_load_dwordx4 v[96:99], v[6:7], off nt
	v_or_b32_e32 v4, 8, v0
	v_ashrrev_i32_e32 v5, 31, v4
	v_or_b32_e32 v6, 9, v0
	v_lshlrev_b64 v[188:189], 12, v[4:5]
	v_ashrrev_i32_e32 v7, 31, v6
	v_lshl_add_u64 v[4:5], v[2:3], 0, v[188:189]
	v_lshlrev_b64 v[192:193], 12, v[6:7]
	v_lshl_add_u64 v[6:7], v[2:3], 0, v[192:193]
	global_load_dwordx4 v[92:95], v[4:5], off nt
	global_load_dwordx4 v[88:91], v[6:7], off nt
	v_or_b32_e32 v4, 10, v0
	v_ashrrev_i32_e32 v5, 31, v4
	v_or_b32_e32 v6, 11, v0
	v_lshlrev_b64 v[196:197], 12, v[4:5]
	v_ashrrev_i32_e32 v7, 31, v6
	v_lshl_add_u64 v[4:5], v[2:3], 0, v[196:197]
	v_lshlrev_b64 v[200:201], 12, v[6:7]
	v_lshl_add_u64 v[6:7], v[2:3], 0, v[200:201]
	global_load_dwordx4 v[84:87], v[4:5], off nt
	global_load_dwordx4 v[80:83], v[6:7], off nt
	v_or_b32_e32 v4, 12, v0
	v_ashrrev_i32_e32 v5, 31, v4
	v_or_b32_e32 v6, 13, v0
	v_lshlrev_b64 v[202:203], 12, v[4:5]
	v_ashrrev_i32_e32 v7, 31, v6
	v_lshl_add_u64 v[4:5], v[2:3], 0, v[202:203]
	v_lshlrev_b64 v[204:205], 12, v[6:7]
	v_lshl_add_u64 v[6:7], v[2:3], 0, v[204:205]
	global_load_dwordx4 v[76:79], v[4:5], off nt
	global_load_dwordx4 v[72:75], v[6:7], off nt
	v_or_b32_e32 v4, 14, v0
	v_ashrrev_i32_e32 v5, 31, v4
	v_or_b32_e32 v6, 15, v0
	v_lshlrev_b64 v[206:207], 12, v[4:5]
	v_ashrrev_i32_e32 v7, 31, v6
	v_lshl_add_u64 v[4:5], v[2:3], 0, v[206:207]
	v_lshlrev_b64 v[208:209], 12, v[6:7]
	v_lshl_add_u64 v[6:7], v[2:3], 0, v[208:209]
	global_load_dwordx4 v[68:71], v[4:5], off nt
	global_load_dwordx4 v[64:67], v[6:7], off nt
	v_or_b32_e32 v4, 16, v0
	v_ashrrev_i32_e32 v5, 31, v4
	v_or_b32_e32 v6, 17, v0
	v_lshlrev_b64 v[146:147], 12, v[4:5]
	v_ashrrev_i32_e32 v7, 31, v6
	v_lshl_add_u64 v[4:5], v[2:3], 0, v[146:147]
	v_lshlrev_b64 v[148:149], 12, v[6:7]
	v_lshl_add_u64 v[6:7], v[2:3], 0, v[148:149]
	global_load_dwordx4 v[60:63], v[4:5], off nt
	global_load_dwordx4 v[56:59], v[6:7], off nt
	v_or_b32_e32 v4, 18, v0
	v_ashrrev_i32_e32 v5, 31, v4
	v_or_b32_e32 v6, 19, v0
	v_lshlrev_b64 v[150:151], 12, v[4:5]
	v_ashrrev_i32_e32 v7, 31, v6
	v_lshl_add_u64 v[4:5], v[2:3], 0, v[150:151]
	v_lshlrev_b64 v[152:153], 12, v[6:7]
	v_lshl_add_u64 v[6:7], v[2:3], 0, v[152:153]
	global_load_dwordx4 v[52:55], v[4:5], off nt
	global_load_dwordx4 v[48:51], v[6:7], off nt
	v_or_b32_e32 v4, 20, v0
	v_ashrrev_i32_e32 v5, 31, v4
	v_or_b32_e32 v6, 21, v0
	v_lshlrev_b64 v[154:155], 12, v[4:5]
	v_ashrrev_i32_e32 v7, 31, v6
	v_lshl_add_u64 v[4:5], v[2:3], 0, v[154:155]
	v_lshlrev_b64 v[156:157], 12, v[6:7]
	v_lshl_add_u64 v[6:7], v[2:3], 0, v[156:157]
	global_load_dwordx4 v[44:47], v[4:5], off nt
	global_load_dwordx4 v[40:43], v[6:7], off nt
	v_or_b32_e32 v4, 22, v0
	v_ashrrev_i32_e32 v5, 31, v4
	v_or_b32_e32 v6, 23, v0
	v_lshlrev_b64 v[160:161], 12, v[4:5]
	v_ashrrev_i32_e32 v7, 31, v6
	v_lshl_add_u64 v[4:5], v[2:3], 0, v[160:161]
	v_lshlrev_b64 v[166:167], 12, v[6:7]
	v_lshl_add_u64 v[6:7], v[2:3], 0, v[166:167]
	global_load_dwordx4 v[36:39], v[4:5], off nt
	global_load_dwordx4 v[32:35], v[6:7], off nt
	v_or_b32_e32 v4, 24, v0
	v_ashrrev_i32_e32 v5, 31, v4
	v_or_b32_e32 v6, 25, v0
	v_lshlrev_b64 v[170:171], 12, v[4:5]
	v_ashrrev_i32_e32 v7, 31, v6
	v_lshl_add_u64 v[4:5], v[2:3], 0, v[170:171]
	v_lshlrev_b64 v[174:175], 12, v[6:7]
	v_lshl_add_u64 v[6:7], v[2:3], 0, v[174:175]
	global_load_dwordx4 v[28:31], v[4:5], off nt
	global_load_dwordx4 v[24:27], v[6:7], off nt
	v_or_b32_e32 v4, 26, v0
	v_ashrrev_i32_e32 v5, 31, v4
	v_or_b32_e32 v6, 27, v0
	v_lshlrev_b64 v[178:179], 12, v[4:5]
	v_ashrrev_i32_e32 v7, 31, v6
	v_lshl_add_u64 v[4:5], v[2:3], 0, v[178:179]
	v_lshlrev_b64 v[182:183], 12, v[6:7]
	v_lshl_add_u64 v[6:7], v[2:3], 0, v[182:183]
	global_load_dwordx4 v[20:23], v[4:5], off nt
	global_load_dwordx4 v[16:19], v[6:7], off nt
	v_or_b32_e32 v4, 28, v0
	v_ashrrev_i32_e32 v5, 31, v4
	v_or_b32_e32 v6, 29, v0
	v_lshlrev_b64 v[186:187], 12, v[4:5]
	v_ashrrev_i32_e32 v7, 31, v6
	v_lshl_add_u64 v[4:5], v[2:3], 0, v[186:187]
	v_lshlrev_b64 v[190:191], 12, v[6:7]
	v_lshl_add_u64 v[6:7], v[2:3], 0, v[190:191]
	global_load_dwordx4 v[12:15], v[4:5], off nt
	global_load_dwordx4 v[8:11], v[6:7], off nt
	v_or_b32_e32 v4, 30, v0
	v_or_b32_e32 v0, 31, v0
	v_ashrrev_i32_e32 v5, 31, v4
	v_ashrrev_i32_e32 v1, 31, v0
	v_lshlrev_b64 v[194:195], 12, v[4:5]
	v_lshlrev_b64 v[198:199], 12, v[0:1]
	v_lshl_add_u64 v[4:5], v[2:3], 0, v[194:195]
	v_lshl_add_u64 v[0:1], v[2:3], 0, v[198:199]
	global_load_dwordx4 v[4:7], v[4:5], off nt
	s_nop 0
	global_load_dwordx4 v[0:3], v[0:1], off nt
	s_waitcnt vmcnt(35)
	v_pk_add_f32 v[128:129], v[128:129], 0 op_sel_hi:[1,0]
	v_pk_add_f32 v[130:131], v[130:131], 0 op_sel_hi:[1,0]
	s_waitcnt vmcnt(34)
	v_pk_add_f32 v[128:129], v[128:129], v[132:133]
	v_pk_add_f32 v[130:131], v[130:131], v[134:135]
	s_waitcnt vmcnt(33)
	v_pk_add_f32 v[128:129], v[128:129], v[136:137]
	v_pk_add_f32 v[130:131], v[130:131], v[138:139]
	s_waitcnt vmcnt(32)
; DI void attn_sample_item(const Params& p, int item, ldsp lds, int tid_) {
;     ...
;     q[t][0] = a[0] * 0.0625f; q[t][1] = a[1] * 0.0625f; q[t][2] = a[2] * 0.0625f; q[t][3] = a[3] * 0.0625f; }
;     ...
;   SC_SCORE(kvA, 0)
;   SC_SCORE(kvB, 1)
	v_pk_add_f32 v[128:129], v[128:129], v[140:141]
	v_pk_add_f32 v[130:131], v[130:131], v[142:143]
	v_mul_f32_e32 v138, 0x3d800000, v129
	v_mul_f32_e32 v135, 0x3d800000, v128
	v_mul_f32_e32 v134, 0x3d800000, v131
	s_add_u32 s66, s14, s28
	s_addc_u32 s67, s15, s29
	v_mul_f32_e32 v137, 0x3d800000, v130
	v_lshlrev_b32_e32 v128, 2, v215
	v_lshlrev_b32_e32 v129, 2, v217
	v_lshlrev_b32_e32 v130, 2, v218
	v_lshlrev_b32_e32 v131, 2, v219
	v_lshlrev_b32_e32 v132, 2, v220
	v_lshlrev_b32_e32 v133, 2, v221
	v_lshl_add_u32 v136, v210, 7, 16
	v_and_b32_e32 v139, 3, v223
	v_bfrev_b32_e32 v139, v139
	v_lshrrev_b32_e32 v139, 20, v139
	v_and_b32_e32 v235, -4, v223
	v_add3_u32 v235, v136, v139, v235
	v_mov_b32_e32 v236, v228
	v_mov_b32_e32 v237, v226
	v_mov_b32_e32 v238, v231
	v_mov_b32_e32 v239, v230
	v_mov_b32_e32 v240, v229
	v_mov_b32_e32 v241, v227
	v_mov_b32_e32 v242, v225
	v_mov_b32_e32 v243, v224
	v_mov_b32_e32 v244, v232
	v_mov_b32_e32 v245, v135
	v_mov_b32_e32 v246, v234
	v_mov_b32_e32 v247, v138
	v_mov_b32_e32 v248, v233
	v_mov_b32_e32 v249, v137
	v_mov_b32_e32 v250, v211
	v_mov_b32_e32 v251, v134
	s_mov_b32 vcc_lo, 0x55555555
	s_mov_b32 vcc_hi, 0x55555555
	s_mov_b32 s4, 0x33333333
	s_mov_b32 s5, 0x33333333
	s_mov_b32 s6, 0x0f0f0f0f
	s_mov_b32 s7, 0x0f0f0f0f
	s_mov_b32 s64, 0x00ff00ff
	s_mov_b32 s65, 0x00ff00ff
	s_waitcnt vmcnt(31)
	v_pk_mul_f32 v[252:253], v[236:237], v[124:125] op_sel_hi:[1,0]
	v_pk_mul_f32 v[254:255], v[244:245], v[124:125] op_sel_hi:[1,0]
	v_pk_fma_f32 v[252:253], v[238:239], v[124:125], v[252:253] op_sel:[0,1,0]
	v_pk_fma_f32 v[254:255], v[246:247], v[124:125], v[254:255] op_sel:[0,1,0]
	v_pk_fma_f32 v[252:253], v[240:241], v[126:127], v[252:253] op_sel_hi:[1,0,1]
	v_pk_fma_f32 v[254:255], v[248:249], v[126:127], v[254:255] op_sel_hi:[1,0,1]
	v_pk_fma_f32 v[252:253], v[242:243], v[126:127], v[252:253] op_sel:[0,1,0]
	v_pk_fma_f32 v[254:255], v[250:251], v[126:127], v[254:255] op_sel:[0,1,0]
	s_waitcnt vmcnt(30)
	v_pk_mul_f32 v[140:141], v[236:237], v[120:121] op_sel_hi:[1,0]
	v_pk_mul_f32 v[142:143], v[244:245], v[120:121] op_sel_hi:[1,0]
	v_pk_fma_f32 v[140:141], v[238:239], v[120:121], v[140:141] op_sel:[0,1,0]
	v_pk_fma_f32 v[142:143], v[246:247], v[120:121], v[142:143] op_sel:[0,1,0]
	v_pk_fma_f32 v[140:141], v[240:241], v[122:123], v[140:141] op_sel_hi:[1,0,1]
	v_pk_fma_f32 v[142:143], v[248:249], v[122:123], v[142:143] op_sel_hi:[1,0,1]
	v_pk_fma_f32 v[140:141], v[242:243], v[122:123], v[140:141] op_sel:[0,1,0]
	v_pk_fma_f32 v[142:143], v[250:251], v[122:123], v[142:143] op_sel:[0,1,0]
	v_add_f32_dpp v124, v252, v252 quad_perm:[1,0,3,2] row_mask:0xf bank_mask:0xf
	v_add_f32_dpp v125, v253, v253 quad_perm:[1,0,3,2] row_mask:0xf bank_mask:0xf
	v_add_f32_dpp v126, v254, v254 quad_perm:[1,0,3,2] row_mask:0xf bank_mask:0xf
	v_add_f32_dpp v127, v255, v255 quad_perm:[1,0,3,2] row_mask:0xf bank_mask:0xf
	v_cndmask_b32_e32 v124, v126, v124, vcc
	v_cndmask_b32_e32 v125, v127, v125, vcc
	s_waitcnt vmcnt(29)
	v_pk_mul_f32 v[252:253], v[236:237], v[116:117] op_sel_hi:[1,0]
	v_pk_mul_f32 v[254:255], v[244:245], v[116:117] op_sel_hi:[1,0]
	v_pk_fma_f32 v[252:253], v[238:239], v[116:117], v[252:253] op_sel:[0,1,0]
	v_pk_fma_f32 v[254:255], v[246:247], v[116:117], v[254:255] op_sel:[0,1,0]
	v_pk_fma_f32 v[252:253], v[240:241], v[118:119], v[252:253] op_sel_hi:[1,0,1]
	v_pk_fma_f32 v[254:255], v[248:249], v[118:119], v[254:255] op_sel_hi:[1,0,1]
	v_pk_fma_f32 v[252:253], v[242:243], v[118:119], v[252:253] op_sel:[0,1,0]
	v_pk_fma_f32 v[254:255], v[250:251], v[118:119], v[254:255] op_sel:[0,1,0]
	v_add_f32_dpp v120, v140, v140 quad_perm:[1,0,3,2] row_mask:0xf bank_mask:0xf
	v_add_f32_dpp v121, v141, v141 quad_perm:[1,0,3,2] row_mask:0xf bank_mask:0xf
	v_add_f32_dpp v122, v142, v142 quad_perm:[1,0,3,2] row_mask:0xf bank_mask:0xf
	v_add_f32_dpp v123, v143, v143 quad_perm:[1,0,3,2] row_mask:0xf bank_mask:0xf
	v_cndmask_b32_e32 v120, v122, v120, vcc
	v_cndmask_b32_e32 v121, v123, v121, vcc
	v_add_f32_dpp v126, v124, v124 quad_perm:[2,3,0,1] row_mask:0xf bank_mask:0xf
	v_add_f32_dpp v127, v125, v125 quad_perm:[2,3,0,1] row_mask:0xf bank_mask:0xf
	v_cndmask_b32_e64 v124, v127, v126, s[4:5]
	s_waitcnt vmcnt(28)
	v_pk_mul_f32 v[140:141], v[236:237], v[112:113] op_sel_hi:[1,0]
	v_pk_mul_f32 v[142:143], v[244:245], v[112:113] op_sel_hi:[1,0]
	v_pk_fma_f32 v[140:141], v[238:239], v[112:113], v[140:141] op_sel:[0,1,0]
	v_pk_fma_f32 v[142:143], v[246:247], v[112:113], v[142:143] op_sel:[0,1,0]
	v_pk_fma_f32 v[140:141], v[240:241], v[114:115], v[140:141] op_sel_hi:[1,0,1]
	v_pk_fma_f32 v[142:143], v[248:249], v[114:115], v[142:143] op_sel_hi:[1,0,1]
	v_pk_fma_f32 v[140:141], v[242:243], v[114:115], v[140:141] op_sel:[0,1,0]
	v_pk_fma_f32 v[142:143], v[250:251], v[114:115], v[142:143] op_sel:[0,1,0]
	v_add_f32_dpp v116, v252, v252 quad_perm:[1,0,3,2] row_mask:0xf bank_mask:0xf
	v_add_f32_dpp v117, v253, v253 quad_perm:[1,0,3,2] row_mask:0xf bank_mask:0xf
	v_add_f32_dpp v118, v254, v254 quad_perm:[1,0,3,2] row_mask:0xf bank_mask:0xf
	v_add_f32_dpp v119, v255, v255 quad_perm:[1,0,3,2] row_mask:0xf bank_mask:0xf
	v_cndmask_b32_e32 v116, v118, v116, vcc
	v_cndmask_b32_e32 v117, v119, v117, vcc
	v_add_f32_dpp v122, v120, v120 quad_perm:[2,3,0,1] row_mask:0xf bank_mask:0xf
	v_add_f32_dpp v123, v121, v121 quad_perm:[2,3,0,1] row_mask:0xf bank_mask:0xf
	v_cndmask_b32_e64 v120, v123, v122, s[4:5]
	v_cndmask_b32_e64 v125, v120, v124, s[6:7]
	v_cndmask_b32_e64 v126, v124, v120, s[6:7]
	s_waitcnt vmcnt(27)
; DI void attn_sample_item(const Params& p, int item, ldsp lds, int tid_) {
;     ...
;   SC_SCORE(kvA, 0)
;   SC_SCORE(kvB, 1)
	v_pk_mul_f32 v[252:253], v[236:237], v[108:109] op_sel_hi:[1,0]
	v_pk_mul_f32 v[254:255], v[244:245], v[108:109] op_sel_hi:[1,0]
	v_pk_fma_f32 v[252:253], v[238:239], v[108:109], v[252:253] op_sel:[0,1,0]
	v_pk_fma_f32 v[254:255], v[246:247], v[108:109], v[254:255] op_sel:[0,1,0]
	v_pk_fma_f32 v[252:253], v[240:241], v[110:111], v[252:253] op_sel_hi:[1,0,1]
	v_pk_fma_f32 v[254:255], v[248:249], v[110:111], v[254:255] op_sel_hi:[1,0,1]
	v_pk_fma_f32 v[252:253], v[242:243], v[110:111], v[252:253] op_sel:[0,1,0]
	v_pk_fma_f32 v[254:255], v[250:251], v[110:111], v[254:255] op_sel:[0,1,0]
	v_add_f32_dpp v124, v126, v125 row_ror:4 row_mask:0xf bank_mask:0xf
	v_add_f32_dpp v112, v140, v140 quad_perm:[1,0,3,2] row_mask:0xf bank_mask:0xf
	v_add_f32_dpp v113, v141, v141 quad_perm:[1,0,3,2] row_mask:0xf bank_mask:0xf
	v_add_f32_dpp v114, v142, v142 quad_perm:[1,0,3,2] row_mask:0xf bank_mask:0xf
	v_add_f32_dpp v115, v143, v143 quad_perm:[1,0,3,2] row_mask:0xf bank_mask:0xf
	v_cndmask_b32_e32 v112, v114, v112, vcc
	v_cndmask_b32_e32 v113, v115, v113, vcc
	v_add_f32_dpp v118, v116, v116 quad_perm:[2,3,0,1] row_mask:0xf bank_mask:0xf
	v_add_f32_dpp v119, v117, v117 quad_perm:[2,3,0,1] row_mask:0xf bank_mask:0xf
	v_cndmask_b32_e64 v116, v119, v118, s[4:5]
	s_waitcnt vmcnt(26)
	v_pk_mul_f32 v[140:141], v[236:237], v[104:105] op_sel_hi:[1,0]
	v_pk_mul_f32 v[142:143], v[244:245], v[104:105] op_sel_hi:[1,0]
	v_pk_fma_f32 v[140:141], v[238:239], v[104:105], v[140:141] op_sel:[0,1,0]
	v_pk_fma_f32 v[142:143], v[246:247], v[104:105], v[142:143] op_sel:[0,1,0]
	v_pk_fma_f32 v[140:141], v[240:241], v[106:107], v[140:141] op_sel_hi:[1,0,1]
	v_pk_fma_f32 v[142:143], v[248:249], v[106:107], v[142:143] op_sel_hi:[1,0,1]
	v_pk_fma_f32 v[140:141], v[242:243], v[106:107], v[140:141] op_sel:[0,1,0]
	v_pk_fma_f32 v[142:143], v[250:251], v[106:107], v[142:143] op_sel:[0,1,0]
	v_add_f32_dpp v108, v252, v252 quad_perm:[1,0,3,2] row_mask:0xf bank_mask:0xf
	v_add_f32_dpp v109, v253, v253 quad_perm:[1,0,3,2] row_mask:0xf bank_mask:0xf
	v_add_f32_dpp v110, v254, v254 quad_perm:[1,0,3,2] row_mask:0xf bank_mask:0xf
	v_add_f32_dpp v111, v255, v255 quad_perm:[1,0,3,2] row_mask:0xf bank_mask:0xf
	v_cndmask_b32_e32 v108, v110, v108, vcc
	v_cndmask_b32_e32 v109, v111, v109, vcc
	v_add_f32_dpp v114, v112, v112 quad_perm:[2,3,0,1] row_mask:0xf bank_mask:0xf
	v_add_f32_dpp v115, v113, v113 quad_perm:[2,3,0,1] row_mask:0xf bank_mask:0xf
	v_cndmask_b32_e64 v112, v115, v114, s[4:5]
	v_cndmask_b32_e64 v117, v112, v116, s[6:7]
	v_cndmask_b32_e64 v118, v116, v112, s[6:7]
	s_waitcnt vmcnt(25)
	v_pk_mul_f32 v[252:253], v[236:237], v[100:101] op_sel_hi:[1,0]
	v_pk_mul_f32 v[254:255], v[244:245], v[100:101] op_sel_hi:[1,0]
	v_pk_fma_f32 v[252:253], v[238:239], v[100:101], v[252:253] op_sel:[0,1,0]
	v_pk_fma_f32 v[254:255], v[246:247], v[100:101], v[254:255] op_sel:[0,1,0]
	v_pk_fma_f32 v[252:253], v[240:241], v[102:103], v[252:253] op_sel_hi:[1,0,1]
	v_pk_fma_f32 v[254:255], v[248:249], v[102:103], v[254:255] op_sel_hi:[1,0,1]
	v_pk_fma_f32 v[252:253], v[242:243], v[102:103], v[252:253] op_sel:[0,1,0]
	v_pk_fma_f32 v[254:255], v[250:251], v[102:103], v[254:255] op_sel:[0,1,0]
	v_add_f32_dpp v116, v118, v117 row_ror:4 row_mask:0xf bank_mask:0xf
	v_cndmask_b32_e64 v125, v116, v124, s[64:65]
	v_cndmask_b32_e64 v126, v124, v116, s[64:65]
	v_add_f32_dpp v104, v140, v140 quad_perm:[1,0,3,2] row_mask:0xf bank_mask:0xf
	v_add_f32_dpp v105, v141, v141 quad_perm:[1,0,3,2] row_mask:0xf bank_mask:0xf
	v_add_f32_dpp v106, v142, v142 quad_perm:[1,0,3,2] row_mask:0xf bank_mask:0xf
	v_add_f32_dpp v107, v143, v143 quad_perm:[1,0,3,2] row_mask:0xf bank_mask:0xf
	v_cndmask_b32_e32 v104, v106, v104, vcc
	v_cndmask_b32_e32 v105, v107, v105, vcc
	v_add_f32_dpp v110, v108, v108 quad_perm:[2,3,0,1] row_mask:0xf bank_mask:0xf
	v_add_f32_dpp v111, v109, v109 quad_perm:[2,3,0,1] row_mask:0xf bank_mask:0xf
	v_cndmask_b32_e64 v108, v111, v110, s[4:5]
	s_waitcnt vmcnt(24)
	v_pk_mul_f32 v[140:141], v[236:237], v[96:97] op_sel_hi:[1,0]
	v_pk_mul_f32 v[142:143], v[244:245], v[96:97] op_sel_hi:[1,0]
	v_pk_fma_f32 v[140:141], v[238:239], v[96:97], v[140:141] op_sel:[0,1,0]
	v_pk_fma_f32 v[142:143], v[246:247], v[96:97], v[142:143] op_sel:[0,1,0]
	v_pk_fma_f32 v[140:141], v[240:241], v[98:99], v[140:141] op_sel_hi:[1,0,1]
	v_pk_fma_f32 v[142:143], v[248:249], v[98:99], v[142:143] op_sel_hi:[1,0,1]
	v_pk_fma_f32 v[140:141], v[242:243], v[98:99], v[140:141] op_sel:[0,1,0]
	v_pk_fma_f32 v[142:143], v[250:251], v[98:99], v[142:143] op_sel:[0,1,0]
	v_add_f32_dpp v124, v126, v125 row_ror:8 row_mask:0xf bank_mask:0xf
	v_add_f32_dpp v100, v252, v252 quad_perm:[1,0,3,2] row_mask:0xf bank_mask:0xf
	v_add_f32_dpp v101, v253, v253 quad_perm:[1,0,3,2] row_mask:0xf bank_mask:0xf
	v_add_f32_dpp v102, v254, v254 quad_perm:[1,0,3,2] row_mask:0xf bank_mask:0xf
	v_add_f32_dpp v103, v255, v255 quad_perm:[1,0,3,2] row_mask:0xf bank_mask:0xf
	v_cndmask_b32_e32 v100, v102, v100, vcc
	v_cndmask_b32_e32 v101, v103, v101, vcc
	v_add_f32_dpp v106, v104, v104 quad_perm:[2,3,0,1] row_mask:0xf bank_mask:0xf
	v_add_f32_dpp v107, v105, v105 quad_perm:[2,3,0,1] row_mask:0xf bank_mask:0xf
	v_cndmask_b32_e64 v104, v107, v106, s[4:5]
	v_cndmask_b32_e64 v109, v104, v108, s[6:7]
	v_cndmask_b32_e64 v110, v108, v104, s[6:7]
	s_waitcnt vmcnt(23)
; DI void attn_sample_item(const Params& p, int item, ldsp lds, int tid_) {
;     ...
;   SC_SCORE(kvA, 0)
;   SC_SCORE(kvB, 1)
	v_pk_mul_f32 v[252:253], v[236:237], v[92:93] op_sel_hi:[1,0]
	v_pk_mul_f32 v[254:255], v[244:245], v[92:93] op_sel_hi:[1,0]
	v_pk_fma_f32 v[252:253], v[238:239], v[92:93], v[252:253] op_sel:[0,1,0]
	v_pk_fma_f32 v[254:255], v[246:247], v[92:93], v[254:255] op_sel:[0,1,0]
	v_pk_fma_f32 v[252:253], v[240:241], v[94:95], v[252:253] op_sel_hi:[1,0,1]
	v_pk_fma_f32 v[254:255], v[248:249], v[94:95], v[254:255] op_sel_hi:[1,0,1]
	v_pk_fma_f32 v[252:253], v[242:243], v[94:95], v[252:253] op_sel:[0,1,0]
	v_pk_fma_f32 v[254:255], v[250:251], v[94:95], v[254:255] op_sel:[0,1,0]
	v_add_f32_dpp v108, v110, v109 row_ror:4 row_mask:0xf bank_mask:0xf
	v_add_f32_dpp v96, v140, v140 quad_perm:[1,0,3,2] row_mask:0xf bank_mask:0xf
	v_add_f32_dpp v97, v141, v141 quad_perm:[1,0,3,2] row_mask:0xf bank_mask:0xf
	v_add_f32_dpp v98, v142, v142 quad_perm:[1,0,3,2] row_mask:0xf bank_mask:0xf
	v_add_f32_dpp v99, v143, v143 quad_perm:[1,0,3,2] row_mask:0xf bank_mask:0xf
	v_cndmask_b32_e32 v96, v98, v96, vcc
	v_cndmask_b32_e32 v97, v99, v97, vcc
	v_add_f32_dpp v102, v100, v100 quad_perm:[2,3,0,1] row_mask:0xf bank_mask:0xf
	v_add_f32_dpp v103, v101, v101 quad_perm:[2,3,0,1] row_mask:0xf bank_mask:0xf
	v_cndmask_b32_e64 v100, v103, v102, s[4:5]
	s_waitcnt vmcnt(22)
	v_pk_mul_f32 v[140:141], v[236:237], v[88:89] op_sel_hi:[1,0]
	v_pk_mul_f32 v[142:143], v[244:245], v[88:89] op_sel_hi:[1,0]
	v_pk_fma_f32 v[140:141], v[238:239], v[88:89], v[140:141] op_sel:[0,1,0]
	v_pk_fma_f32 v[142:143], v[246:247], v[88:89], v[142:143] op_sel:[0,1,0]
	v_pk_fma_f32 v[140:141], v[240:241], v[90:91], v[140:141] op_sel_hi:[1,0,1]
	v_pk_fma_f32 v[142:143], v[248:249], v[90:91], v[142:143] op_sel_hi:[1,0,1]
	v_pk_fma_f32 v[140:141], v[242:243], v[90:91], v[140:141] op_sel:[0,1,0]
	v_pk_fma_f32 v[142:143], v[250:251], v[90:91], v[142:143] op_sel:[0,1,0]
	v_add_f32_dpp v92, v252, v252 quad_perm:[1,0,3,2] row_mask:0xf bank_mask:0xf
	v_add_f32_dpp v93, v253, v253 quad_perm:[1,0,3,2] row_mask:0xf bank_mask:0xf
	v_add_f32_dpp v94, v254, v254 quad_perm:[1,0,3,2] row_mask:0xf bank_mask:0xf
	v_add_f32_dpp v95, v255, v255 quad_perm:[1,0,3,2] row_mask:0xf bank_mask:0xf
	v_cndmask_b32_e32 v92, v94, v92, vcc
	v_cndmask_b32_e32 v93, v95, v93, vcc
	v_add_f32_dpp v98, v96, v96 quad_perm:[2,3,0,1] row_mask:0xf bank_mask:0xf
	v_add_f32_dpp v99, v97, v97 quad_perm:[2,3,0,1] row_mask:0xf bank_mask:0xf
	v_cndmask_b32_e64 v96, v99, v98, s[4:5]
	v_cndmask_b32_e64 v101, v96, v100, s[6:7]
	v_cndmask_b32_e64 v102, v100, v96, s[6:7]
	s_waitcnt vmcnt(21)
	v_pk_mul_f32 v[252:253], v[236:237], v[84:85] op_sel_hi:[1,0]
	v_pk_mul_f32 v[254:255], v[244:245], v[84:85] op_sel_hi:[1,0]
	v_pk_fma_f32 v[252:253], v[238:239], v[84:85], v[252:253] op_sel:[0,1,0]
	v_pk_fma_f32 v[254:255], v[246:247], v[84:85], v[254:255] op_sel:[0,1,0]
	v_pk_fma_f32 v[252:253], v[240:241], v[86:87], v[252:253] op_sel_hi:[1,0,1]
	v_pk_fma_f32 v[254:255], v[248:249], v[86:87], v[254:255] op_sel_hi:[1,0,1]
	v_pk_fma_f32 v[252:253], v[242:243], v[86:87], v[252:253] op_sel:[0,1,0]
	v_pk_fma_f32 v[254:255], v[250:251], v[86:87], v[254:255] op_sel:[0,1,0]
	v_add_f32_dpp v100, v102, v101 row_ror:4 row_mask:0xf bank_mask:0xf
	v_cndmask_b32_e64 v109, v100, v108, s[64:65]
	v_cndmask_b32_e64 v110, v108, v100, s[64:65]
	v_add_f32_dpp v88, v140, v140 quad_perm:[1,0,3,2] row_mask:0xf bank_mask:0xf
	v_add_f32_dpp v89, v141, v141 quad_perm:[1,0,3,2] row_mask:0xf bank_mask:0xf
	v_add_f32_dpp v90, v142, v142 quad_perm:[1,0,3,2] row_mask:0xf bank_mask:0xf
	v_add_f32_dpp v91, v143, v143 quad_perm:[1,0,3,2] row_mask:0xf bank_mask:0xf
	v_cndmask_b32_e32 v88, v90, v88, vcc
	v_cndmask_b32_e32 v89, v91, v89, vcc
	v_add_f32_dpp v94, v92, v92 quad_perm:[2,3,0,1] row_mask:0xf bank_mask:0xf
	v_add_f32_dpp v95, v93, v93 quad_perm:[2,3,0,1] row_mask:0xf bank_mask:0xf
	v_cndmask_b32_e64 v92, v95, v94, s[4:5]
	s_waitcnt vmcnt(20)
	v_pk_mul_f32 v[140:141], v[236:237], v[80:81] op_sel_hi:[1,0]
	v_pk_mul_f32 v[142:143], v[244:245], v[80:81] op_sel_hi:[1,0]
	v_pk_fma_f32 v[140:141], v[238:239], v[80:81], v[140:141] op_sel:[0,1,0]
	v_pk_fma_f32 v[142:143], v[246:247], v[80:81], v[142:143] op_sel:[0,1,0]
	v_pk_fma_f32 v[140:141], v[240:241], v[82:83], v[140:141] op_sel_hi:[1,0,1]
	v_pk_fma_f32 v[142:143], v[248:249], v[82:83], v[142:143] op_sel_hi:[1,0,1]
	v_pk_fma_f32 v[140:141], v[242:243], v[82:83], v[140:141] op_sel:[0,1,0]
	v_pk_fma_f32 v[142:143], v[250:251], v[82:83], v[142:143] op_sel:[0,1,0]
	v_add_f32_dpp v108, v110, v109 row_ror:8 row_mask:0xf bank_mask:0xf
	v_add_f32_dpp v84, v252, v252 quad_perm:[1,0,3,2] row_mask:0xf bank_mask:0xf
	v_add_f32_dpp v85, v253, v253 quad_perm:[1,0,3,2] row_mask:0xf bank_mask:0xf
	v_add_f32_dpp v86, v254, v254 quad_perm:[1,0,3,2] row_mask:0xf bank_mask:0xf
	v_add_f32_dpp v87, v255, v255 quad_perm:[1,0,3,2] row_mask:0xf bank_mask:0xf
	v_cndmask_b32_e32 v84, v86, v84, vcc
	v_cndmask_b32_e32 v85, v87, v85, vcc
	v_add_f32_dpp v90, v88, v88 quad_perm:[2,3,0,1] row_mask:0xf bank_mask:0xf
	v_add_f32_dpp v91, v89, v89 quad_perm:[2,3,0,1] row_mask:0xf bank_mask:0xf
	v_cndmask_b32_e64 v88, v91, v90, s[4:5]
	v_cndmask_b32_e64 v93, v88, v92, s[6:7]
	v_cndmask_b32_e64 v94, v92, v88, s[6:7]
	s_waitcnt vmcnt(19)
; DI void attn_sample_item(const Params& p, int item, ldsp lds, int tid_) {
;     ...
;   SC_SCORE(kvA, 0)
;   SC_SCORE(kvB, 1)
	v_pk_mul_f32 v[252:253], v[236:237], v[76:77] op_sel_hi:[1,0]
	v_pk_mul_f32 v[254:255], v[244:245], v[76:77] op_sel_hi:[1,0]
	v_pk_fma_f32 v[252:253], v[238:239], v[76:77], v[252:253] op_sel:[0,1,0]
	v_pk_fma_f32 v[254:255], v[246:247], v[76:77], v[254:255] op_sel:[0,1,0]
	v_pk_fma_f32 v[252:253], v[240:241], v[78:79], v[252:253] op_sel_hi:[1,0,1]
	v_pk_fma_f32 v[254:255], v[248:249], v[78:79], v[254:255] op_sel_hi:[1,0,1]
	v_pk_fma_f32 v[252:253], v[242:243], v[78:79], v[252:253] op_sel:[0,1,0]
	v_pk_fma_f32 v[254:255], v[250:251], v[78:79], v[254:255] op_sel:[0,1,0]
	v_permlane16_swap_b32_e32 v124, v108
	v_add_f32_e32 v124, v124, v108
	v_add_f32_dpp v92, v94, v93 row_ror:4 row_mask:0xf bank_mask:0xf
	v_add_f32_dpp v80, v140, v140 quad_perm:[1,0,3,2] row_mask:0xf bank_mask:0xf
	v_add_f32_dpp v81, v141, v141 quad_perm:[1,0,3,2] row_mask:0xf bank_mask:0xf
	v_add_f32_dpp v82, v142, v142 quad_perm:[1,0,3,2] row_mask:0xf bank_mask:0xf
	v_add_f32_dpp v83, v143, v143 quad_perm:[1,0,3,2] row_mask:0xf bank_mask:0xf
	v_cndmask_b32_e32 v80, v82, v80, vcc
	v_cndmask_b32_e32 v81, v83, v81, vcc
	v_add_f32_dpp v86, v84, v84 quad_perm:[2,3,0,1] row_mask:0xf bank_mask:0xf
	v_add_f32_dpp v87, v85, v85 quad_perm:[2,3,0,1] row_mask:0xf bank_mask:0xf
	v_cndmask_b32_e64 v84, v87, v86, s[4:5]
	s_waitcnt vmcnt(18)
	v_pk_mul_f32 v[140:141], v[236:237], v[72:73] op_sel_hi:[1,0]
	v_pk_mul_f32 v[142:143], v[244:245], v[72:73] op_sel_hi:[1,0]
	v_pk_fma_f32 v[140:141], v[238:239], v[72:73], v[140:141] op_sel:[0,1,0]
	v_pk_fma_f32 v[142:143], v[246:247], v[72:73], v[142:143] op_sel:[0,1,0]
	v_pk_fma_f32 v[140:141], v[240:241], v[74:75], v[140:141] op_sel_hi:[1,0,1]
	v_pk_fma_f32 v[142:143], v[248:249], v[74:75], v[142:143] op_sel_hi:[1,0,1]
	v_pk_fma_f32 v[140:141], v[242:243], v[74:75], v[140:141] op_sel:[0,1,0]
	v_pk_fma_f32 v[142:143], v[250:251], v[74:75], v[142:143] op_sel:[0,1,0]
	v_add_f32_dpp v76, v252, v252 quad_perm:[1,0,3,2] row_mask:0xf bank_mask:0xf
	v_add_f32_dpp v77, v253, v253 quad_perm:[1,0,3,2] row_mask:0xf bank_mask:0xf
	v_add_f32_dpp v78, v254, v254 quad_perm:[1,0,3,2] row_mask:0xf bank_mask:0xf
	v_add_f32_dpp v79, v255, v255 quad_perm:[1,0,3,2] row_mask:0xf bank_mask:0xf
	v_cndmask_b32_e32 v76, v78, v76, vcc
	v_cndmask_b32_e32 v77, v79, v77, vcc
	v_add_f32_dpp v82, v80, v80 quad_perm:[2,3,0,1] row_mask:0xf bank_mask:0xf
	v_add_f32_dpp v83, v81, v81 quad_perm:[2,3,0,1] row_mask:0xf bank_mask:0xf
	v_cndmask_b32_e64 v80, v83, v82, s[4:5]
	v_cndmask_b32_e64 v85, v80, v84, s[6:7]
	v_cndmask_b32_e64 v86, v84, v80, s[6:7]
	s_waitcnt vmcnt(17)
	v_pk_mul_f32 v[252:253], v[236:237], v[68:69] op_sel_hi:[1,0]
	v_pk_mul_f32 v[254:255], v[244:245], v[68:69] op_sel_hi:[1,0]
	v_pk_fma_f32 v[252:253], v[238:239], v[68:69], v[252:253] op_sel:[0,1,0]
	v_pk_fma_f32 v[254:255], v[246:247], v[68:69], v[254:255] op_sel:[0,1,0]
	v_pk_fma_f32 v[252:253], v[240:241], v[70:71], v[252:253] op_sel_hi:[1,0,1]
	v_pk_fma_f32 v[254:255], v[248:249], v[70:71], v[254:255] op_sel_hi:[1,0,1]
	v_pk_fma_f32 v[252:253], v[242:243], v[70:71], v[252:253] op_sel:[0,1,0]
	v_pk_fma_f32 v[254:255], v[250:251], v[70:71], v[254:255] op_sel:[0,1,0]
	v_add_f32_dpp v84, v86, v85 row_ror:4 row_mask:0xf bank_mask:0xf
	v_cndmask_b32_e64 v93, v84, v92, s[64:65]
	v_cndmask_b32_e64 v94, v92, v84, s[64:65]
	v_add_f32_dpp v72, v140, v140 quad_perm:[1,0,3,2] row_mask:0xf bank_mask:0xf
	v_add_f32_dpp v73, v141, v141 quad_perm:[1,0,3,2] row_mask:0xf bank_mask:0xf
	v_add_f32_dpp v74, v142, v142 quad_perm:[1,0,3,2] row_mask:0xf bank_mask:0xf
	v_add_f32_dpp v75, v143, v143 quad_perm:[1,0,3,2] row_mask:0xf bank_mask:0xf
	v_cndmask_b32_e32 v72, v74, v72, vcc
	v_cndmask_b32_e32 v73, v75, v73, vcc
	v_add_f32_dpp v78, v76, v76 quad_perm:[2,3,0,1] row_mask:0xf bank_mask:0xf
	v_add_f32_dpp v79, v77, v77 quad_perm:[2,3,0,1] row_mask:0xf bank_mask:0xf
	v_cndmask_b32_e64 v76, v79, v78, s[4:5]
	s_waitcnt vmcnt(16)
	v_pk_mul_f32 v[140:141], v[236:237], v[64:65] op_sel_hi:[1,0]
	v_pk_mul_f32 v[142:143], v[244:245], v[64:65] op_sel_hi:[1,0]
	v_pk_fma_f32 v[140:141], v[238:239], v[64:65], v[140:141] op_sel:[0,1,0]
	v_pk_fma_f32 v[142:143], v[246:247], v[64:65], v[142:143] op_sel:[0,1,0]
	v_pk_fma_f32 v[140:141], v[240:241], v[66:67], v[140:141] op_sel_hi:[1,0,1]
	v_pk_fma_f32 v[142:143], v[248:249], v[66:67], v[142:143] op_sel_hi:[1,0,1]
	v_pk_fma_f32 v[140:141], v[242:243], v[66:67], v[140:141] op_sel:[0,1,0]
	v_pk_fma_f32 v[142:143], v[250:251], v[66:67], v[142:143] op_sel:[0,1,0]
	v_add_f32_dpp v92, v94, v93 row_ror:8 row_mask:0xf bank_mask:0xf
	v_add_f32_dpp v68, v252, v252 quad_perm:[1,0,3,2] row_mask:0xf bank_mask:0xf
	v_add_f32_dpp v69, v253, v253 quad_perm:[1,0,3,2] row_mask:0xf bank_mask:0xf
	v_add_f32_dpp v70, v254, v254 quad_perm:[1,0,3,2] row_mask:0xf bank_mask:0xf
	v_add_f32_dpp v71, v255, v255 quad_perm:[1,0,3,2] row_mask:0xf bank_mask:0xf
	v_cndmask_b32_e32 v68, v70, v68, vcc
	v_cndmask_b32_e32 v69, v71, v69, vcc
	v_add_f32_dpp v74, v72, v72 quad_perm:[2,3,0,1] row_mask:0xf bank_mask:0xf
	v_add_f32_dpp v75, v73, v73 quad_perm:[2,3,0,1] row_mask:0xf bank_mask:0xf
	v_cndmask_b32_e64 v72, v75, v74, s[4:5]
	v_cndmask_b32_e64 v77, v72, v76, s[6:7]
	v_cndmask_b32_e64 v78, v76, v72, s[6:7]
	s_waitcnt vmcnt(15)
; DI void attn_sample_item(const Params& p, int item, ldsp lds, int tid_) {
;     ...
;   SC_SCORE(kvA, 0)
;   SC_SCORE(kvB, 1)
	v_pk_mul_f32 v[252:253], v[236:237], v[60:61] op_sel_hi:[1,0]
	v_pk_mul_f32 v[254:255], v[244:245], v[60:61] op_sel_hi:[1,0]
	v_pk_fma_f32 v[252:253], v[238:239], v[60:61], v[252:253] op_sel:[0,1,0]
	v_pk_fma_f32 v[254:255], v[246:247], v[60:61], v[254:255] op_sel:[0,1,0]
	v_pk_fma_f32 v[252:253], v[240:241], v[62:63], v[252:253] op_sel_hi:[1,0,1]
	v_pk_fma_f32 v[254:255], v[248:249], v[62:63], v[254:255] op_sel_hi:[1,0,1]
	v_pk_fma_f32 v[252:253], v[242:243], v[62:63], v[252:253] op_sel:[0,1,0]
	v_pk_fma_f32 v[254:255], v[250:251], v[62:63], v[254:255] op_sel:[0,1,0]
	v_add_f32_dpp v76, v78, v77 row_ror:4 row_mask:0xf bank_mask:0xf
	v_add_f32_dpp v64, v140, v140 quad_perm:[1,0,3,2] row_mask:0xf bank_mask:0xf
	v_add_f32_dpp v65, v141, v141 quad_perm:[1,0,3,2] row_mask:0xf bank_mask:0xf
	v_add_f32_dpp v66, v142, v142 quad_perm:[1,0,3,2] row_mask:0xf bank_mask:0xf
	v_add_f32_dpp v67, v143, v143 quad_perm:[1,0,3,2] row_mask:0xf bank_mask:0xf
	v_cndmask_b32_e32 v64, v66, v64, vcc
	v_cndmask_b32_e32 v65, v67, v65, vcc
	v_add_f32_dpp v70, v68, v68 quad_perm:[2,3,0,1] row_mask:0xf bank_mask:0xf
	v_add_f32_dpp v71, v69, v69 quad_perm:[2,3,0,1] row_mask:0xf bank_mask:0xf
	v_cndmask_b32_e64 v68, v71, v70, s[4:5]
	s_waitcnt vmcnt(14)
	v_pk_mul_f32 v[140:141], v[236:237], v[56:57] op_sel_hi:[1,0]
	v_pk_mul_f32 v[142:143], v[244:245], v[56:57] op_sel_hi:[1,0]
	v_pk_fma_f32 v[140:141], v[238:239], v[56:57], v[140:141] op_sel:[0,1,0]
	v_pk_fma_f32 v[142:143], v[246:247], v[56:57], v[142:143] op_sel:[0,1,0]
	v_pk_fma_f32 v[140:141], v[240:241], v[58:59], v[140:141] op_sel_hi:[1,0,1]
	v_pk_fma_f32 v[142:143], v[248:249], v[58:59], v[142:143] op_sel_hi:[1,0,1]
	v_pk_fma_f32 v[140:141], v[242:243], v[58:59], v[140:141] op_sel:[0,1,0]
	v_pk_fma_f32 v[142:143], v[250:251], v[58:59], v[142:143] op_sel:[0,1,0]
	v_add_f32_dpp v60, v252, v252 quad_perm:[1,0,3,2] row_mask:0xf bank_mask:0xf
	v_add_f32_dpp v61, v253, v253 quad_perm:[1,0,3,2] row_mask:0xf bank_mask:0xf
	v_add_f32_dpp v62, v254, v254 quad_perm:[1,0,3,2] row_mask:0xf bank_mask:0xf
	v_add_f32_dpp v63, v255, v255 quad_perm:[1,0,3,2] row_mask:0xf bank_mask:0xf
	v_cndmask_b32_e32 v60, v62, v60, vcc
	v_cndmask_b32_e32 v61, v63, v61, vcc
	v_add_f32_dpp v66, v64, v64 quad_perm:[2,3,0,1] row_mask:0xf bank_mask:0xf
	v_add_f32_dpp v67, v65, v65 quad_perm:[2,3,0,1] row_mask:0xf bank_mask:0xf
	v_cndmask_b32_e64 v64, v67, v66, s[4:5]
	v_cndmask_b32_e64 v69, v64, v68, s[6:7]
	v_cndmask_b32_e64 v70, v68, v64, s[6:7]
	s_waitcnt vmcnt(13)
	v_pk_mul_f32 v[252:253], v[236:237], v[52:53] op_sel_hi:[1,0]
	v_pk_mul_f32 v[254:255], v[244:245], v[52:53] op_sel_hi:[1,0]
	v_pk_fma_f32 v[252:253], v[238:239], v[52:53], v[252:253] op_sel:[0,1,0]
	v_pk_fma_f32 v[254:255], v[246:247], v[52:53], v[254:255] op_sel:[0,1,0]
	v_pk_fma_f32 v[252:253], v[240:241], v[54:55], v[252:253] op_sel_hi:[1,0,1]
	v_pk_fma_f32 v[254:255], v[248:249], v[54:55], v[254:255] op_sel_hi:[1,0,1]
	v_pk_fma_f32 v[252:253], v[242:243], v[54:55], v[252:253] op_sel:[0,1,0]
	v_pk_fma_f32 v[254:255], v[250:251], v[54:55], v[254:255] op_sel:[0,1,0]
	v_add_f32_dpp v68, v70, v69 row_ror:4 row_mask:0xf bank_mask:0xf
	v_cndmask_b32_e64 v77, v68, v76, s[64:65]
	v_cndmask_b32_e64 v78, v76, v68, s[64:65]
	v_add_f32_dpp v56, v140, v140 quad_perm:[1,0,3,2] row_mask:0xf bank_mask:0xf
	v_add_f32_dpp v57, v141, v141 quad_perm:[1,0,3,2] row_mask:0xf bank_mask:0xf
	v_add_f32_dpp v58, v142, v142 quad_perm:[1,0,3,2] row_mask:0xf bank_mask:0xf
	v_add_f32_dpp v59, v143, v143 quad_perm:[1,0,3,2] row_mask:0xf bank_mask:0xf
	v_cndmask_b32_e32 v56, v58, v56, vcc
	v_cndmask_b32_e32 v57, v59, v57, vcc
	v_add_f32_dpp v62, v60, v60 quad_perm:[2,3,0,1] row_mask:0xf bank_mask:0xf
	v_add_f32_dpp v63, v61, v61 quad_perm:[2,3,0,1] row_mask:0xf bank_mask:0xf
	v_cndmask_b32_e64 v60, v63, v62, s[4:5]
	s_waitcnt vmcnt(12)
	v_pk_mul_f32 v[140:141], v[236:237], v[48:49] op_sel_hi:[1,0]
	v_pk_mul_f32 v[142:143], v[244:245], v[48:49] op_sel_hi:[1,0]
	v_pk_fma_f32 v[140:141], v[238:239], v[48:49], v[140:141] op_sel:[0,1,0]
	v_pk_fma_f32 v[142:143], v[246:247], v[48:49], v[142:143] op_sel:[0,1,0]
	v_pk_fma_f32 v[140:141], v[240:241], v[50:51], v[140:141] op_sel_hi:[1,0,1]
	v_pk_fma_f32 v[142:143], v[248:249], v[50:51], v[142:143] op_sel_hi:[1,0,1]
	v_pk_fma_f32 v[140:141], v[242:243], v[50:51], v[140:141] op_sel:[0,1,0]
	v_pk_fma_f32 v[142:143], v[250:251], v[50:51], v[142:143] op_sel:[0,1,0]
	v_add_f32_dpp v76, v78, v77 row_ror:8 row_mask:0xf bank_mask:0xf
	v_add_f32_dpp v52, v252, v252 quad_perm:[1,0,3,2] row_mask:0xf bank_mask:0xf
	v_add_f32_dpp v53, v253, v253 quad_perm:[1,0,3,2] row_mask:0xf bank_mask:0xf
	v_add_f32_dpp v54, v254, v254 quad_perm:[1,0,3,2] row_mask:0xf bank_mask:0xf
	v_add_f32_dpp v55, v255, v255 quad_perm:[1,0,3,2] row_mask:0xf bank_mask:0xf
	v_cndmask_b32_e32 v52, v54, v52, vcc
	v_cndmask_b32_e32 v53, v55, v53, vcc
	v_add_f32_dpp v58, v56, v56 quad_perm:[2,3,0,1] row_mask:0xf bank_mask:0xf
	v_add_f32_dpp v59, v57, v57 quad_perm:[2,3,0,1] row_mask:0xf bank_mask:0xf
	v_cndmask_b32_e64 v56, v59, v58, s[4:5]
	v_cndmask_b32_e64 v61, v56, v60, s[6:7]
	v_cndmask_b32_e64 v62, v60, v56, s[6:7]
	s_waitcnt vmcnt(11)
; DI void attn_sample_item(const Params& p, int item, ldsp lds, int tid_) {
;     ...
;   SC_SCORE(kvA, 0)
;   SC_SCORE(kvB, 1)
	v_pk_mul_f32 v[252:253], v[236:237], v[44:45] op_sel_hi:[1,0]
	v_pk_mul_f32 v[254:255], v[244:245], v[44:45] op_sel_hi:[1,0]
	v_pk_fma_f32 v[252:253], v[238:239], v[44:45], v[252:253] op_sel:[0,1,0]
	v_pk_fma_f32 v[254:255], v[246:247], v[44:45], v[254:255] op_sel:[0,1,0]
	v_pk_fma_f32 v[252:253], v[240:241], v[46:47], v[252:253] op_sel_hi:[1,0,1]
	v_pk_fma_f32 v[254:255], v[248:249], v[46:47], v[254:255] op_sel_hi:[1,0,1]
	v_pk_fma_f32 v[252:253], v[242:243], v[46:47], v[252:253] op_sel:[0,1,0]
	v_pk_fma_f32 v[254:255], v[250:251], v[46:47], v[254:255] op_sel:[0,1,0]
	v_permlane16_swap_b32_e32 v92, v76
	v_add_f32_e32 v92, v92, v76
	v_add_f32_dpp v60, v62, v61 row_ror:4 row_mask:0xf bank_mask:0xf
	v_add_f32_dpp v48, v140, v140 quad_perm:[1,0,3,2] row_mask:0xf bank_mask:0xf
	v_add_f32_dpp v49, v141, v141 quad_perm:[1,0,3,2] row_mask:0xf bank_mask:0xf
	v_add_f32_dpp v50, v142, v142 quad_perm:[1,0,3,2] row_mask:0xf bank_mask:0xf
	v_add_f32_dpp v51, v143, v143 quad_perm:[1,0,3,2] row_mask:0xf bank_mask:0xf
	v_cndmask_b32_e32 v48, v50, v48, vcc
	v_cndmask_b32_e32 v49, v51, v49, vcc
	v_add_f32_dpp v54, v52, v52 quad_perm:[2,3,0,1] row_mask:0xf bank_mask:0xf
	v_add_f32_dpp v55, v53, v53 quad_perm:[2,3,0,1] row_mask:0xf bank_mask:0xf
	v_cndmask_b32_e64 v52, v55, v54, s[4:5]
	s_waitcnt vmcnt(10)
	v_pk_mul_f32 v[140:141], v[236:237], v[40:41] op_sel_hi:[1,0]
	v_pk_mul_f32 v[142:143], v[244:245], v[40:41] op_sel_hi:[1,0]
	v_pk_fma_f32 v[140:141], v[238:239], v[40:41], v[140:141] op_sel:[0,1,0]
	v_pk_fma_f32 v[142:143], v[246:247], v[40:41], v[142:143] op_sel:[0,1,0]
	v_pk_fma_f32 v[140:141], v[240:241], v[42:43], v[140:141] op_sel_hi:[1,0,1]
	v_pk_fma_f32 v[142:143], v[248:249], v[42:43], v[142:143] op_sel_hi:[1,0,1]
	v_pk_fma_f32 v[140:141], v[242:243], v[42:43], v[140:141] op_sel:[0,1,0]
	v_pk_fma_f32 v[142:143], v[250:251], v[42:43], v[142:143] op_sel:[0,1,0]
	v_permlane32_swap_b32_e32 v124, v92
	v_add_f32_e32 v124, v124, v92
	ds_write_b32 v235, v124
	v_add_f32_dpp v44, v252, v252 quad_perm:[1,0,3,2] row_mask:0xf bank_mask:0xf
	v_add_f32_dpp v45, v253, v253 quad_perm:[1,0,3,2] row_mask:0xf bank_mask:0xf
	v_add_f32_dpp v46, v254, v254 quad_perm:[1,0,3,2] row_mask:0xf bank_mask:0xf
	v_add_f32_dpp v47, v255, v255 quad_perm:[1,0,3,2] row_mask:0xf bank_mask:0xf
	v_cndmask_b32_e32 v44, v46, v44, vcc
	v_cndmask_b32_e32 v45, v47, v45, vcc
	v_add_f32_dpp v50, v48, v48 quad_perm:[2,3,0,1] row_mask:0xf bank_mask:0xf
	v_add_f32_dpp v51, v49, v49 quad_perm:[2,3,0,1] row_mask:0xf bank_mask:0xf
	v_cndmask_b32_e64 v48, v51, v50, s[4:5]
	v_cndmask_b32_e64 v53, v48, v52, s[6:7]
	v_cndmask_b32_e64 v54, v52, v48, s[6:7]
	s_waitcnt vmcnt(9)
	v_pk_mul_f32 v[252:253], v[236:237], v[36:37] op_sel_hi:[1,0]
	v_pk_mul_f32 v[254:255], v[244:245], v[36:37] op_sel_hi:[1,0]
	v_pk_fma_f32 v[252:253], v[238:239], v[36:37], v[252:253] op_sel:[0,1,0]
	v_pk_fma_f32 v[254:255], v[246:247], v[36:37], v[254:255] op_sel:[0,1,0]
	v_pk_fma_f32 v[252:253], v[240:241], v[38:39], v[252:253] op_sel_hi:[1,0,1]
	v_pk_fma_f32 v[254:255], v[248:249], v[38:39], v[254:255] op_sel_hi:[1,0,1]
	v_pk_fma_f32 v[252:253], v[242:243], v[38:39], v[252:253] op_sel:[0,1,0]
	v_pk_fma_f32 v[254:255], v[250:251], v[38:39], v[254:255] op_sel:[0,1,0]
	v_add_f32_dpp v52, v54, v53 row_ror:4 row_mask:0xf bank_mask:0xf
	v_cndmask_b32_e64 v61, v52, v60, s[64:65]
	v_cndmask_b32_e64 v62, v60, v52, s[64:65]
	v_add_f32_dpp v40, v140, v140 quad_perm:[1,0,3,2] row_mask:0xf bank_mask:0xf
	v_add_f32_dpp v41, v141, v141 quad_perm:[1,0,3,2] row_mask:0xf bank_mask:0xf
	v_add_f32_dpp v42, v142, v142 quad_perm:[1,0,3,2] row_mask:0xf bank_mask:0xf
	v_add_f32_dpp v43, v143, v143 quad_perm:[1,0,3,2] row_mask:0xf bank_mask:0xf
	v_cndmask_b32_e32 v40, v42, v40, vcc
	v_cndmask_b32_e32 v41, v43, v41, vcc
	v_add_f32_dpp v46, v44, v44 quad_perm:[2,3,0,1] row_mask:0xf bank_mask:0xf
	v_add_f32_dpp v47, v45, v45 quad_perm:[2,3,0,1] row_mask:0xf bank_mask:0xf
	v_cndmask_b32_e64 v44, v47, v46, s[4:5]
	s_waitcnt vmcnt(8)
	v_pk_mul_f32 v[140:141], v[236:237], v[32:33] op_sel_hi:[1,0]
	v_pk_mul_f32 v[142:143], v[244:245], v[32:33] op_sel_hi:[1,0]
	v_pk_fma_f32 v[140:141], v[238:239], v[32:33], v[140:141] op_sel:[0,1,0]
	v_pk_fma_f32 v[142:143], v[246:247], v[32:33], v[142:143] op_sel:[0,1,0]
	v_pk_fma_f32 v[140:141], v[240:241], v[34:35], v[140:141] op_sel_hi:[1,0,1]
	v_pk_fma_f32 v[142:143], v[248:249], v[34:35], v[142:143] op_sel_hi:[1,0,1]
	v_pk_fma_f32 v[140:141], v[242:243], v[34:35], v[140:141] op_sel:[0,1,0]
	v_pk_fma_f32 v[142:143], v[250:251], v[34:35], v[142:143] op_sel:[0,1,0]
	v_add_f32_dpp v60, v62, v61 row_ror:8 row_mask:0xf bank_mask:0xf
	v_add_f32_dpp v36, v252, v252 quad_perm:[1,0,3,2] row_mask:0xf bank_mask:0xf
	v_add_f32_dpp v37, v253, v253 quad_perm:[1,0,3,2] row_mask:0xf bank_mask:0xf
	v_add_f32_dpp v38, v254, v254 quad_perm:[1,0,3,2] row_mask:0xf bank_mask:0xf
	v_add_f32_dpp v39, v255, v255 quad_perm:[1,0,3,2] row_mask:0xf bank_mask:0xf
	v_cndmask_b32_e32 v36, v38, v36, vcc
	v_cndmask_b32_e32 v37, v39, v37, vcc
	v_add_f32_dpp v42, v40, v40 quad_perm:[2,3,0,1] row_mask:0xf bank_mask:0xf
	v_add_f32_dpp v43, v41, v41 quad_perm:[2,3,0,1] row_mask:0xf bank_mask:0xf
	v_cndmask_b32_e64 v40, v43, v42, s[4:5]
	v_cndmask_b32_e64 v45, v40, v44, s[6:7]
	v_cndmask_b32_e64 v46, v44, v40, s[6:7]
	s_waitcnt vmcnt(7)
; DI void attn_sample_item(const Params& p, int item, ldsp lds, int tid_) {
;     ...
;   SC_SCORE(kvA, 0)
;   SC_SCORE(kvB, 1)
	v_pk_mul_f32 v[252:253], v[236:237], v[28:29] op_sel_hi:[1,0]
	v_pk_mul_f32 v[254:255], v[244:245], v[28:29] op_sel_hi:[1,0]
	v_pk_fma_f32 v[252:253], v[238:239], v[28:29], v[252:253] op_sel:[0,1,0]
	v_pk_fma_f32 v[254:255], v[246:247], v[28:29], v[254:255] op_sel:[0,1,0]
	v_pk_fma_f32 v[252:253], v[240:241], v[30:31], v[252:253] op_sel_hi:[1,0,1]
	v_pk_fma_f32 v[254:255], v[248:249], v[30:31], v[254:255] op_sel_hi:[1,0,1]
	v_pk_fma_f32 v[252:253], v[242:243], v[30:31], v[252:253] op_sel:[0,1,0]
	v_pk_fma_f32 v[254:255], v[250:251], v[30:31], v[254:255] op_sel:[0,1,0]
	v_add_f32_dpp v44, v46, v45 row_ror:4 row_mask:0xf bank_mask:0xf
	v_add_f32_dpp v32, v140, v140 quad_perm:[1,0,3,2] row_mask:0xf bank_mask:0xf
	v_add_f32_dpp v33, v141, v141 quad_perm:[1,0,3,2] row_mask:0xf bank_mask:0xf
	v_add_f32_dpp v34, v142, v142 quad_perm:[1,0,3,2] row_mask:0xf bank_mask:0xf
	v_add_f32_dpp v35, v143, v143 quad_perm:[1,0,3,2] row_mask:0xf bank_mask:0xf
	v_cndmask_b32_e32 v32, v34, v32, vcc
	v_cndmask_b32_e32 v33, v35, v33, vcc
	v_add_f32_dpp v38, v36, v36 quad_perm:[2,3,0,1] row_mask:0xf bank_mask:0xf
	v_add_f32_dpp v39, v37, v37 quad_perm:[2,3,0,1] row_mask:0xf bank_mask:0xf
	v_cndmask_b32_e64 v36, v39, v38, s[4:5]
	s_waitcnt vmcnt(6)
	v_pk_mul_f32 v[140:141], v[236:237], v[24:25] op_sel_hi:[1,0]
	v_pk_mul_f32 v[142:143], v[244:245], v[24:25] op_sel_hi:[1,0]
	v_pk_fma_f32 v[140:141], v[238:239], v[24:25], v[140:141] op_sel:[0,1,0]
	v_pk_fma_f32 v[142:143], v[246:247], v[24:25], v[142:143] op_sel:[0,1,0]
	v_pk_fma_f32 v[140:141], v[240:241], v[26:27], v[140:141] op_sel_hi:[1,0,1]
	v_pk_fma_f32 v[142:143], v[248:249], v[26:27], v[142:143] op_sel_hi:[1,0,1]
	v_pk_fma_f32 v[140:141], v[242:243], v[26:27], v[140:141] op_sel:[0,1,0]
	v_pk_fma_f32 v[142:143], v[250:251], v[26:27], v[142:143] op_sel:[0,1,0]
	v_add_f32_dpp v28, v252, v252 quad_perm:[1,0,3,2] row_mask:0xf bank_mask:0xf
	v_add_f32_dpp v29, v253, v253 quad_perm:[1,0,3,2] row_mask:0xf bank_mask:0xf
	v_add_f32_dpp v30, v254, v254 quad_perm:[1,0,3,2] row_mask:0xf bank_mask:0xf
	v_add_f32_dpp v31, v255, v255 quad_perm:[1,0,3,2] row_mask:0xf bank_mask:0xf
	v_cndmask_b32_e32 v28, v30, v28, vcc
	v_cndmask_b32_e32 v29, v31, v29, vcc
	v_add_f32_dpp v34, v32, v32 quad_perm:[2,3,0,1] row_mask:0xf bank_mask:0xf
	v_add_f32_dpp v35, v33, v33 quad_perm:[2,3,0,1] row_mask:0xf bank_mask:0xf
	v_cndmask_b32_e64 v32, v35, v34, s[4:5]
	v_cndmask_b32_e64 v37, v32, v36, s[6:7]
	v_cndmask_b32_e64 v38, v36, v32, s[6:7]
	s_waitcnt vmcnt(5)
	v_pk_mul_f32 v[252:253], v[236:237], v[20:21] op_sel_hi:[1,0]
	v_pk_mul_f32 v[254:255], v[244:245], v[20:21] op_sel_hi:[1,0]
	v_pk_fma_f32 v[252:253], v[238:239], v[20:21], v[252:253] op_sel:[0,1,0]
	v_pk_fma_f32 v[254:255], v[246:247], v[20:21], v[254:255] op_sel:[0,1,0]
	v_pk_fma_f32 v[252:253], v[240:241], v[22:23], v[252:253] op_sel_hi:[1,0,1]
	v_pk_fma_f32 v[254:255], v[248:249], v[22:23], v[254:255] op_sel_hi:[1,0,1]
	v_pk_fma_f32 v[252:253], v[242:243], v[22:23], v[252:253] op_sel:[0,1,0]
	v_pk_fma_f32 v[254:255], v[250:251], v[22:23], v[254:255] op_sel:[0,1,0]
	v_add_f32_dpp v36, v38, v37 row_ror:4 row_mask:0xf bank_mask:0xf
	v_cndmask_b32_e64 v45, v36, v44, s[64:65]
	v_cndmask_b32_e64 v46, v44, v36, s[64:65]
	v_add_f32_dpp v24, v140, v140 quad_perm:[1,0,3,2] row_mask:0xf bank_mask:0xf
	v_add_f32_dpp v25, v141, v141 quad_perm:[1,0,3,2] row_mask:0xf bank_mask:0xf
	v_add_f32_dpp v26, v142, v142 quad_perm:[1,0,3,2] row_mask:0xf bank_mask:0xf
	v_add_f32_dpp v27, v143, v143 quad_perm:[1,0,3,2] row_mask:0xf bank_mask:0xf
	v_cndmask_b32_e32 v24, v26, v24, vcc
	v_cndmask_b32_e32 v25, v27, v25, vcc
	v_add_f32_dpp v30, v28, v28 quad_perm:[2,3,0,1] row_mask:0xf bank_mask:0xf
	v_add_f32_dpp v31, v29, v29 quad_perm:[2,3,0,1] row_mask:0xf bank_mask:0xf
	v_cndmask_b32_e64 v28, v31, v30, s[4:5]
	s_waitcnt vmcnt(4)
	v_pk_mul_f32 v[140:141], v[236:237], v[16:17] op_sel_hi:[1,0]
	v_pk_mul_f32 v[142:143], v[244:245], v[16:17] op_sel_hi:[1,0]
	v_pk_fma_f32 v[140:141], v[238:239], v[16:17], v[140:141] op_sel:[0,1,0]
	v_pk_fma_f32 v[142:143], v[246:247], v[16:17], v[142:143] op_sel:[0,1,0]
	v_pk_fma_f32 v[140:141], v[240:241], v[18:19], v[140:141] op_sel_hi:[1,0,1]
	v_pk_fma_f32 v[142:143], v[248:249], v[18:19], v[142:143] op_sel_hi:[1,0,1]
	v_pk_fma_f32 v[140:141], v[242:243], v[18:19], v[140:141] op_sel:[0,1,0]
	v_pk_fma_f32 v[142:143], v[250:251], v[18:19], v[142:143] op_sel:[0,1,0]
	v_add_f32_dpp v44, v46, v45 row_ror:8 row_mask:0xf bank_mask:0xf
	v_add_f32_dpp v20, v252, v252 quad_perm:[1,0,3,2] row_mask:0xf bank_mask:0xf
	v_add_f32_dpp v21, v253, v253 quad_perm:[1,0,3,2] row_mask:0xf bank_mask:0xf
	v_add_f32_dpp v22, v254, v254 quad_perm:[1,0,3,2] row_mask:0xf bank_mask:0xf
	v_add_f32_dpp v23, v255, v255 quad_perm:[1,0,3,2] row_mask:0xf bank_mask:0xf
	v_cndmask_b32_e32 v20, v22, v20, vcc
	v_cndmask_b32_e32 v21, v23, v21, vcc
	v_add_f32_dpp v26, v24, v24 quad_perm:[2,3,0,1] row_mask:0xf bank_mask:0xf
	v_add_f32_dpp v27, v25, v25 quad_perm:[2,3,0,1] row_mask:0xf bank_mask:0xf
	v_cndmask_b32_e64 v24, v27, v26, s[4:5]
	v_cndmask_b32_e64 v29, v24, v28, s[6:7]
	v_cndmask_b32_e64 v30, v28, v24, s[6:7]
	s_waitcnt vmcnt(3)
; DI void attn_sample_item(const Params& p, int item, ldsp lds, int tid_) {
;     ...
;   SC_SCORE(kvA, 0)
;   SC_SCORE(kvB, 1)
	v_pk_mul_f32 v[252:253], v[236:237], v[12:13] op_sel_hi:[1,0]
	v_pk_mul_f32 v[254:255], v[244:245], v[12:13] op_sel_hi:[1,0]
	v_pk_fma_f32 v[252:253], v[238:239], v[12:13], v[252:253] op_sel:[0,1,0]
	v_pk_fma_f32 v[254:255], v[246:247], v[12:13], v[254:255] op_sel:[0,1,0]
	v_pk_fma_f32 v[252:253], v[240:241], v[14:15], v[252:253] op_sel_hi:[1,0,1]
	v_pk_fma_f32 v[254:255], v[248:249], v[14:15], v[254:255] op_sel_hi:[1,0,1]
	v_pk_fma_f32 v[252:253], v[242:243], v[14:15], v[252:253] op_sel:[0,1,0]
	v_pk_fma_f32 v[254:255], v[250:251], v[14:15], v[254:255] op_sel:[0,1,0]
	v_permlane16_swap_b32_e32 v60, v44
	v_add_f32_e32 v60, v60, v44
	v_add_f32_dpp v28, v30, v29 row_ror:4 row_mask:0xf bank_mask:0xf
	v_add_f32_dpp v16, v140, v140 quad_perm:[1,0,3,2] row_mask:0xf bank_mask:0xf
	v_add_f32_dpp v17, v141, v141 quad_perm:[1,0,3,2] row_mask:0xf bank_mask:0xf
	v_add_f32_dpp v18, v142, v142 quad_perm:[1,0,3,2] row_mask:0xf bank_mask:0xf
	v_add_f32_dpp v19, v143, v143 quad_perm:[1,0,3,2] row_mask:0xf bank_mask:0xf
	v_cndmask_b32_e32 v16, v18, v16, vcc
	v_cndmask_b32_e32 v17, v19, v17, vcc
	v_add_f32_dpp v22, v20, v20 quad_perm:[2,3,0,1] row_mask:0xf bank_mask:0xf
	v_add_f32_dpp v23, v21, v21 quad_perm:[2,3,0,1] row_mask:0xf bank_mask:0xf
	v_cndmask_b32_e64 v20, v23, v22, s[4:5]
	s_waitcnt vmcnt(2)
	v_pk_mul_f32 v[140:141], v[236:237], v[8:9] op_sel_hi:[1,0]
	v_pk_mul_f32 v[142:143], v[244:245], v[8:9] op_sel_hi:[1,0]
	v_pk_fma_f32 v[140:141], v[238:239], v[8:9], v[140:141] op_sel:[0,1,0]
	v_pk_fma_f32 v[142:143], v[246:247], v[8:9], v[142:143] op_sel:[0,1,0]
	v_pk_fma_f32 v[140:141], v[240:241], v[10:11], v[140:141] op_sel_hi:[1,0,1]
	v_pk_fma_f32 v[142:143], v[248:249], v[10:11], v[142:143] op_sel_hi:[1,0,1]
	v_pk_fma_f32 v[140:141], v[242:243], v[10:11], v[140:141] op_sel:[0,1,0]
	v_pk_fma_f32 v[142:143], v[250:251], v[10:11], v[142:143] op_sel:[0,1,0]
	v_add_f32_dpp v12, v252, v252 quad_perm:[1,0,3,2] row_mask:0xf bank_mask:0xf
	v_add_f32_dpp v13, v253, v253 quad_perm:[1,0,3,2] row_mask:0xf bank_mask:0xf
	v_add_f32_dpp v14, v254, v254 quad_perm:[1,0,3,2] row_mask:0xf bank_mask:0xf
	v_add_f32_dpp v15, v255, v255 quad_perm:[1,0,3,2] row_mask:0xf bank_mask:0xf
	v_cndmask_b32_e32 v12, v14, v12, vcc
	v_cndmask_b32_e32 v13, v15, v13, vcc
	v_add_f32_dpp v18, v16, v16 quad_perm:[2,3,0,1] row_mask:0xf bank_mask:0xf
	v_add_f32_dpp v19, v17, v17 quad_perm:[2,3,0,1] row_mask:0xf bank_mask:0xf
	v_cndmask_b32_e64 v16, v19, v18, s[4:5]
	v_cndmask_b32_e64 v21, v16, v20, s[6:7]
	v_cndmask_b32_e64 v22, v20, v16, s[6:7]
	s_waitcnt vmcnt(1)
	v_pk_mul_f32 v[252:253], v[236:237], v[4:5] op_sel_hi:[1,0]
	v_pk_mul_f32 v[254:255], v[244:245], v[4:5] op_sel_hi:[1,0]
	v_pk_fma_f32 v[252:253], v[238:239], v[4:5], v[252:253] op_sel:[0,1,0]
	v_pk_fma_f32 v[254:255], v[246:247], v[4:5], v[254:255] op_sel:[0,1,0]
	v_pk_fma_f32 v[252:253], v[240:241], v[6:7], v[252:253] op_sel_hi:[1,0,1]
	v_pk_fma_f32 v[254:255], v[248:249], v[6:7], v[254:255] op_sel_hi:[1,0,1]
	v_pk_fma_f32 v[252:253], v[242:243], v[6:7], v[252:253] op_sel:[0,1,0]
	v_pk_fma_f32 v[254:255], v[250:251], v[6:7], v[254:255] op_sel:[0,1,0]
	v_add_f32_dpp v20, v22, v21 row_ror:4 row_mask:0xf bank_mask:0xf
	v_cndmask_b32_e64 v29, v20, v28, s[64:65]
	v_cndmask_b32_e64 v30, v28, v20, s[64:65]
	v_add_f32_dpp v8, v140, v140 quad_perm:[1,0,3,2] row_mask:0xf bank_mask:0xf
	v_add_f32_dpp v9, v141, v141 quad_perm:[1,0,3,2] row_mask:0xf bank_mask:0xf
	v_add_f32_dpp v10, v142, v142 quad_perm:[1,0,3,2] row_mask:0xf bank_mask:0xf
	v_add_f32_dpp v11, v143, v143 quad_perm:[1,0,3,2] row_mask:0xf bank_mask:0xf
	v_cndmask_b32_e32 v8, v10, v8, vcc
	v_cndmask_b32_e32 v9, v11, v9, vcc
	v_add_f32_dpp v14, v12, v12 quad_perm:[2,3,0,1] row_mask:0xf bank_mask:0xf
	v_add_f32_dpp v15, v13, v13 quad_perm:[2,3,0,1] row_mask:0xf bank_mask:0xf
	v_cndmask_b32_e64 v12, v15, v14, s[4:5]
	s_waitcnt vmcnt(0)
; DI void lbar() { asm volatile("s_waitcnt lgkmcnt(0)" ::: "memory"); __builtin_amdgcn_s_barrier(); asm volatile("" ::: "memory"); }
; DI void attn_sample_item(const Params& p, int item, ldsp lds, int tid_) {
;     ...
;   SC_SCORE(kvA, 0)
;   SC_SCORE(kvB, 1)
;     ...
;   f32x4 vvA[16], vvB[16];
; #pragma unroll
;   for (int j = 0; j < 16; ++j) vvA[j] = __builtin_nontemporal_load((const f32x4*)(cv + (size_t)(wid * 32 + j) * 1024 + lane * 4));
;   lbar();
;   if (wid < 4) {
;     ...
;   for (int j = 0; j < 16; ++j) vvB[j] = __builtin_nontemporal_load((const f32x4*)(cv + (size_t)(wid * 32 + 16 + j) * 1024 + lane * 4));
	v_pk_mul_f32 v[140:141], v[236:237], v[0:1] op_sel_hi:[1,0]
	v_pk_mul_f32 v[142:143], v[244:245], v[0:1] op_sel_hi:[1,0]
	v_pk_fma_f32 v[140:141], v[238:239], v[0:1], v[140:141] op_sel:[0,1,0]
	v_pk_fma_f32 v[142:143], v[246:247], v[0:1], v[142:143] op_sel:[0,1,0]
	v_pk_fma_f32 v[140:141], v[240:241], v[2:3], v[140:141] op_sel_hi:[1,0,1]
	v_pk_fma_f32 v[142:143], v[248:249], v[2:3], v[142:143] op_sel_hi:[1,0,1]
	v_pk_fma_f32 v[140:141], v[242:243], v[2:3], v[140:141] op_sel:[0,1,0]
	v_pk_fma_f32 v[142:143], v[250:251], v[2:3], v[142:143] op_sel:[0,1,0]
	v_add_f32_dpp v28, v30, v29 row_ror:8 row_mask:0xf bank_mask:0xf
	v_add_f32_dpp v4, v252, v252 quad_perm:[1,0,3,2] row_mask:0xf bank_mask:0xf
	v_add_f32_dpp v5, v253, v253 quad_perm:[1,0,3,2] row_mask:0xf bank_mask:0xf
	v_add_f32_dpp v6, v254, v254 quad_perm:[1,0,3,2] row_mask:0xf bank_mask:0xf
	v_add_f32_dpp v7, v255, v255 quad_perm:[1,0,3,2] row_mask:0xf bank_mask:0xf
	v_cndmask_b32_e32 v4, v6, v4, vcc
	v_cndmask_b32_e32 v5, v7, v5, vcc
	v_add_f32_dpp v10, v8, v8 quad_perm:[2,3,0,1] row_mask:0xf bank_mask:0xf
	v_add_f32_dpp v11, v9, v9 quad_perm:[2,3,0,1] row_mask:0xf bank_mask:0xf
	v_cndmask_b32_e64 v8, v11, v10, s[4:5]
	v_cndmask_b32_e64 v13, v8, v12, s[6:7]
	v_cndmask_b32_e64 v14, v12, v8, s[6:7]
	s_nop 1
	v_add_f32_dpp v12, v14, v13 row_ror:4 row_mask:0xf bank_mask:0xf
	v_add_f32_dpp v0, v140, v140 quad_perm:[1,0,3,2] row_mask:0xf bank_mask:0xf
	v_add_f32_dpp v1, v141, v141 quad_perm:[1,0,3,2] row_mask:0xf bank_mask:0xf
	v_add_f32_dpp v2, v142, v142 quad_perm:[1,0,3,2] row_mask:0xf bank_mask:0xf
	v_add_f32_dpp v3, v143, v143 quad_perm:[1,0,3,2] row_mask:0xf bank_mask:0xf
	v_cndmask_b32_e32 v0, v2, v0, vcc
	v_cndmask_b32_e32 v1, v3, v1, vcc
	v_add_f32_dpp v6, v4, v4 quad_perm:[2,3,0,1] row_mask:0xf bank_mask:0xf
	v_add_f32_dpp v7, v5, v5 quad_perm:[2,3,0,1] row_mask:0xf bank_mask:0xf
	v_cndmask_b32_e64 v4, v7, v6, s[4:5]
	v_add_f32_dpp v2, v0, v0 quad_perm:[2,3,0,1] row_mask:0xf bank_mask:0xf
	v_add_f32_dpp v3, v1, v1 quad_perm:[2,3,0,1] row_mask:0xf bank_mask:0xf
	v_cndmask_b32_e64 v0, v3, v2, s[4:5]
	v_cndmask_b32_e64 v5, v0, v4, s[6:7]
	v_cndmask_b32_e64 v6, v4, v0, s[6:7]
	s_nop 1
	v_add_f32_dpp v4, v6, v5 row_ror:4 row_mask:0xf bank_mask:0xf
	v_cndmask_b32_e64 v13, v4, v12, s[64:65]
	v_cndmask_b32_e64 v14, v12, v4, s[64:65]
	s_nop 1
	v_add_f32_dpp v12, v14, v13 row_ror:8 row_mask:0xf bank_mask:0xf
	s_nop 1
	v_permlane16_swap_b32_e32 v28, v12
	v_add_f32_e32 v28, v28, v12
	s_nop 1
	v_permlane32_swap_b32_e32 v60, v28
	v_add_f32_e32 v60, v60, v28
	ds_write_b32 v235, v60 offset:64
	v_add_u32_e32 v100, v158, v144
	global_load_dwordx4 v[100:103], v100, s[66:67] nt
	v_add_u32_e32 v92, v162, v144
	global_load_dwordx4 v[92:95], v92, s[66:67] nt
	v_add_u32_e32 v112, v164, v144
	global_load_dwordx4 v[112:115], v112, s[66:67] nt
	v_add_u32_e32 v108, v168, v144
	global_load_dwordx4 v[108:111], v108, s[66:67] nt
	v_add_u32_e32 v120, v172, v144
	global_load_dwordx4 v[120:123], v120, s[66:67] nt
	v_add_u32_e32 v116, v176, v144
	global_load_dwordx4 v[116:119], v116, s[66:67] nt
	v_add_u32_e32 v124, v180, v144
	global_load_dwordx4 v[124:127], v124, s[66:67] nt
	v_add_u32_e32 v104, v184, v144
	global_load_dwordx4 v[104:107], v104, s[66:67] nt
	v_add_u32_e32 v68, v188, v144
	global_load_dwordx4 v[68:71], v68, s[66:67] nt
	v_add_u32_e32 v64, v192, v144
	global_load_dwordx4 v[64:67], v64, s[66:67] nt
	v_add_u32_e32 v80, v196, v144
	global_load_dwordx4 v[80:83], v80, s[66:67] nt
	v_add_u32_e32 v76, v200, v144
	global_load_dwordx4 v[76:79], v76, s[66:67] nt
	v_add_u32_e32 v88, v202, v144
	global_load_dwordx4 v[88:91], v88, s[66:67] nt
	v_add_u32_e32 v84, v204, v144
	global_load_dwordx4 v[84:87], v84, s[66:67] nt
	v_add_u32_e32 v96, v206, v144
	global_load_dwordx4 v[96:99], v96, s[66:67] nt
	v_add_u32_e32 v72, v208, v144
	global_load_dwordx4 v[72:75], v72, s[66:67] nt
	v_add_u32_e32 v40, v146, v144
	global_load_dwordx4 v[40:43], v40, s[66:67] nt
	v_add_u32_e32 v36, v148, v144
	global_load_dwordx4 v[36:39], v36, s[66:67] nt
	v_add_u32_e32 v48, v150, v144
	global_load_dwordx4 v[48:51], v48, s[66:67] nt
	v_add_u32_e32 v44, v152, v144
	global_load_dwordx4 v[44:47], v44, s[66:67] nt
	v_add_u32_e32 v56, v154, v144
	global_load_dwordx4 v[56:59], v56, s[66:67] nt
	v_add_u32_e32 v52, v156, v144
	global_load_dwordx4 v[52:55], v52, s[66:67] nt
	v_add_u32_e32 v60, v160, v144
	global_load_dwordx4 v[60:63], v60, s[66:67] nt
	v_add_u32_e32 v32, v166, v144
	global_load_dwordx4 v[32:35], v32, s[66:67] nt
	v_add_u32_e32 v12, v170, v144
	global_load_dwordx4 v[12:15], v12, s[66:67] nt
	v_add_u32_e32 v4, v174, v144
	global_load_dwordx4 v[4:7], v4, s[66:67] nt
	v_add_u32_e32 v20, v178, v144
	global_load_dwordx4 v[20:23], v20, s[66:67] nt
	v_add_u32_e32 v8, v182, v144
	global_load_dwordx4 v[8:11], v8, s[66:67] nt
	v_add_u32_e32 v24, v186, v144
	global_load_dwordx4 v[24:27], v24, s[66:67] nt
	v_add_u32_e32 v16, v190, v144
	global_load_dwordx4 v[16:19], v16, s[66:67] nt
	v_add_u32_e32 v28, v194, v144
	global_load_dwordx4 v[28:31], v28, s[66:67] nt
	v_add_u32_e32 v0, v198, v144
	global_load_dwordx4 v[0:3], v0, s[66:67] nt
	v_lshlrev_b32_e32 v240, 2, v223
	s_waitcnt lgkmcnt(0)
	s_barrier
	v_cmp_gt_i32_e32 vcc, 4, v210
	s_and_saveexec_b64 s[4:5], vcc
	s_cbranch_execz .LBB0_1675

; DI float wave_sum(float v) { for (int o = 32; o >= 1; o >>= 1) v += __shfl_xor(v, o); return v; }
; DI void attn_sample_item(const Params& p, int item, ldsp lds, int tid_) {
;     ...
;   if (wid < 4) {
;     float v[4]; float mx = -1e30f;
; #pragma unroll
;     for (int j = 0; j < 4; ++j) { v[j] = SC[wid * 256 + j * 64 + lane]; mx = fmaxf(mx, v[j]); }
;     for (int o = 32; o >= 1; o >>= 1) mx = fmaxf(mx, __shfl_xor(mx, o));
;     float s = 0.f;
; #pragma unroll
;     for (int j = 0; j < 4; ++j) { v[j] = __expf(v[j] - mx); s += v[j]; }
;     s = wave_sum(s); const float inv = 1.f / s;
; #pragma unroll
;     for (int j = 0; j < 4; ++j) SC[wid * 256 + j * 64 + lane] = v[j] * inv;
;   }
	v_lshlrev_b32_e32 v241, 10, v210
	v_add3_u32 v244, 16, v241, v240
	ds_read2st64_b32 v[240:241], v244 offset1:1
	ds_read2st64_b32 v[242:243], v244 offset0:2 offset1:3
	s_waitcnt lgkmcnt(1)
	v_max3_f32 v245, v240, s35, v241
	s_waitcnt lgkmcnt(0)
	v_max3_f32 v245, v245, v242, v243
	s_nop 1
	v_max_f32_dpp v245, v245, v245 quad_perm:[1,0,3,2] row_mask:0xf bank_mask:0xf
	s_nop 1
	v_max_f32_dpp v245, v245, v245 quad_perm:[2,3,0,1] row_mask:0xf bank_mask:0xf
	s_nop 1
	v_max_f32_dpp v245, v245, v245 row_ror:4 row_mask:0xf bank_mask:0xf
	s_nop 1
	v_max_f32_dpp v245, v245, v245 row_ror:8 row_mask:0xf bank_mask:0xf
	v_mov_b32_e32 v246, v245
	s_nop 1
	v_permlane16_swap_b32_e32 v245, v246
	v_max_f32_e32 v245, v245, v246
	v_mov_b32_e32 v246, v245
	s_nop 1
	v_permlane32_swap_b32_e32 v245, v246
	v_max_f32_e32 v245, v245, v246
	v_sub_f32_e32 v240, v240, v245
	v_sub_f32_e32 v241, v241, v245
	v_mul_f32_e32 v240, 0x3fb8aa3b, v240
	v_sub_f32_e32 v242, v242, v245
	v_mul_f32_e32 v241, 0x3fb8aa3b, v241
	v_exp_f32_e32 v240, v240
	v_sub_f32_e32 v243, v243, v245
	v_mul_f32_e32 v242, 0x3fb8aa3b, v242
	v_exp_f32_e32 v241, v241
	v_mul_f32_e32 v243, 0x3fb8aa3b, v243
	v_exp_f32_e32 v242, v242
	v_exp_f32_e32 v243, v243
	v_add_f32_e32 v245, 0, v240
	v_add_f32_e32 v245, v241, v245
	v_add_f32_e32 v245, v242, v245
	v_add_f32_e32 v245, v243, v245
	s_nop 1
	v_add_f32_dpp v245, v245, v245 quad_perm:[1,0,3,2] row_mask:0xf bank_mask:0xf
	s_nop 1
	v_add_f32_dpp v245, v245, v245 quad_perm:[2,3,0,1] row_mask:0xf bank_mask:0xf
	s_nop 1
	v_add_f32_dpp v245, v245, v245 row_ror:4 row_mask:0xf bank_mask:0xf
	s_nop 1
	v_add_f32_dpp v245, v245, v245 row_ror:8 row_mask:0xf bank_mask:0xf
	v_mov_b32_e32 v246, v245
	s_nop 1
	v_permlane16_swap_b32_e32 v245, v246
	v_add_f32_e32 v245, v245, v246
	v_mov_b32_e32 v246, v245
	s_nop 1
	v_permlane32_swap_b32_e32 v245, v246
	v_add_f32_e32 v245, v245, v246
	v_div_scale_f32 v246, s[6:7], v245, v245, 1.0
	v_rcp_f32_e32 v247, v246
	v_div_scale_f32 v248, vcc, 1.0, v245, 1.0
	v_fma_f32 v249, -v246, v247, 1.0
	v_fmac_f32_e32 v247, v249, v247
	v_mul_f32_e32 v249, v248, v247
	v_fma_f32 v250, -v246, v249, v248
	v_fmac_f32_e32 v249, v250, v247
	v_fma_f32 v246, -v246, v249, v248
	v_div_fmas_f32 v246, v246, v247, v249
	v_div_fixup_f32 v245, v246, v245, 1.0
	v_mul_f32_e32 v240, v240, v245
	v_mul_f32_e32 v241, v241, v245
	v_mul_f32_e32 v242, v242, v245
	v_mul_f32_e32 v243, v243, v245
	ds_write2st64_b32 v244, v240, v241 offset1:1
	ds_write2st64_b32 v244, v242, v243 offset0:2 offset1:3
	s_branch .LBB0_1675
